# residual epilogues (both GEMMs) + in-proj plain epilogue: permlane16 swap + dwordx4; NVT quad-transpose stores; gate gemm deep load pipeline
# speedup vs baseline: 1.0118x; 1.0042x over previous
.LBB0_53:
	v_lshl_add_u32 v194, s46, 8, v235
	v_lshl_or_b32 v192, s45, 8, v237
	v_ashrrev_i32_e32 v195, 31, v194
	v_lshlrev_b64 v[128:129], 11, v[194:195]
	v_ashrrev_i32_e32 v193, 31, v192
	v_lshl_add_u64 v[128:129], v[128:129], 0, v[192:193]
	v_lshlrev_b64 v[130:131], 1, v[128:129]
	s_and_b64 vcc, exec, s[10:11]
	v_lshl_add_u64 v[198:199], s[94:95], 0, v[130:131]
	v_lshl_add_u64 v[196:197], s[8:9], 0, v[130:131]
	s_cbranch_vccz .LBB0_71
	v_and_b32_e32 v230, 16, v225
	v_readlane_b32 s26, v255, 35
	v_readlane_b32 s27, v255, 36
	v_lshrrev_b32_e32 v231, 1, v230
	v_add_u32_e32 v230, v230, v231
	v_add_co_u32_e32 v164, vcc, v198, v230
	s_lshl_b32 s2, s45, 4
	s_nop 0
	v_addc_co_u32_e32 v165, vcc, 0, v199, vcc
	v_add_co_u32_e32 v166, vcc, v196, v230
	s_lshl_b32 s3, s41, 2
	s_nop 0
	v_addc_co_u32_e32 v167, vcc, 0, v197, vcc
	s_add_i32 s2, s2, s3
	v_mov_b32_e32 v168, v164
	v_mov_b32_e32 v169, v165
	v_mov_b32_e32 v170, v166
	v_mov_b32_e32 v171, v167
	global_load_dwordx4 v[132:135], v[168:169], off
	global_load_dwordx4 v[136:139], v[170:171], off
	global_load_dwordx4 v[140:143], v[168:169], off offset:256
	global_load_dwordx4 v[144:147], v[170:171], off offset:256
	v_add_co_u32_e32 v168, vcc, 0x10000, v164
	s_nop 1
	v_addc_co_u32_e32 v169, vcc, 0, v165, vcc
	v_add_co_u32_e32 v170, vcc, 0x10000, v166
	s_nop 1
	v_addc_co_u32_e32 v171, vcc, 0, v167, vcc
	global_load_dwordx4 v[148:151], v[168:169], off
	global_load_dwordx4 v[152:155], v[170:171], off
	global_load_dwordx4 v[156:159], v[168:169], off offset:256
	global_load_dwordx4 v[160:163], v[170:171], off offset:256
	v_add_co_u32_e32 v168, vcc, 0x20000, v164
	s_nop 1
	v_addc_co_u32_e32 v169, vcc, 0, v165, vcc
	v_add_co_u32_e32 v170, vcc, 0x20000, v166
	s_nop 1
	v_addc_co_u32_e32 v171, vcc, 0, v167, vcc
	global_load_dwordx4 v[200:203], v[168:169], off
	global_load_dwordx4 v[204:207], v[170:171], off
	global_load_dwordx4 v[208:211], v[168:169], off offset:256
	global_load_dwordx4 v[212:215], v[170:171], off offset:256
	v_lshlrev_b32_e32 v230, 7, v194
	v_add_u32_e32 v230, s2, v230
	v_mov_b32_e32 v173, s27
	v_add_co_u32_e32 v172, vcc, s26, v230
	s_nop 1
	v_addc_co_u32_e32 v173, vcc, 0, v173, vcc
	v_mov_b32_e32 v128, v164
	v_mov_b32_e32 v129, v165
	v_mov_b32_e32 v130, v166
	v_mov_b32_e32 v131, v167
	v_permlane16_swap_b32_e32 v124, v120
	v_permlane16_swap_b32_e32 v125, v121
	v_permlane16_swap_b32_e32 v126, v122
	v_permlane16_swap_b32_e32 v127, v123
	s_waitcnt vmcnt(11)
	v_lshlrev_b32_e32 v216, 16, v132
	v_and_b32_e32 v217, 0xffff0000, v132
	s_waitcnt vmcnt(10)
	v_lshlrev_b32_e32 v218, 16, v136
	v_and_b32_e32 v219, 0xffff0000, v136
	v_lshlrev_b32_e32 v168, 16, v133
	v_and_b32_e32 v169, 0xffff0000, v133
	v_lshlrev_b32_e32 v170, 16, v137
	v_and_b32_e32 v171, 0xffff0000, v137
	v_pk_add_f32 v[216:217], v[216:217], v[218:219]
	v_pk_add_f32 v[168:169], v[168:169], v[170:171]
	v_pk_add_f32 v[124:125], v[216:217], v[124:125]
	v_pk_add_f32 v[126:127], v[168:169], v[126:127]
	v_lshlrev_b32_e32 v216, 16, v134
	v_and_b32_e32 v217, 0xffff0000, v134
	v_lshlrev_b32_e32 v218, 16, v138
	v_and_b32_e32 v219, 0xffff0000, v138
	v_lshlrev_b32_e32 v168, 16, v135
	v_and_b32_e32 v169, 0xffff0000, v135
	v_lshlrev_b32_e32 v170, 16, v139
	v_and_b32_e32 v171, 0xffff0000, v139
	v_pk_add_f32 v[216:217], v[216:217], v[218:219]
	v_pk_add_f32 v[168:169], v[168:169], v[170:171]
	v_pk_add_f32 v[120:121], v[216:217], v[120:121]
	v_pk_add_f32 v[122:123], v[168:169], v[122:123]
	v_cvt_pk_bf16_f32 v132, v124, v125
	v_cvt_pk_bf16_f32 v133, v126, v127
	v_cvt_pk_bf16_f32 v134, v120, v121
	v_cvt_pk_bf16_f32 v135, v122, v123
	global_store_dwordx4 v[128:129], v[132:135], off
	v_lshlrev_b32_e32 v216, 16, v132
	v_and_b32_e32 v217, 0xffff0000, v132
	v_pk_add_f32 v[216:217], v[124:125], v[216:217] neg_lo:[0,1] neg_hi:[0,1]
	v_pk_mul_f32 v[228:229], v[124:125], v[124:125]
	v_cvt_pk_bf16_f32 v136, v216, v217
	v_lshlrev_b32_e32 v216, 16, v133
	v_and_b32_e32 v217, 0xffff0000, v133
	v_pk_add_f32 v[216:217], v[126:127], v[216:217] neg_lo:[0,1] neg_hi:[0,1]
	v_pk_fma_f32 v[228:229], v[126:127], v[126:127], v[228:229]
	v_cvt_pk_bf16_f32 v137, v216, v217
	v_lshlrev_b32_e32 v216, 16, v134
	v_and_b32_e32 v217, 0xffff0000, v134
	v_pk_add_f32 v[216:217], v[120:121], v[216:217] neg_lo:[0,1] neg_hi:[0,1]
	v_pk_fma_f32 v[228:229], v[120:121], v[120:121], v[228:229]
	v_cvt_pk_bf16_f32 v138, v216, v217
	v_lshlrev_b32_e32 v216, 16, v135
	v_and_b32_e32 v217, 0xffff0000, v135
	v_pk_add_f32 v[216:217], v[122:123], v[216:217] neg_lo:[0,1] neg_hi:[0,1]
	v_pk_fma_f32 v[228:229], v[122:123], v[122:123], v[228:229]
	v_cvt_pk_bf16_f32 v139, v216, v217
	global_store_dwordx4 v[130:131], v[136:139], off
	v_permlane16_swap_b32_e32 v116, v112
	v_permlane16_swap_b32_e32 v117, v113
	v_permlane16_swap_b32_e32 v118, v114
	v_permlane16_swap_b32_e32 v119, v115
	s_waitcnt vmcnt(11)
	v_lshlrev_b32_e32 v216, 16, v140
	v_and_b32_e32 v217, 0xffff0000, v140
	s_waitcnt vmcnt(10)
	v_lshlrev_b32_e32 v218, 16, v144
	v_and_b32_e32 v219, 0xffff0000, v144
	v_lshlrev_b32_e32 v168, 16, v141
	v_and_b32_e32 v169, 0xffff0000, v141
	v_lshlrev_b32_e32 v170, 16, v145
	v_and_b32_e32 v171, 0xffff0000, v145
	v_pk_add_f32 v[216:217], v[216:217], v[218:219]
	v_pk_add_f32 v[168:169], v[168:169], v[170:171]
	v_pk_add_f32 v[116:117], v[216:217], v[116:117]
	v_pk_add_f32 v[118:119], v[168:169], v[118:119]
	v_lshlrev_b32_e32 v216, 16, v142
	v_and_b32_e32 v217, 0xffff0000, v142
	v_lshlrev_b32_e32 v218, 16, v146
	v_and_b32_e32 v219, 0xffff0000, v146
	v_lshlrev_b32_e32 v168, 16, v143
	v_and_b32_e32 v169, 0xffff0000, v143
	v_lshlrev_b32_e32 v170, 16, v147
	v_and_b32_e32 v171, 0xffff0000, v147
	v_pk_add_f32 v[216:217], v[216:217], v[218:219]
	v_pk_add_f32 v[168:169], v[168:169], v[170:171]
	v_pk_add_f32 v[112:113], v[216:217], v[112:113]
	v_pk_add_f32 v[114:115], v[168:169], v[114:115]
	v_cvt_pk_bf16_f32 v140, v116, v117
	v_cvt_pk_bf16_f32 v141, v118, v119
	v_cvt_pk_bf16_f32 v142, v112, v113
	v_cvt_pk_bf16_f32 v143, v114, v115
	global_store_dwordx4 v[128:129], v[140:143], off offset:256
	v_lshlrev_b32_e32 v216, 16, v140
	v_and_b32_e32 v217, 0xffff0000, v140
	v_pk_add_f32 v[216:217], v[116:117], v[216:217] neg_lo:[0,1] neg_hi:[0,1]
	v_pk_fma_f32 v[228:229], v[116:117], v[116:117], v[228:229]
	v_cvt_pk_bf16_f32 v144, v216, v217
	v_lshlrev_b32_e32 v216, 16, v141
	v_and_b32_e32 v217, 0xffff0000, v141
	v_pk_add_f32 v[216:217], v[118:119], v[216:217] neg_lo:[0,1] neg_hi:[0,1]
	v_pk_fma_f32 v[228:229], v[118:119], v[118:119], v[228:229]
	v_cvt_pk_bf16_f32 v145, v216, v217
	v_lshlrev_b32_e32 v216, 16, v142
	v_and_b32_e32 v217, 0xffff0000, v142
	v_pk_add_f32 v[216:217], v[112:113], v[216:217] neg_lo:[0,1] neg_hi:[0,1]
	v_pk_fma_f32 v[228:229], v[112:113], v[112:113], v[228:229]
	v_cvt_pk_bf16_f32 v146, v216, v217
	v_lshlrev_b32_e32 v216, 16, v143
	v_and_b32_e32 v217, 0xffff0000, v143
	v_pk_add_f32 v[216:217], v[114:115], v[216:217] neg_lo:[0,1] neg_hi:[0,1]
	v_pk_fma_f32 v[228:229], v[114:115], v[114:115], v[228:229]
	v_cvt_pk_bf16_f32 v147, v216, v217
	global_store_dwordx4 v[130:131], v[144:147], off offset:256
	v_add_f32_e32 v230, v228, v229
	v_mov_b32_e32 v231, v230
	s_nop 1
	v_permlane16_swap_b32_e32 v231, v230
	v_add_f32_e32 v230, v230, v231
	v_mov_b32_e32 v231, v230
	s_nop 1
	v_permlane32_swap_b32_e32 v231, v230
	v_add_f32_e32 v230, v230, v231
	v_mov_b32_e32 v174, v172
	v_mov_b32_e32 v175, v173
	s_and_saveexec_b64 s[24:25], s[14:15]
	global_store_dword v[174:175], v230, off
	s_mov_b64 exec, s[24:25]
	v_add_co_u32_e32 v168, vcc, 0x30000, v164
	s_nop 1
	v_addc_co_u32_e32 v169, vcc, 0, v165, vcc
	v_add_co_u32_e32 v170, vcc, 0x30000, v166
	s_nop 1
	v_addc_co_u32_e32 v171, vcc, 0, v167, vcc
	global_load_dwordx4 v[132:135], v[168:169], off
	global_load_dwordx4 v[136:139], v[170:171], off
	global_load_dwordx4 v[140:143], v[168:169], off offset:256
	global_load_dwordx4 v[144:147], v[170:171], off offset:256
	v_add_co_u32_e32 v128, vcc, 0x10000, v164
	s_nop 1
	v_addc_co_u32_e32 v129, vcc, 0, v165, vcc
	v_add_co_u32_e32 v130, vcc, 0x10000, v166
	s_nop 1
	v_addc_co_u32_e32 v131, vcc, 0, v167, vcc
	v_permlane16_swap_b32_e32 v108, v104
	v_permlane16_swap_b32_e32 v109, v105
	v_permlane16_swap_b32_e32 v110, v106
	v_permlane16_swap_b32_e32 v111, v107
	s_waitcnt vmcnt(16)
	v_lshlrev_b32_e32 v216, 16, v148
	v_and_b32_e32 v217, 0xffff0000, v148
	s_waitcnt vmcnt(15)
	v_lshlrev_b32_e32 v218, 16, v152
	v_and_b32_e32 v219, 0xffff0000, v152
	v_lshlrev_b32_e32 v168, 16, v149
	v_and_b32_e32 v169, 0xffff0000, v149
	v_lshlrev_b32_e32 v170, 16, v153
	v_and_b32_e32 v171, 0xffff0000, v153
	v_pk_add_f32 v[216:217], v[216:217], v[218:219]
	v_pk_add_f32 v[168:169], v[168:169], v[170:171]
	v_pk_add_f32 v[108:109], v[216:217], v[108:109]
	v_pk_add_f32 v[110:111], v[168:169], v[110:111]
	v_lshlrev_b32_e32 v216, 16, v150
	v_and_b32_e32 v217, 0xffff0000, v150
	v_lshlrev_b32_e32 v218, 16, v154
	v_and_b32_e32 v219, 0xffff0000, v154
	v_lshlrev_b32_e32 v168, 16, v151
	v_and_b32_e32 v169, 0xffff0000, v151
	v_lshlrev_b32_e32 v170, 16, v155
	v_and_b32_e32 v171, 0xffff0000, v155
	v_pk_add_f32 v[216:217], v[216:217], v[218:219]
	v_pk_add_f32 v[168:169], v[168:169], v[170:171]
	v_pk_add_f32 v[104:105], v[216:217], v[104:105]
	v_pk_add_f32 v[106:107], v[168:169], v[106:107]
	v_cvt_pk_bf16_f32 v148, v108, v109
	v_cvt_pk_bf16_f32 v149, v110, v111
	v_cvt_pk_bf16_f32 v150, v104, v105
	v_cvt_pk_bf16_f32 v151, v106, v107
	global_store_dwordx4 v[128:129], v[148:151], off
	v_lshlrev_b32_e32 v216, 16, v148
	v_and_b32_e32 v217, 0xffff0000, v148
	v_pk_add_f32 v[216:217], v[108:109], v[216:217] neg_lo:[0,1] neg_hi:[0,1]
	v_pk_mul_f32 v[228:229], v[108:109], v[108:109]
	v_cvt_pk_bf16_f32 v152, v216, v217
	v_lshlrev_b32_e32 v216, 16, v149
	v_and_b32_e32 v217, 0xffff0000, v149
	v_pk_add_f32 v[216:217], v[110:111], v[216:217] neg_lo:[0,1] neg_hi:[0,1]
	v_pk_fma_f32 v[228:229], v[110:111], v[110:111], v[228:229]
	v_cvt_pk_bf16_f32 v153, v216, v217
	v_lshlrev_b32_e32 v216, 16, v150
	v_and_b32_e32 v217, 0xffff0000, v150
	v_pk_add_f32 v[216:217], v[104:105], v[216:217] neg_lo:[0,1] neg_hi:[0,1]
	v_pk_fma_f32 v[228:229], v[104:105], v[104:105], v[228:229]
	v_cvt_pk_bf16_f32 v154, v216, v217
	v_lshlrev_b32_e32 v216, 16, v151
	v_and_b32_e32 v217, 0xffff0000, v151
	v_pk_add_f32 v[216:217], v[106:107], v[216:217] neg_lo:[0,1] neg_hi:[0,1]
	v_pk_fma_f32 v[228:229], v[106:107], v[106:107], v[228:229]
	v_cvt_pk_bf16_f32 v155, v216, v217
	global_store_dwordx4 v[130:131], v[152:155], off
	v_permlane16_swap_b32_e32 v100, v96
	v_permlane16_swap_b32_e32 v101, v97
	v_permlane16_swap_b32_e32 v102, v98
	v_permlane16_swap_b32_e32 v103, v99
	s_waitcnt vmcnt(16)
	v_lshlrev_b32_e32 v216, 16, v156
	v_and_b32_e32 v217, 0xffff0000, v156
	s_waitcnt vmcnt(15)
	v_lshlrev_b32_e32 v218, 16, v160
	v_and_b32_e32 v219, 0xffff0000, v160
	v_lshlrev_b32_e32 v168, 16, v157
	v_and_b32_e32 v169, 0xffff0000, v157
	v_lshlrev_b32_e32 v170, 16, v161
	v_and_b32_e32 v171, 0xffff0000, v161
	v_pk_add_f32 v[216:217], v[216:217], v[218:219]
	v_pk_add_f32 v[168:169], v[168:169], v[170:171]
	v_pk_add_f32 v[100:101], v[216:217], v[100:101]
	v_pk_add_f32 v[102:103], v[168:169], v[102:103]
	v_lshlrev_b32_e32 v216, 16, v158
	v_and_b32_e32 v217, 0xffff0000, v158
	v_lshlrev_b32_e32 v218, 16, v162
	v_and_b32_e32 v219, 0xffff0000, v162
	v_lshlrev_b32_e32 v168, 16, v159
	v_and_b32_e32 v169, 0xffff0000, v159
	v_lshlrev_b32_e32 v170, 16, v163
	v_and_b32_e32 v171, 0xffff0000, v163
	v_pk_add_f32 v[216:217], v[216:217], v[218:219]
	v_pk_add_f32 v[168:169], v[168:169], v[170:171]
	v_pk_add_f32 v[96:97], v[216:217], v[96:97]
	v_pk_add_f32 v[98:99], v[168:169], v[98:99]
	v_cvt_pk_bf16_f32 v156, v100, v101
	v_cvt_pk_bf16_f32 v157, v102, v103
	v_cvt_pk_bf16_f32 v158, v96, v97
	v_cvt_pk_bf16_f32 v159, v98, v99
	global_store_dwordx4 v[128:129], v[156:159], off offset:256
	v_lshlrev_b32_e32 v216, 16, v156
	v_and_b32_e32 v217, 0xffff0000, v156
	v_pk_add_f32 v[216:217], v[100:101], v[216:217] neg_lo:[0,1] neg_hi:[0,1]
	v_pk_fma_f32 v[228:229], v[100:101], v[100:101], v[228:229]
	v_cvt_pk_bf16_f32 v160, v216, v217
	v_lshlrev_b32_e32 v216, 16, v157
	v_and_b32_e32 v217, 0xffff0000, v157
	v_pk_add_f32 v[216:217], v[102:103], v[216:217] neg_lo:[0,1] neg_hi:[0,1]
	v_pk_fma_f32 v[228:229], v[102:103], v[102:103], v[228:229]
	v_cvt_pk_bf16_f32 v161, v216, v217
	v_lshlrev_b32_e32 v216, 16, v158
	v_and_b32_e32 v217, 0xffff0000, v158
	v_pk_add_f32 v[216:217], v[96:97], v[216:217] neg_lo:[0,1] neg_hi:[0,1]
	v_pk_fma_f32 v[228:229], v[96:97], v[96:97], v[228:229]
	v_cvt_pk_bf16_f32 v162, v216, v217
	v_lshlrev_b32_e32 v216, 16, v159
	v_and_b32_e32 v217, 0xffff0000, v159
	v_pk_add_f32 v[216:217], v[98:99], v[216:217] neg_lo:[0,1] neg_hi:[0,1]
	v_pk_fma_f32 v[228:229], v[98:99], v[98:99], v[228:229]
	v_cvt_pk_bf16_f32 v163, v216, v217
	global_store_dwordx4 v[130:131], v[160:163], off offset:256
	v_add_f32_e32 v230, v228, v229
	v_mov_b32_e32 v231, v230
	s_nop 1
	v_permlane16_swap_b32_e32 v231, v230
	v_add_f32_e32 v230, v230, v231
	v_mov_b32_e32 v231, v230
	s_nop 1
	v_permlane32_swap_b32_e32 v231, v230
	v_add_f32_e32 v230, v230, v231
	v_add_co_u32_e32 v174, vcc, 0x800, v172
	s_nop 1
	v_addc_co_u32_e32 v175, vcc, 0, v173, vcc
	s_and_saveexec_b64 s[24:25], s[14:15]
	global_store_dword v[174:175], v230, off
	s_mov_b64 exec, s[24:25]
	v_add_co_u32_e32 v168, vcc, 0x80000, v164
	s_nop 1
	v_addc_co_u32_e32 v169, vcc, 0, v165, vcc
	v_add_co_u32_e32 v170, vcc, 0x80000, v166
	s_nop 1
	v_addc_co_u32_e32 v171, vcc, 0, v167, vcc
	global_load_dwordx4 v[148:151], v[168:169], off
	global_load_dwordx4 v[152:155], v[170:171], off
	global_load_dwordx4 v[156:159], v[168:169], off offset:256
	global_load_dwordx4 v[160:163], v[170:171], off offset:256
	v_add_co_u32_e32 v128, vcc, 0x20000, v164
	s_nop 1
	v_addc_co_u32_e32 v129, vcc, 0, v165, vcc
	v_add_co_u32_e32 v130, vcc, 0x20000, v166
	s_nop 1
	v_addc_co_u32_e32 v131, vcc, 0, v167, vcc
	v_permlane16_swap_b32_e32 v92, v88
	v_permlane16_swap_b32_e32 v93, v89
	v_permlane16_swap_b32_e32 v94, v90
	v_permlane16_swap_b32_e32 v95, v91
	s_waitcnt vmcnt(21)
	v_lshlrev_b32_e32 v216, 16, v200
	v_and_b32_e32 v217, 0xffff0000, v200
	s_waitcnt vmcnt(20)
	v_lshlrev_b32_e32 v218, 16, v204
	v_and_b32_e32 v219, 0xffff0000, v204
	v_lshlrev_b32_e32 v168, 16, v201
	v_and_b32_e32 v169, 0xffff0000, v201
	v_lshlrev_b32_e32 v170, 16, v205
	v_and_b32_e32 v171, 0xffff0000, v205
	v_pk_add_f32 v[216:217], v[216:217], v[218:219]
	v_pk_add_f32 v[168:169], v[168:169], v[170:171]
	v_pk_add_f32 v[92:93], v[216:217], v[92:93]
	v_pk_add_f32 v[94:95], v[168:169], v[94:95]
	v_lshlrev_b32_e32 v216, 16, v202
	v_and_b32_e32 v217, 0xffff0000, v202
	v_lshlrev_b32_e32 v218, 16, v206
	v_and_b32_e32 v219, 0xffff0000, v206
	v_lshlrev_b32_e32 v168, 16, v203
	v_and_b32_e32 v169, 0xffff0000, v203
	v_lshlrev_b32_e32 v170, 16, v207
	v_and_b32_e32 v171, 0xffff0000, v207
	v_pk_add_f32 v[216:217], v[216:217], v[218:219]
	v_pk_add_f32 v[168:169], v[168:169], v[170:171]
	v_pk_add_f32 v[88:89], v[216:217], v[88:89]
	v_pk_add_f32 v[90:91], v[168:169], v[90:91]
	v_cvt_pk_bf16_f32 v200, v92, v93
	v_cvt_pk_bf16_f32 v201, v94, v95
	v_cvt_pk_bf16_f32 v202, v88, v89
	v_cvt_pk_bf16_f32 v203, v90, v91
	global_store_dwordx4 v[128:129], v[200:203], off
	v_lshlrev_b32_e32 v216, 16, v200
	v_and_b32_e32 v217, 0xffff0000, v200
	v_pk_add_f32 v[216:217], v[92:93], v[216:217] neg_lo:[0,1] neg_hi:[0,1]
	v_pk_mul_f32 v[228:229], v[92:93], v[92:93]
	v_cvt_pk_bf16_f32 v204, v216, v217
	v_lshlrev_b32_e32 v216, 16, v201
	v_and_b32_e32 v217, 0xffff0000, v201
	v_pk_add_f32 v[216:217], v[94:95], v[216:217] neg_lo:[0,1] neg_hi:[0,1]
	v_pk_fma_f32 v[228:229], v[94:95], v[94:95], v[228:229]
	v_cvt_pk_bf16_f32 v205, v216, v217
	v_lshlrev_b32_e32 v216, 16, v202
	v_and_b32_e32 v217, 0xffff0000, v202
	v_pk_add_f32 v[216:217], v[88:89], v[216:217] neg_lo:[0,1] neg_hi:[0,1]
	v_pk_fma_f32 v[228:229], v[88:89], v[88:89], v[228:229]
	v_cvt_pk_bf16_f32 v206, v216, v217
	v_lshlrev_b32_e32 v216, 16, v203
	v_and_b32_e32 v217, 0xffff0000, v203
	v_pk_add_f32 v[216:217], v[90:91], v[216:217] neg_lo:[0,1] neg_hi:[0,1]
	v_pk_fma_f32 v[228:229], v[90:91], v[90:91], v[228:229]
	v_cvt_pk_bf16_f32 v207, v216, v217
	global_store_dwordx4 v[130:131], v[204:207], off
	v_permlane16_swap_b32_e32 v84, v80
	v_permlane16_swap_b32_e32 v85, v81
	v_permlane16_swap_b32_e32 v86, v82
	v_permlane16_swap_b32_e32 v87, v83
	s_waitcnt vmcnt(21)
	v_lshlrev_b32_e32 v216, 16, v208
	v_and_b32_e32 v217, 0xffff0000, v208
	s_waitcnt vmcnt(20)
	v_lshlrev_b32_e32 v218, 16, v212
	v_and_b32_e32 v219, 0xffff0000, v212
	v_lshlrev_b32_e32 v168, 16, v209
	v_and_b32_e32 v169, 0xffff0000, v209
	v_lshlrev_b32_e32 v170, 16, v213
	v_and_b32_e32 v171, 0xffff0000, v213
	v_pk_add_f32 v[216:217], v[216:217], v[218:219]
	v_pk_add_f32 v[168:169], v[168:169], v[170:171]
	v_pk_add_f32 v[84:85], v[216:217], v[84:85]
	v_pk_add_f32 v[86:87], v[168:169], v[86:87]
	v_lshlrev_b32_e32 v216, 16, v210
	v_and_b32_e32 v217, 0xffff0000, v210
	v_lshlrev_b32_e32 v218, 16, v214
	v_and_b32_e32 v219, 0xffff0000, v214
	v_lshlrev_b32_e32 v168, 16, v211
	v_and_b32_e32 v169, 0xffff0000, v211
	v_lshlrev_b32_e32 v170, 16, v215
	v_and_b32_e32 v171, 0xffff0000, v215
	v_pk_add_f32 v[216:217], v[216:217], v[218:219]
	v_pk_add_f32 v[168:169], v[168:169], v[170:171]
	v_pk_add_f32 v[80:81], v[216:217], v[80:81]
	v_pk_add_f32 v[82:83], v[168:169], v[82:83]
	v_cvt_pk_bf16_f32 v208, v84, v85
	v_cvt_pk_bf16_f32 v209, v86, v87
	v_cvt_pk_bf16_f32 v210, v80, v81
	v_cvt_pk_bf16_f32 v211, v82, v83
	global_store_dwordx4 v[128:129], v[208:211], off offset:256
	v_lshlrev_b32_e32 v216, 16, v208
	v_and_b32_e32 v217, 0xffff0000, v208
	v_pk_add_f32 v[216:217], v[84:85], v[216:217] neg_lo:[0,1] neg_hi:[0,1]
	v_pk_fma_f32 v[228:229], v[84:85], v[84:85], v[228:229]
	v_cvt_pk_bf16_f32 v212, v216, v217
	v_lshlrev_b32_e32 v216, 16, v209
	v_and_b32_e32 v217, 0xffff0000, v209
	v_pk_add_f32 v[216:217], v[86:87], v[216:217] neg_lo:[0,1] neg_hi:[0,1]
	v_pk_fma_f32 v[228:229], v[86:87], v[86:87], v[228:229]
	v_cvt_pk_bf16_f32 v213, v216, v217
	v_lshlrev_b32_e32 v216, 16, v210
	v_and_b32_e32 v217, 0xffff0000, v210
	v_pk_add_f32 v[216:217], v[80:81], v[216:217] neg_lo:[0,1] neg_hi:[0,1]
	v_pk_fma_f32 v[228:229], v[80:81], v[80:81], v[228:229]
	v_cvt_pk_bf16_f32 v214, v216, v217
	v_lshlrev_b32_e32 v216, 16, v211
	v_and_b32_e32 v217, 0xffff0000, v211
	v_pk_add_f32 v[216:217], v[82:83], v[216:217] neg_lo:[0,1] neg_hi:[0,1]
	v_pk_fma_f32 v[228:229], v[82:83], v[82:83], v[228:229]
	v_cvt_pk_bf16_f32 v215, v216, v217
	global_store_dwordx4 v[130:131], v[212:215], off offset:256
	v_add_f32_e32 v230, v228, v229
	v_mov_b32_e32 v231, v230
	s_nop 1
	v_permlane16_swap_b32_e32 v231, v230
	v_add_f32_e32 v230, v230, v231
	v_mov_b32_e32 v231, v230
	s_nop 1
	v_permlane32_swap_b32_e32 v231, v230
	v_add_f32_e32 v230, v230, v231
	v_add_co_u32_e32 v174, vcc, 0x1000, v172
	s_nop 1
	v_addc_co_u32_e32 v175, vcc, 0, v173, vcc
	s_and_saveexec_b64 s[24:25], s[14:15]
	global_store_dword v[174:175], v230, off
	s_mov_b64 exec, s[24:25]
	v_add_co_u32_e32 v168, vcc, 0x90000, v164
	s_nop 1
	v_addc_co_u32_e32 v169, vcc, 0, v165, vcc
	v_add_co_u32_e32 v170, vcc, 0x90000, v166
	s_nop 1
	v_addc_co_u32_e32 v171, vcc, 0, v167, vcc
	global_load_dwordx4 v[200:203], v[168:169], off
	global_load_dwordx4 v[204:207], v[170:171], off
	global_load_dwordx4 v[208:211], v[168:169], off offset:256
	global_load_dwordx4 v[212:215], v[170:171], off offset:256
	v_add_co_u32_e32 v128, vcc, 0x30000, v164
	s_nop 1
	v_addc_co_u32_e32 v129, vcc, 0, v165, vcc
	v_add_co_u32_e32 v130, vcc, 0x30000, v166
	s_nop 1
	v_addc_co_u32_e32 v131, vcc, 0, v167, vcc
	v_permlane16_swap_b32_e32 v76, v72
	v_permlane16_swap_b32_e32 v77, v73
	v_permlane16_swap_b32_e32 v78, v74
	v_permlane16_swap_b32_e32 v79, v75
	s_waitcnt vmcnt(21)
	v_lshlrev_b32_e32 v216, 16, v132
	v_and_b32_e32 v217, 0xffff0000, v132
	s_waitcnt vmcnt(20)
	v_lshlrev_b32_e32 v218, 16, v136
	v_and_b32_e32 v219, 0xffff0000, v136
	v_lshlrev_b32_e32 v168, 16, v133
	v_and_b32_e32 v169, 0xffff0000, v133
	v_lshlrev_b32_e32 v170, 16, v137
	v_and_b32_e32 v171, 0xffff0000, v137
	v_pk_add_f32 v[216:217], v[216:217], v[218:219]
	v_pk_add_f32 v[168:169], v[168:169], v[170:171]
	v_pk_add_f32 v[76:77], v[216:217], v[76:77]
	v_pk_add_f32 v[78:79], v[168:169], v[78:79]
	v_lshlrev_b32_e32 v216, 16, v134
	v_and_b32_e32 v217, 0xffff0000, v134
	v_lshlrev_b32_e32 v218, 16, v138
	v_and_b32_e32 v219, 0xffff0000, v138
	v_lshlrev_b32_e32 v168, 16, v135
	v_and_b32_e32 v169, 0xffff0000, v135
	v_lshlrev_b32_e32 v170, 16, v139
	v_and_b32_e32 v171, 0xffff0000, v139
	v_pk_add_f32 v[216:217], v[216:217], v[218:219]
	v_pk_add_f32 v[168:169], v[168:169], v[170:171]
	v_pk_add_f32 v[72:73], v[216:217], v[72:73]
	v_pk_add_f32 v[74:75], v[168:169], v[74:75]
	v_cvt_pk_bf16_f32 v132, v76, v77
	v_cvt_pk_bf16_f32 v133, v78, v79
	v_cvt_pk_bf16_f32 v134, v72, v73
	v_cvt_pk_bf16_f32 v135, v74, v75
	global_store_dwordx4 v[128:129], v[132:135], off
	v_lshlrev_b32_e32 v216, 16, v132
	v_and_b32_e32 v217, 0xffff0000, v132
	v_pk_add_f32 v[216:217], v[76:77], v[216:217] neg_lo:[0,1] neg_hi:[0,1]
	v_pk_mul_f32 v[228:229], v[76:77], v[76:77]
	v_cvt_pk_bf16_f32 v136, v216, v217
	v_lshlrev_b32_e32 v216, 16, v133
	v_and_b32_e32 v217, 0xffff0000, v133
	v_pk_add_f32 v[216:217], v[78:79], v[216:217] neg_lo:[0,1] neg_hi:[0,1]
	v_pk_fma_f32 v[228:229], v[78:79], v[78:79], v[228:229]
	v_cvt_pk_bf16_f32 v137, v216, v217
	v_lshlrev_b32_e32 v216, 16, v134
	v_and_b32_e32 v217, 0xffff0000, v134
	v_pk_add_f32 v[216:217], v[72:73], v[216:217] neg_lo:[0,1] neg_hi:[0,1]
	v_pk_fma_f32 v[228:229], v[72:73], v[72:73], v[228:229]
	v_cvt_pk_bf16_f32 v138, v216, v217
	v_lshlrev_b32_e32 v216, 16, v135
	v_and_b32_e32 v217, 0xffff0000, v135
	v_pk_add_f32 v[216:217], v[74:75], v[216:217] neg_lo:[0,1] neg_hi:[0,1]
	v_pk_fma_f32 v[228:229], v[74:75], v[74:75], v[228:229]
	v_cvt_pk_bf16_f32 v139, v216, v217
	global_store_dwordx4 v[130:131], v[136:139], off
	v_permlane16_swap_b32_e32 v68, v64
	v_permlane16_swap_b32_e32 v69, v65
	v_permlane16_swap_b32_e32 v70, v66
	v_permlane16_swap_b32_e32 v71, v67
	s_waitcnt vmcnt(21)
	v_lshlrev_b32_e32 v216, 16, v140
	v_and_b32_e32 v217, 0xffff0000, v140
	s_waitcnt vmcnt(20)
	v_lshlrev_b32_e32 v218, 16, v144
	v_and_b32_e32 v219, 0xffff0000, v144
	v_lshlrev_b32_e32 v168, 16, v141
	v_and_b32_e32 v169, 0xffff0000, v141
	v_lshlrev_b32_e32 v170, 16, v145
	v_and_b32_e32 v171, 0xffff0000, v145
	v_pk_add_f32 v[216:217], v[216:217], v[218:219]
	v_pk_add_f32 v[168:169], v[168:169], v[170:171]
	v_pk_add_f32 v[68:69], v[216:217], v[68:69]
	v_pk_add_f32 v[70:71], v[168:169], v[70:71]
	v_lshlrev_b32_e32 v216, 16, v142
	v_and_b32_e32 v217, 0xffff0000, v142
	v_lshlrev_b32_e32 v218, 16, v146
	v_and_b32_e32 v219, 0xffff0000, v146
	v_lshlrev_b32_e32 v168, 16, v143
	v_and_b32_e32 v169, 0xffff0000, v143
	v_lshlrev_b32_e32 v170, 16, v147
	v_and_b32_e32 v171, 0xffff0000, v147
	v_pk_add_f32 v[216:217], v[216:217], v[218:219]
	v_pk_add_f32 v[168:169], v[168:169], v[170:171]
	v_pk_add_f32 v[64:65], v[216:217], v[64:65]
	v_pk_add_f32 v[66:67], v[168:169], v[66:67]
	v_cvt_pk_bf16_f32 v140, v68, v69
	v_cvt_pk_bf16_f32 v141, v70, v71
	v_cvt_pk_bf16_f32 v142, v64, v65
	v_cvt_pk_bf16_f32 v143, v66, v67
	global_store_dwordx4 v[128:129], v[140:143], off offset:256
	v_lshlrev_b32_e32 v216, 16, v140
	v_and_b32_e32 v217, 0xffff0000, v140
	v_pk_add_f32 v[216:217], v[68:69], v[216:217] neg_lo:[0,1] neg_hi:[0,1]
	v_pk_fma_f32 v[228:229], v[68:69], v[68:69], v[228:229]
	v_cvt_pk_bf16_f32 v144, v216, v217
	v_lshlrev_b32_e32 v216, 16, v141
	v_and_b32_e32 v217, 0xffff0000, v141
	v_pk_add_f32 v[216:217], v[70:71], v[216:217] neg_lo:[0,1] neg_hi:[0,1]
	v_pk_fma_f32 v[228:229], v[70:71], v[70:71], v[228:229]
	v_cvt_pk_bf16_f32 v145, v216, v217
	v_lshlrev_b32_e32 v216, 16, v142
	v_and_b32_e32 v217, 0xffff0000, v142
	v_pk_add_f32 v[216:217], v[64:65], v[216:217] neg_lo:[0,1] neg_hi:[0,1]
	v_pk_fma_f32 v[228:229], v[64:65], v[64:65], v[228:229]
	v_cvt_pk_bf16_f32 v146, v216, v217
	v_lshlrev_b32_e32 v216, 16, v143
	v_and_b32_e32 v217, 0xffff0000, v143
	v_pk_add_f32 v[216:217], v[66:67], v[216:217] neg_lo:[0,1] neg_hi:[0,1]
	v_pk_fma_f32 v[228:229], v[66:67], v[66:67], v[228:229]
	v_cvt_pk_bf16_f32 v147, v216, v217
	global_store_dwordx4 v[130:131], v[144:147], off offset:256
	v_add_f32_e32 v230, v228, v229
	v_mov_b32_e32 v231, v230
	s_nop 1
	v_permlane16_swap_b32_e32 v231, v230
	v_add_f32_e32 v230, v230, v231
	v_mov_b32_e32 v231, v230
	s_nop 1
	v_permlane32_swap_b32_e32 v231, v230
	v_add_f32_e32 v230, v230, v231
	v_add_co_u32_e32 v174, vcc, 0x1800, v172
	s_nop 1
	v_addc_co_u32_e32 v175, vcc, 0, v173, vcc
	s_and_saveexec_b64 s[24:25], s[14:15]
	global_store_dword v[174:175], v230, off
	s_mov_b64 exec, s[24:25]
	v_add_co_u32_e32 v168, vcc, 0xa0000, v164
	s_nop 1
	v_addc_co_u32_e32 v169, vcc, 0, v165, vcc
	v_add_co_u32_e32 v170, vcc, 0xa0000, v166
	s_nop 1
	v_addc_co_u32_e32 v171, vcc, 0, v167, vcc
	global_load_dwordx4 v[132:135], v[168:169], off
	global_load_dwordx4 v[136:139], v[170:171], off
	global_load_dwordx4 v[140:143], v[168:169], off offset:256
	global_load_dwordx4 v[144:147], v[170:171], off offset:256
	v_add_co_u32_e32 v128, vcc, 0x80000, v164
	s_nop 1
	v_addc_co_u32_e32 v129, vcc, 0, v165, vcc
	v_add_co_u32_e32 v130, vcc, 0x80000, v166
	s_nop 1
	v_addc_co_u32_e32 v131, vcc, 0, v167, vcc
	v_permlane16_swap_b32_e32 v60, v56
	v_permlane16_swap_b32_e32 v61, v57
	v_permlane16_swap_b32_e32 v62, v58
	v_permlane16_swap_b32_e32 v63, v59
	s_waitcnt vmcnt(21)
	v_lshlrev_b32_e32 v216, 16, v148
	v_and_b32_e32 v217, 0xffff0000, v148
	s_waitcnt vmcnt(20)
	v_lshlrev_b32_e32 v218, 16, v152
	v_and_b32_e32 v219, 0xffff0000, v152
	v_lshlrev_b32_e32 v168, 16, v149
	v_and_b32_e32 v169, 0xffff0000, v149
	v_lshlrev_b32_e32 v170, 16, v153
	v_and_b32_e32 v171, 0xffff0000, v153
	v_pk_add_f32 v[216:217], v[216:217], v[218:219]
	v_pk_add_f32 v[168:169], v[168:169], v[170:171]
	v_pk_add_f32 v[60:61], v[216:217], v[60:61]
	v_pk_add_f32 v[62:63], v[168:169], v[62:63]
	v_lshlrev_b32_e32 v216, 16, v150
	v_and_b32_e32 v217, 0xffff0000, v150
	v_lshlrev_b32_e32 v218, 16, v154
	v_and_b32_e32 v219, 0xffff0000, v154
	v_lshlrev_b32_e32 v168, 16, v151
	v_and_b32_e32 v169, 0xffff0000, v151
	v_lshlrev_b32_e32 v170, 16, v155
	v_and_b32_e32 v171, 0xffff0000, v155
	v_pk_add_f32 v[216:217], v[216:217], v[218:219]
	v_pk_add_f32 v[168:169], v[168:169], v[170:171]
	v_pk_add_f32 v[56:57], v[216:217], v[56:57]
	v_pk_add_f32 v[58:59], v[168:169], v[58:59]
	v_cvt_pk_bf16_f32 v148, v60, v61
	v_cvt_pk_bf16_f32 v149, v62, v63
	v_cvt_pk_bf16_f32 v150, v56, v57
	v_cvt_pk_bf16_f32 v151, v58, v59
	global_store_dwordx4 v[128:129], v[148:151], off
	v_lshlrev_b32_e32 v216, 16, v148
	v_and_b32_e32 v217, 0xffff0000, v148
	v_pk_add_f32 v[216:217], v[60:61], v[216:217] neg_lo:[0,1] neg_hi:[0,1]
	v_pk_mul_f32 v[228:229], v[60:61], v[60:61]
	v_cvt_pk_bf16_f32 v152, v216, v217
	v_lshlrev_b32_e32 v216, 16, v149
	v_and_b32_e32 v217, 0xffff0000, v149
	v_pk_add_f32 v[216:217], v[62:63], v[216:217] neg_lo:[0,1] neg_hi:[0,1]
	v_pk_fma_f32 v[228:229], v[62:63], v[62:63], v[228:229]
	v_cvt_pk_bf16_f32 v153, v216, v217
	v_lshlrev_b32_e32 v216, 16, v150
	v_and_b32_e32 v217, 0xffff0000, v150
	v_pk_add_f32 v[216:217], v[56:57], v[216:217] neg_lo:[0,1] neg_hi:[0,1]
	v_pk_fma_f32 v[228:229], v[56:57], v[56:57], v[228:229]
	v_cvt_pk_bf16_f32 v154, v216, v217
	v_lshlrev_b32_e32 v216, 16, v151
	v_and_b32_e32 v217, 0xffff0000, v151
	v_pk_add_f32 v[216:217], v[58:59], v[216:217] neg_lo:[0,1] neg_hi:[0,1]
	v_pk_fma_f32 v[228:229], v[58:59], v[58:59], v[228:229]
	v_cvt_pk_bf16_f32 v155, v216, v217
	global_store_dwordx4 v[130:131], v[152:155], off
	v_permlane16_swap_b32_e32 v52, v48
	v_permlane16_swap_b32_e32 v53, v49
	v_permlane16_swap_b32_e32 v54, v50
	v_permlane16_swap_b32_e32 v55, v51
	s_waitcnt vmcnt(21)
	v_lshlrev_b32_e32 v216, 16, v156
	v_and_b32_e32 v217, 0xffff0000, v156
	s_waitcnt vmcnt(20)
	v_lshlrev_b32_e32 v218, 16, v160
	v_and_b32_e32 v219, 0xffff0000, v160
	v_lshlrev_b32_e32 v168, 16, v157
	v_and_b32_e32 v169, 0xffff0000, v157
	v_lshlrev_b32_e32 v170, 16, v161
	v_and_b32_e32 v171, 0xffff0000, v161
	v_pk_add_f32 v[216:217], v[216:217], v[218:219]
	v_pk_add_f32 v[168:169], v[168:169], v[170:171]
	v_pk_add_f32 v[52:53], v[216:217], v[52:53]
	v_pk_add_f32 v[54:55], v[168:169], v[54:55]
	v_lshlrev_b32_e32 v216, 16, v158
	v_and_b32_e32 v217, 0xffff0000, v158
	v_lshlrev_b32_e32 v218, 16, v162
	v_and_b32_e32 v219, 0xffff0000, v162
	v_lshlrev_b32_e32 v168, 16, v159
	v_and_b32_e32 v169, 0xffff0000, v159
	v_lshlrev_b32_e32 v170, 16, v163
	v_and_b32_e32 v171, 0xffff0000, v163
	v_pk_add_f32 v[216:217], v[216:217], v[218:219]
	v_pk_add_f32 v[168:169], v[168:169], v[170:171]
	v_pk_add_f32 v[48:49], v[216:217], v[48:49]
	v_pk_add_f32 v[50:51], v[168:169], v[50:51]
	v_cvt_pk_bf16_f32 v156, v52, v53
	v_cvt_pk_bf16_f32 v157, v54, v55
	v_cvt_pk_bf16_f32 v158, v48, v49
	v_cvt_pk_bf16_f32 v159, v50, v51
	global_store_dwordx4 v[128:129], v[156:159], off offset:256
	v_lshlrev_b32_e32 v216, 16, v156
	v_and_b32_e32 v217, 0xffff0000, v156
	v_pk_add_f32 v[216:217], v[52:53], v[216:217] neg_lo:[0,1] neg_hi:[0,1]
	v_pk_fma_f32 v[228:229], v[52:53], v[52:53], v[228:229]
	v_cvt_pk_bf16_f32 v160, v216, v217
	v_lshlrev_b32_e32 v216, 16, v157
	v_and_b32_e32 v217, 0xffff0000, v157
	v_pk_add_f32 v[216:217], v[54:55], v[216:217] neg_lo:[0,1] neg_hi:[0,1]
	v_pk_fma_f32 v[228:229], v[54:55], v[54:55], v[228:229]
	v_cvt_pk_bf16_f32 v161, v216, v217
	v_lshlrev_b32_e32 v216, 16, v158
	v_and_b32_e32 v217, 0xffff0000, v158
	v_pk_add_f32 v[216:217], v[48:49], v[216:217] neg_lo:[0,1] neg_hi:[0,1]
	v_pk_fma_f32 v[228:229], v[48:49], v[48:49], v[228:229]
	v_cvt_pk_bf16_f32 v162, v216, v217
	v_lshlrev_b32_e32 v216, 16, v159
	v_and_b32_e32 v217, 0xffff0000, v159
	v_pk_add_f32 v[216:217], v[50:51], v[216:217] neg_lo:[0,1] neg_hi:[0,1]
	v_pk_fma_f32 v[228:229], v[50:51], v[50:51], v[228:229]
	v_cvt_pk_bf16_f32 v163, v216, v217
	global_store_dwordx4 v[130:131], v[160:163], off offset:256
	v_add_f32_e32 v230, v228, v229
	v_mov_b32_e32 v231, v230
	s_nop 1
	v_permlane16_swap_b32_e32 v231, v230
	v_add_f32_e32 v230, v230, v231
	v_mov_b32_e32 v231, v230
	s_nop 1
	v_permlane32_swap_b32_e32 v231, v230
	v_add_f32_e32 v230, v230, v231
	v_add_co_u32_e32 v174, vcc, 0x4000, v172
	s_nop 1
	v_addc_co_u32_e32 v175, vcc, 0, v173, vcc
	s_and_saveexec_b64 s[24:25], s[14:15]
	global_store_dword v[174:175], v230, off
	s_mov_b64 exec, s[24:25]
	v_add_co_u32_e32 v168, vcc, 0xb0000, v164
	s_nop 1
	v_addc_co_u32_e32 v169, vcc, 0, v165, vcc
	v_add_co_u32_e32 v170, vcc, 0xb0000, v166
	s_nop 1
	v_addc_co_u32_e32 v171, vcc, 0, v167, vcc
	global_load_dwordx4 v[148:151], v[168:169], off
	global_load_dwordx4 v[152:155], v[170:171], off
	global_load_dwordx4 v[156:159], v[168:169], off offset:256
	global_load_dwordx4 v[160:163], v[170:171], off offset:256
	v_add_co_u32_e32 v128, vcc, 0x90000, v164
	s_nop 1
	v_addc_co_u32_e32 v129, vcc, 0, v165, vcc
	v_add_co_u32_e32 v130, vcc, 0x90000, v166
	s_nop 1
	v_addc_co_u32_e32 v131, vcc, 0, v167, vcc
	v_permlane16_swap_b32_e32 v44, v40
	v_permlane16_swap_b32_e32 v45, v41
	v_permlane16_swap_b32_e32 v46, v42
	v_permlane16_swap_b32_e32 v47, v43
	s_waitcnt vmcnt(21)
	v_lshlrev_b32_e32 v216, 16, v200
	v_and_b32_e32 v217, 0xffff0000, v200
	s_waitcnt vmcnt(20)
	v_lshlrev_b32_e32 v218, 16, v204
	v_and_b32_e32 v219, 0xffff0000, v204
	v_lshlrev_b32_e32 v168, 16, v201
	v_and_b32_e32 v169, 0xffff0000, v201
	v_lshlrev_b32_e32 v170, 16, v205
	v_and_b32_e32 v171, 0xffff0000, v205
	v_pk_add_f32 v[216:217], v[216:217], v[218:219]
	v_pk_add_f32 v[168:169], v[168:169], v[170:171]
	v_pk_add_f32 v[44:45], v[216:217], v[44:45]
	v_pk_add_f32 v[46:47], v[168:169], v[46:47]
	v_lshlrev_b32_e32 v216, 16, v202
	v_and_b32_e32 v217, 0xffff0000, v202
	v_lshlrev_b32_e32 v218, 16, v206
	v_and_b32_e32 v219, 0xffff0000, v206
	v_lshlrev_b32_e32 v168, 16, v203
	v_and_b32_e32 v169, 0xffff0000, v203
	v_lshlrev_b32_e32 v170, 16, v207
	v_and_b32_e32 v171, 0xffff0000, v207
	v_pk_add_f32 v[216:217], v[216:217], v[218:219]
	v_pk_add_f32 v[168:169], v[168:169], v[170:171]
	v_pk_add_f32 v[40:41], v[216:217], v[40:41]
	v_pk_add_f32 v[42:43], v[168:169], v[42:43]
	v_cvt_pk_bf16_f32 v200, v44, v45
	v_cvt_pk_bf16_f32 v201, v46, v47
	v_cvt_pk_bf16_f32 v202, v40, v41
	v_cvt_pk_bf16_f32 v203, v42, v43
	global_store_dwordx4 v[128:129], v[200:203], off
	v_lshlrev_b32_e32 v216, 16, v200
	v_and_b32_e32 v217, 0xffff0000, v200
	v_pk_add_f32 v[216:217], v[44:45], v[216:217] neg_lo:[0,1] neg_hi:[0,1]
	v_pk_mul_f32 v[228:229], v[44:45], v[44:45]
	v_cvt_pk_bf16_f32 v204, v216, v217
	v_lshlrev_b32_e32 v216, 16, v201
	v_and_b32_e32 v217, 0xffff0000, v201
	v_pk_add_f32 v[216:217], v[46:47], v[216:217] neg_lo:[0,1] neg_hi:[0,1]
	v_pk_fma_f32 v[228:229], v[46:47], v[46:47], v[228:229]
	v_cvt_pk_bf16_f32 v205, v216, v217
	v_lshlrev_b32_e32 v216, 16, v202
	v_and_b32_e32 v217, 0xffff0000, v202
	v_pk_add_f32 v[216:217], v[40:41], v[216:217] neg_lo:[0,1] neg_hi:[0,1]
	v_pk_fma_f32 v[228:229], v[40:41], v[40:41], v[228:229]
	v_cvt_pk_bf16_f32 v206, v216, v217
	v_lshlrev_b32_e32 v216, 16, v203
	v_and_b32_e32 v217, 0xffff0000, v203
	v_pk_add_f32 v[216:217], v[42:43], v[216:217] neg_lo:[0,1] neg_hi:[0,1]
	v_pk_fma_f32 v[228:229], v[42:43], v[42:43], v[228:229]
	v_cvt_pk_bf16_f32 v207, v216, v217
	global_store_dwordx4 v[130:131], v[204:207], off
	v_permlane16_swap_b32_e32 v36, v32
	v_permlane16_swap_b32_e32 v37, v33
	v_permlane16_swap_b32_e32 v38, v34
	v_permlane16_swap_b32_e32 v39, v35
	s_waitcnt vmcnt(21)
	v_lshlrev_b32_e32 v216, 16, v208
	v_and_b32_e32 v217, 0xffff0000, v208
	s_waitcnt vmcnt(20)
	v_lshlrev_b32_e32 v218, 16, v212
	v_and_b32_e32 v219, 0xffff0000, v212
	v_lshlrev_b32_e32 v168, 16, v209
	v_and_b32_e32 v169, 0xffff0000, v209
	v_lshlrev_b32_e32 v170, 16, v213
	v_and_b32_e32 v171, 0xffff0000, v213
	v_pk_add_f32 v[216:217], v[216:217], v[218:219]
	v_pk_add_f32 v[168:169], v[168:169], v[170:171]
	v_pk_add_f32 v[36:37], v[216:217], v[36:37]
	v_pk_add_f32 v[38:39], v[168:169], v[38:39]
	v_lshlrev_b32_e32 v216, 16, v210
	v_and_b32_e32 v217, 0xffff0000, v210
	v_lshlrev_b32_e32 v218, 16, v214
	v_and_b32_e32 v219, 0xffff0000, v214
	v_lshlrev_b32_e32 v168, 16, v211
	v_and_b32_e32 v169, 0xffff0000, v211
	v_lshlrev_b32_e32 v170, 16, v215
	v_and_b32_e32 v171, 0xffff0000, v215
	v_pk_add_f32 v[216:217], v[216:217], v[218:219]
	v_pk_add_f32 v[168:169], v[168:169], v[170:171]
	v_pk_add_f32 v[32:33], v[216:217], v[32:33]
	v_pk_add_f32 v[34:35], v[168:169], v[34:35]
	v_cvt_pk_bf16_f32 v208, v36, v37
	v_cvt_pk_bf16_f32 v209, v38, v39
	v_cvt_pk_bf16_f32 v210, v32, v33
	v_cvt_pk_bf16_f32 v211, v34, v35
	global_store_dwordx4 v[128:129], v[208:211], off offset:256
	v_lshlrev_b32_e32 v216, 16, v208
	v_and_b32_e32 v217, 0xffff0000, v208
	v_pk_add_f32 v[216:217], v[36:37], v[216:217] neg_lo:[0,1] neg_hi:[0,1]
	v_pk_fma_f32 v[228:229], v[36:37], v[36:37], v[228:229]
	v_cvt_pk_bf16_f32 v212, v216, v217
	v_lshlrev_b32_e32 v216, 16, v209
	v_and_b32_e32 v217, 0xffff0000, v209
	v_pk_add_f32 v[216:217], v[38:39], v[216:217] neg_lo:[0,1] neg_hi:[0,1]
	v_pk_fma_f32 v[228:229], v[38:39], v[38:39], v[228:229]
	v_cvt_pk_bf16_f32 v213, v216, v217
	v_lshlrev_b32_e32 v216, 16, v210
	v_and_b32_e32 v217, 0xffff0000, v210
	v_pk_add_f32 v[216:217], v[32:33], v[216:217] neg_lo:[0,1] neg_hi:[0,1]
	v_pk_fma_f32 v[228:229], v[32:33], v[32:33], v[228:229]
	v_cvt_pk_bf16_f32 v214, v216, v217
	v_lshlrev_b32_e32 v216, 16, v211
	v_and_b32_e32 v217, 0xffff0000, v211
	v_pk_add_f32 v[216:217], v[34:35], v[216:217] neg_lo:[0,1] neg_hi:[0,1]
	v_pk_fma_f32 v[228:229], v[34:35], v[34:35], v[228:229]
	v_cvt_pk_bf16_f32 v215, v216, v217
	global_store_dwordx4 v[130:131], v[212:215], off offset:256
	v_add_f32_e32 v230, v228, v229
	v_mov_b32_e32 v231, v230
	s_nop 1
	v_permlane16_swap_b32_e32 v231, v230
	v_add_f32_e32 v230, v230, v231
	v_mov_b32_e32 v231, v230
	s_nop 1
	v_permlane32_swap_b32_e32 v231, v230
	v_add_f32_e32 v230, v230, v231
	v_add_co_u32_e32 v174, vcc, 0x4800, v172
	s_nop 1
	v_addc_co_u32_e32 v175, vcc, 0, v173, vcc
	s_and_saveexec_b64 s[24:25], s[14:15]
	global_store_dword v[174:175], v230, off
	s_mov_b64 exec, s[24:25]
	v_add_co_u32_e32 v128, vcc, 0xa0000, v164
	s_nop 1
	v_addc_co_u32_e32 v129, vcc, 0, v165, vcc
	v_add_co_u32_e32 v130, vcc, 0xa0000, v166
	s_nop 1
	v_addc_co_u32_e32 v131, vcc, 0, v167, vcc
	v_permlane16_swap_b32_e32 v28, v24
	v_permlane16_swap_b32_e32 v29, v25
	v_permlane16_swap_b32_e32 v30, v26
	v_permlane16_swap_b32_e32 v31, v27
	s_waitcnt vmcnt(17)
	v_lshlrev_b32_e32 v216, 16, v132
	v_and_b32_e32 v217, 0xffff0000, v132
	s_waitcnt vmcnt(16)
	v_lshlrev_b32_e32 v218, 16, v136
	v_and_b32_e32 v219, 0xffff0000, v136
	v_lshlrev_b32_e32 v168, 16, v133
	v_and_b32_e32 v169, 0xffff0000, v133
	v_lshlrev_b32_e32 v170, 16, v137
	v_and_b32_e32 v171, 0xffff0000, v137
	v_pk_add_f32 v[216:217], v[216:217], v[218:219]
	v_pk_add_f32 v[168:169], v[168:169], v[170:171]
	v_pk_add_f32 v[28:29], v[216:217], v[28:29]
	v_pk_add_f32 v[30:31], v[168:169], v[30:31]
	v_lshlrev_b32_e32 v216, 16, v134
	v_and_b32_e32 v217, 0xffff0000, v134
	v_lshlrev_b32_e32 v218, 16, v138
	v_and_b32_e32 v219, 0xffff0000, v138
	v_lshlrev_b32_e32 v168, 16, v135
	v_and_b32_e32 v169, 0xffff0000, v135
	v_lshlrev_b32_e32 v170, 16, v139
	v_and_b32_e32 v171, 0xffff0000, v139
	v_pk_add_f32 v[216:217], v[216:217], v[218:219]
	v_pk_add_f32 v[168:169], v[168:169], v[170:171]
	v_pk_add_f32 v[24:25], v[216:217], v[24:25]
	v_pk_add_f32 v[26:27], v[168:169], v[26:27]
	v_cvt_pk_bf16_f32 v132, v28, v29
	v_cvt_pk_bf16_f32 v133, v30, v31
	v_cvt_pk_bf16_f32 v134, v24, v25
	v_cvt_pk_bf16_f32 v135, v26, v27
	global_store_dwordx4 v[128:129], v[132:135], off
	v_lshlrev_b32_e32 v216, 16, v132
	v_and_b32_e32 v217, 0xffff0000, v132
	v_pk_add_f32 v[216:217], v[28:29], v[216:217] neg_lo:[0,1] neg_hi:[0,1]
	v_pk_mul_f32 v[228:229], v[28:29], v[28:29]
	v_cvt_pk_bf16_f32 v136, v216, v217
	v_lshlrev_b32_e32 v216, 16, v133
	v_and_b32_e32 v217, 0xffff0000, v133
	v_pk_add_f32 v[216:217], v[30:31], v[216:217] neg_lo:[0,1] neg_hi:[0,1]
	v_pk_fma_f32 v[228:229], v[30:31], v[30:31], v[228:229]
	v_cvt_pk_bf16_f32 v137, v216, v217
	v_lshlrev_b32_e32 v216, 16, v134
	v_and_b32_e32 v217, 0xffff0000, v134
	v_pk_add_f32 v[216:217], v[24:25], v[216:217] neg_lo:[0,1] neg_hi:[0,1]
	v_pk_fma_f32 v[228:229], v[24:25], v[24:25], v[228:229]
	v_cvt_pk_bf16_f32 v138, v216, v217
	v_lshlrev_b32_e32 v216, 16, v135
	v_and_b32_e32 v217, 0xffff0000, v135
	v_pk_add_f32 v[216:217], v[26:27], v[216:217] neg_lo:[0,1] neg_hi:[0,1]
	v_pk_fma_f32 v[228:229], v[26:27], v[26:27], v[228:229]
	v_cvt_pk_bf16_f32 v139, v216, v217
	global_store_dwordx4 v[130:131], v[136:139], off
	v_permlane16_swap_b32_e32 v20, v16
	v_permlane16_swap_b32_e32 v21, v17
	v_permlane16_swap_b32_e32 v22, v18
	v_permlane16_swap_b32_e32 v23, v19
	s_waitcnt vmcnt(17)
	v_lshlrev_b32_e32 v216, 16, v140
	v_and_b32_e32 v217, 0xffff0000, v140
	s_waitcnt vmcnt(16)
	v_lshlrev_b32_e32 v218, 16, v144
	v_and_b32_e32 v219, 0xffff0000, v144
	v_lshlrev_b32_e32 v168, 16, v141
	v_and_b32_e32 v169, 0xffff0000, v141
	v_lshlrev_b32_e32 v170, 16, v145
	v_and_b32_e32 v171, 0xffff0000, v145
	v_pk_add_f32 v[216:217], v[216:217], v[218:219]
	v_pk_add_f32 v[168:169], v[168:169], v[170:171]
	v_pk_add_f32 v[20:21], v[216:217], v[20:21]
	v_pk_add_f32 v[22:23], v[168:169], v[22:23]
	v_lshlrev_b32_e32 v216, 16, v142
	v_and_b32_e32 v217, 0xffff0000, v142
	v_lshlrev_b32_e32 v218, 16, v146
	v_and_b32_e32 v219, 0xffff0000, v146
	v_lshlrev_b32_e32 v168, 16, v143
	v_and_b32_e32 v169, 0xffff0000, v143
	v_lshlrev_b32_e32 v170, 16, v147
	v_and_b32_e32 v171, 0xffff0000, v147
	v_pk_add_f32 v[216:217], v[216:217], v[218:219]
	v_pk_add_f32 v[168:169], v[168:169], v[170:171]
	v_pk_add_f32 v[16:17], v[216:217], v[16:17]
	v_pk_add_f32 v[18:19], v[168:169], v[18:19]
	v_cvt_pk_bf16_f32 v140, v20, v21
	v_cvt_pk_bf16_f32 v141, v22, v23
	v_cvt_pk_bf16_f32 v142, v16, v17
	v_cvt_pk_bf16_f32 v143, v18, v19
	global_store_dwordx4 v[128:129], v[140:143], off offset:256
	v_lshlrev_b32_e32 v216, 16, v140
	v_and_b32_e32 v217, 0xffff0000, v140
	v_pk_add_f32 v[216:217], v[20:21], v[216:217] neg_lo:[0,1] neg_hi:[0,1]
	v_pk_fma_f32 v[228:229], v[20:21], v[20:21], v[228:229]
	v_cvt_pk_bf16_f32 v144, v216, v217
	v_lshlrev_b32_e32 v216, 16, v141
	v_and_b32_e32 v217, 0xffff0000, v141
	v_pk_add_f32 v[216:217], v[22:23], v[216:217] neg_lo:[0,1] neg_hi:[0,1]
	v_pk_fma_f32 v[228:229], v[22:23], v[22:23], v[228:229]
	v_cvt_pk_bf16_f32 v145, v216, v217
	v_lshlrev_b32_e32 v216, 16, v142
	v_and_b32_e32 v217, 0xffff0000, v142
	v_pk_add_f32 v[216:217], v[16:17], v[216:217] neg_lo:[0,1] neg_hi:[0,1]
	v_pk_fma_f32 v[228:229], v[16:17], v[16:17], v[228:229]
	v_cvt_pk_bf16_f32 v146, v216, v217
	v_lshlrev_b32_e32 v216, 16, v143
	v_and_b32_e32 v217, 0xffff0000, v143
	v_pk_add_f32 v[216:217], v[18:19], v[216:217] neg_lo:[0,1] neg_hi:[0,1]
	v_pk_fma_f32 v[228:229], v[18:19], v[18:19], v[228:229]
	v_cvt_pk_bf16_f32 v147, v216, v217
	global_store_dwordx4 v[130:131], v[144:147], off offset:256
	v_add_f32_e32 v230, v228, v229
	v_mov_b32_e32 v231, v230
	s_nop 1
	v_permlane16_swap_b32_e32 v231, v230
	v_add_f32_e32 v230, v230, v231
	v_mov_b32_e32 v231, v230
	s_nop 1
	v_permlane32_swap_b32_e32 v231, v230
	v_add_f32_e32 v230, v230, v231
	v_add_co_u32_e32 v174, vcc, 0x5000, v172
	s_nop 1
	v_addc_co_u32_e32 v175, vcc, 0, v173, vcc
	s_and_saveexec_b64 s[24:25], s[14:15]
	global_store_dword v[174:175], v230, off
	s_mov_b64 exec, s[24:25]
	v_add_co_u32_e32 v128, vcc, 0xb0000, v164
	s_nop 1
	v_addc_co_u32_e32 v129, vcc, 0, v165, vcc
	v_add_co_u32_e32 v130, vcc, 0xb0000, v166
	s_nop 1
	v_addc_co_u32_e32 v131, vcc, 0, v167, vcc
	v_permlane16_swap_b32_e32 v12, v8
	v_permlane16_swap_b32_e32 v13, v9
	v_permlane16_swap_b32_e32 v14, v10
	v_permlane16_swap_b32_e32 v15, v11
	s_waitcnt vmcnt(13)
	v_lshlrev_b32_e32 v216, 16, v148
	v_and_b32_e32 v217, 0xffff0000, v148
	s_waitcnt vmcnt(12)
	v_lshlrev_b32_e32 v218, 16, v152
	v_and_b32_e32 v219, 0xffff0000, v152
	v_lshlrev_b32_e32 v168, 16, v149
	v_and_b32_e32 v169, 0xffff0000, v149
	v_lshlrev_b32_e32 v170, 16, v153
	v_and_b32_e32 v171, 0xffff0000, v153
	v_pk_add_f32 v[216:217], v[216:217], v[218:219]
	v_pk_add_f32 v[168:169], v[168:169], v[170:171]
	v_pk_add_f32 v[12:13], v[216:217], v[12:13]
	v_pk_add_f32 v[14:15], v[168:169], v[14:15]
	v_lshlrev_b32_e32 v216, 16, v150
	v_and_b32_e32 v217, 0xffff0000, v150
	v_lshlrev_b32_e32 v218, 16, v154
	v_and_b32_e32 v219, 0xffff0000, v154
	v_lshlrev_b32_e32 v168, 16, v151
	v_and_b32_e32 v169, 0xffff0000, v151
	v_lshlrev_b32_e32 v170, 16, v155
	v_and_b32_e32 v171, 0xffff0000, v155
	v_pk_add_f32 v[216:217], v[216:217], v[218:219]
	v_pk_add_f32 v[168:169], v[168:169], v[170:171]
	v_pk_add_f32 v[8:9], v[216:217], v[8:9]
	v_pk_add_f32 v[10:11], v[168:169], v[10:11]
	v_cvt_pk_bf16_f32 v148, v12, v13
	v_cvt_pk_bf16_f32 v149, v14, v15
	v_cvt_pk_bf16_f32 v150, v8, v9
	v_cvt_pk_bf16_f32 v151, v10, v11
	global_store_dwordx4 v[128:129], v[148:151], off
	v_lshlrev_b32_e32 v216, 16, v148
	v_and_b32_e32 v217, 0xffff0000, v148
	v_pk_add_f32 v[216:217], v[12:13], v[216:217] neg_lo:[0,1] neg_hi:[0,1]
	v_pk_mul_f32 v[228:229], v[12:13], v[12:13]
	v_cvt_pk_bf16_f32 v152, v216, v217
	v_lshlrev_b32_e32 v216, 16, v149
	v_and_b32_e32 v217, 0xffff0000, v149
	v_pk_add_f32 v[216:217], v[14:15], v[216:217] neg_lo:[0,1] neg_hi:[0,1]
	v_pk_fma_f32 v[228:229], v[14:15], v[14:15], v[228:229]
	v_cvt_pk_bf16_f32 v153, v216, v217
	v_lshlrev_b32_e32 v216, 16, v150
	v_and_b32_e32 v217, 0xffff0000, v150
	v_pk_add_f32 v[216:217], v[8:9], v[216:217] neg_lo:[0,1] neg_hi:[0,1]
	v_pk_fma_f32 v[228:229], v[8:9], v[8:9], v[228:229]
	v_cvt_pk_bf16_f32 v154, v216, v217
	v_lshlrev_b32_e32 v216, 16, v151
	v_and_b32_e32 v217, 0xffff0000, v151
	v_pk_add_f32 v[216:217], v[10:11], v[216:217] neg_lo:[0,1] neg_hi:[0,1]
	v_pk_fma_f32 v[228:229], v[10:11], v[10:11], v[228:229]
	v_cvt_pk_bf16_f32 v155, v216, v217
	global_store_dwordx4 v[130:131], v[152:155], off
	v_permlane16_swap_b32_e32 v4, v0
	v_permlane16_swap_b32_e32 v5, v1
	v_permlane16_swap_b32_e32 v6, v2
	v_permlane16_swap_b32_e32 v7, v3
	s_waitcnt vmcnt(13)
	v_lshlrev_b32_e32 v216, 16, v156
	v_and_b32_e32 v217, 0xffff0000, v156
	s_waitcnt vmcnt(12)
	v_lshlrev_b32_e32 v218, 16, v160
	v_and_b32_e32 v219, 0xffff0000, v160
	v_lshlrev_b32_e32 v168, 16, v157
	v_and_b32_e32 v169, 0xffff0000, v157
	v_lshlrev_b32_e32 v170, 16, v161
	v_and_b32_e32 v171, 0xffff0000, v161
	v_pk_add_f32 v[216:217], v[216:217], v[218:219]
	v_pk_add_f32 v[168:169], v[168:169], v[170:171]
	v_pk_add_f32 v[4:5], v[216:217], v[4:5]
	v_pk_add_f32 v[6:7], v[168:169], v[6:7]
	v_lshlrev_b32_e32 v216, 16, v158
	v_and_b32_e32 v217, 0xffff0000, v158
	v_lshlrev_b32_e32 v218, 16, v162
	v_and_b32_e32 v219, 0xffff0000, v162
	v_lshlrev_b32_e32 v168, 16, v159
	v_and_b32_e32 v169, 0xffff0000, v159
	v_lshlrev_b32_e32 v170, 16, v163
	v_and_b32_e32 v171, 0xffff0000, v163
	v_pk_add_f32 v[216:217], v[216:217], v[218:219]
	v_pk_add_f32 v[168:169], v[168:169], v[170:171]
	v_pk_add_f32 v[0:1], v[216:217], v[0:1]
	v_pk_add_f32 v[2:3], v[168:169], v[2:3]
	v_cvt_pk_bf16_f32 v156, v4, v5
	v_cvt_pk_bf16_f32 v157, v6, v7
	v_cvt_pk_bf16_f32 v158, v0, v1
	v_cvt_pk_bf16_f32 v159, v2, v3
	global_store_dwordx4 v[128:129], v[156:159], off offset:256
	v_lshlrev_b32_e32 v216, 16, v156
	v_and_b32_e32 v217, 0xffff0000, v156
	v_pk_add_f32 v[216:217], v[4:5], v[216:217] neg_lo:[0,1] neg_hi:[0,1]
	v_pk_fma_f32 v[228:229], v[4:5], v[4:5], v[228:229]
	v_cvt_pk_bf16_f32 v160, v216, v217
	v_lshlrev_b32_e32 v216, 16, v157
	v_and_b32_e32 v217, 0xffff0000, v157
	v_pk_add_f32 v[216:217], v[6:7], v[216:217] neg_lo:[0,1] neg_hi:[0,1]
	v_pk_fma_f32 v[228:229], v[6:7], v[6:7], v[228:229]
	v_cvt_pk_bf16_f32 v161, v216, v217
	v_lshlrev_b32_e32 v216, 16, v158
	v_and_b32_e32 v217, 0xffff0000, v158
	v_pk_add_f32 v[216:217], v[0:1], v[216:217] neg_lo:[0,1] neg_hi:[0,1]
	v_pk_fma_f32 v[228:229], v[0:1], v[0:1], v[228:229]
	v_cvt_pk_bf16_f32 v162, v216, v217
	v_lshlrev_b32_e32 v216, 16, v159
	v_and_b32_e32 v217, 0xffff0000, v159
	v_pk_add_f32 v[216:217], v[2:3], v[216:217] neg_lo:[0,1] neg_hi:[0,1]
	v_pk_fma_f32 v[228:229], v[2:3], v[2:3], v[228:229]
	v_cvt_pk_bf16_f32 v163, v216, v217
	global_store_dwordx4 v[130:131], v[160:163], off offset:256
	v_add_f32_e32 v230, v228, v229
	v_mov_b32_e32 v231, v230
	s_nop 1
	v_permlane16_swap_b32_e32 v231, v230
	v_add_f32_e32 v230, v230, v231
	v_mov_b32_e32 v231, v230
	s_nop 1
	v_permlane32_swap_b32_e32 v231, v230
	v_add_f32_e32 v230, v230, v231
	v_add_co_u32_e32 v174, vcc, 0x5800, v172
	s_nop 1
	v_addc_co_u32_e32 v175, vcc, 0, v173, vcc
	s_and_saveexec_b64 s[24:25], s[14:15]
	global_store_dword v[174:175], v230, off
	s_mov_b64 exec, s[24:25]
	s_andn2_b64 vcc, exec, s[4:5]
	s_mov_b64 s[2:3], -1
	s_cbranch_vccnz .LBB0_42
	s_branch .LBB0_88

.LBB0_294:
	v_lshl_add_u32 v136, s42, 8, v214
	v_lshl_or_b32 v134, s41, 8, v216
	v_ashrrev_i32_e32 v137, 31, v136
	v_lshlrev_b64 v[138:139], 11, v[136:137]
	v_ashrrev_i32_e32 v135, 31, v134
	v_lshl_add_u64 v[212:213], v[138:139], 0, v[134:135]
	v_lshlrev_b64 v[138:139], 1, v[212:213]
	v_lshl_add_u64 v[140:141], s[94:95], 0, v[138:139]
	s_mov_b32 s8, 0x10000
	v_add_co_u32_e32 v142, vcc, s8, v140
	v_lshl_add_u64 v[138:139], s[10:11], 0, v[138:139]
	s_nop 0
	v_addc_co_u32_e32 v143, vcc, 0, v141, vcc
	s_and_b64 vcc, exec, s[12:13]
	s_cbranch_vccnz .Lnew_resB
	v_add_co_u32_e32 v144, vcc, s8, v138
	s_mov_b32 s8, 0x20000
	s_nop 0
	v_addc_co_u32_e32 v145, vcc, 0, v139, vcc
	global_load_dwordx2 v[218:219], v[140:141], off
	global_load_dwordx2 v[228:229], v[138:139], off
	global_load_dwordx2 v[210:211], v[140:141], off offset:32
	global_load_dwordx2 v[208:209], v[138:139], off offset:32
	global_load_dwordx2 v[206:207], v[140:141], off offset:256
	global_load_dwordx2 v[204:205], v[138:139], off offset:256
	global_load_dwordx2 v[200:201], v[140:141], off offset:288
	global_load_dwordx2 v[202:203], v[138:139], off offset:288
	global_load_dwordx2 v[196:197], v[142:143], off
	global_load_dwordx2 v[198:199], v[144:145], off
	global_load_dwordx2 v[194:195], v[142:143], off offset:32
	global_load_dwordx2 v[192:193], v[144:145], off offset:32
	global_load_dwordx2 v[190:191], v[142:143], off offset:256
	global_load_dwordx2 v[188:189], v[144:145], off offset:256
	global_load_dwordx2 v[174:175], v[142:143], off offset:288
	global_load_dwordx2 v[186:187], v[144:145], off offset:288
	v_add_co_u32_e32 v142, vcc, s8, v140
	s_waitcnt vmcnt(0)
	v_lshlrev_b32_e32 v230, 16, v218
	v_addc_co_u32_e32 v143, vcc, 0, v141, vcc
	v_add_co_u32_e32 v144, vcc, s8, v138
	s_mov_b32 s8, 0x30000
	s_nop 0
	v_addc_co_u32_e32 v145, vcc, 0, v139, vcc
	global_load_dwordx2 v[170:171], v[142:143], off
	global_load_dwordx2 v[172:173], v[144:145], off
	global_load_dwordx2 v[168:169], v[142:143], off offset:32
	global_load_dwordx2 v[166:167], v[144:145], off offset:32
	global_load_dwordx2 v[164:165], v[142:143], off offset:256
	global_load_dwordx2 v[162:163], v[144:145], off offset:256
	global_load_dwordx2 v[158:159], v[142:143], off offset:288
	global_load_dwordx2 v[160:161], v[144:145], off offset:288
	v_add_co_u32_e32 v142, vcc, s8, v140
	v_and_b32_e32 v231, 0xffff0000, v218
	s_nop 0
	v_addc_co_u32_e32 v143, vcc, 0, v141, vcc
	v_add_co_u32_e32 v144, vcc, s8, v138
	global_load_dwordx2 v[154:155], v[142:143], off
	s_nop 0
	v_addc_co_u32_e32 v145, vcc, 0, v139, vcc
	global_load_dwordx2 v[156:157], v[144:145], off
	global_load_dwordx2 v[152:153], v[142:143], off offset:32
	global_load_dwordx2 v[150:151], v[144:145], off offset:32
	global_load_dwordx2 v[148:149], v[142:143], off offset:256
	global_load_dwordx2 v[146:147], v[144:145], off offset:256
	s_nop 0
	global_load_dwordx2 v[142:143], v[142:143], off offset:288
	s_nop 0
	global_load_dwordx2 v[144:145], v[144:145], off offset:288
	v_lshlrev_b32_e32 v236, 16, v228
	v_and_b32_e32 v237, 0xffff0000, v228
	v_lshlrev_b32_e32 v218, 16, v219
	v_and_b32_e32 v219, 0xffff0000, v219
	v_lshlrev_b32_e32 v228, 16, v229
	v_and_b32_e32 v229, 0xffff0000, v229
	v_pk_add_f32 v[230:231], v[230:231], v[236:237]
	v_pk_add_f32 v[218:219], v[218:219], v[228:229]
	v_pk_add_f32 v[124:125], v[124:125], v[230:231]
	v_pk_add_f32 v[126:127], v[126:127], v[218:219]
	s_mov_b64 s[8:9], -1
	s_and_b64 vcc, exec, s[12:13]
	s_cbranch_vccz .LBB0_296
	v_cvt_pk_bf16_f32 v218, v124, v125
	v_cvt_pk_bf16_f32 v219, v126, v127
	v_lshlrev_b32_e32 v228, 16, v218
	v_and_b32_e32 v229, 0xffff0000, v218
	v_lshlrev_b32_e32 v230, 16, v219
	v_and_b32_e32 v231, 0xffff0000, v219
	global_store_dwordx2 v[140:141], v[218:219], off
	v_sub_f32_e32 v219, v127, v231
	v_sub_f32_e32 v230, v126, v230
	v_sub_f32_e32 v218, v125, v229
	v_sub_f32_e32 v228, v124, v228
	v_cvt_pk_bf16_f32 v218, v228, v218
	v_cvt_pk_bf16_f32 v219, v230, v219
	global_store_dwordx2 v[138:139], v[218:219], off
	v_pk_mul_f32 v[218:219], v[126:127], v[126:127]
	v_pk_mul_f32 v[228:229], v[124:125], v[124:125]
	s_mov_b64 s[8:9], 0
	v_pk_mov_b32 v[230:231], v[228:229], v[218:219] op_sel:[1,0]
	v_mov_b32_e32 v229, v219
	v_pk_add_f32 v[218:219], v[230:231], v[228:229]
	s_nop 0
	v_add_f32_e32 v218, v218, v219

.Lnew_resB:
	v_and_b32_e32 v236, 16, v225
	v_readlane_b32 s24, v255, 35
	v_readlane_b32 s25, v255, 36
	v_lshrrev_b32_e32 v237, 1, v236
	v_add_u32_e32 v236, v236, v237
	v_add_co_u32_e32 v204, vcc, v140, v236
	s_lshl_b32 s20, s41, 4
	s_nop 0
	v_addc_co_u32_e32 v205, vcc, 0, v141, vcc
	v_add_co_u32_e32 v206, vcc, v138, v236
	s_lshl_b32 s21, s35, 2
	s_nop 0
	v_addc_co_u32_e32 v207, vcc, 0, v139, vcc
	s_add_i32 s20, s20, s21
	v_mov_b32_e32 v208, v204
	v_mov_b32_e32 v209, v205
	v_mov_b32_e32 v210, v206
	v_mov_b32_e32 v211, v207
	global_load_dwordx4 v[144:147], v[208:209], off
	global_load_dwordx4 v[148:151], v[210:211], off
	global_load_dwordx4 v[152:155], v[208:209], off offset:256
	global_load_dwordx4 v[156:159], v[210:211], off offset:256
	v_add_co_u32_e32 v208, vcc, 0x10000, v204
	s_nop 1
	v_addc_co_u32_e32 v209, vcc, 0, v205, vcc
	v_add_co_u32_e32 v210, vcc, 0x10000, v206
	s_nop 1
	v_addc_co_u32_e32 v211, vcc, 0, v207, vcc
	global_load_dwordx4 v[160:163], v[208:209], off
	global_load_dwordx4 v[164:167], v[210:211], off
	global_load_dwordx4 v[168:171], v[208:209], off offset:256
	global_load_dwordx4 v[172:175], v[210:211], off offset:256
	v_add_co_u32_e32 v208, vcc, 0x20000, v204
	s_nop 1
	v_addc_co_u32_e32 v209, vcc, 0, v205, vcc
	v_add_co_u32_e32 v210, vcc, 0x20000, v206
	s_nop 1
	v_addc_co_u32_e32 v211, vcc, 0, v207, vcc
	global_load_dwordx4 v[188:191], v[208:209], off
	global_load_dwordx4 v[192:195], v[210:211], off
	global_load_dwordx4 v[196:199], v[208:209], off offset:256
	global_load_dwordx4 v[200:203], v[210:211], off offset:256
	v_lshlrev_b32_e32 v236, 7, v136
	v_add_u32_e32 v236, s20, v236
	v_mov_b32_e32 v135, s25
	v_add_co_u32_e32 v134, vcc, s24, v236
	s_nop 1
	v_addc_co_u32_e32 v135, vcc, 0, v135, vcc
	v_mov_b32_e32 v212, v204
	v_mov_b32_e32 v213, v205
	v_mov_b32_e32 v186, v206
	v_mov_b32_e32 v187, v207
	v_permlane16_swap_b32_e32 v124, v120
	v_permlane16_swap_b32_e32 v125, v121
	v_permlane16_swap_b32_e32 v126, v122
	v_permlane16_swap_b32_e32 v127, v123
	s_waitcnt vmcnt(11)
	v_lshlrev_b32_e32 v218, 16, v144
	v_and_b32_e32 v219, 0xffff0000, v144
	s_waitcnt vmcnt(10)
	v_lshlrev_b32_e32 v228, 16, v148
	v_and_b32_e32 v229, 0xffff0000, v148
	v_lshlrev_b32_e32 v208, 16, v145
	v_and_b32_e32 v209, 0xffff0000, v145
	v_lshlrev_b32_e32 v210, 16, v149
	v_and_b32_e32 v211, 0xffff0000, v149
	v_pk_add_f32 v[218:219], v[218:219], v[228:229]
	v_pk_add_f32 v[208:209], v[208:209], v[210:211]
	v_pk_add_f32 v[124:125], v[218:219], v[124:125]
	v_pk_add_f32 v[126:127], v[208:209], v[126:127]
	v_lshlrev_b32_e32 v218, 16, v146
	v_and_b32_e32 v219, 0xffff0000, v146
	v_lshlrev_b32_e32 v228, 16, v150
	v_and_b32_e32 v229, 0xffff0000, v150
	v_lshlrev_b32_e32 v208, 16, v147
	v_and_b32_e32 v209, 0xffff0000, v147
	v_lshlrev_b32_e32 v210, 16, v151
	v_and_b32_e32 v211, 0xffff0000, v151
	v_pk_add_f32 v[218:219], v[218:219], v[228:229]
	v_pk_add_f32 v[208:209], v[208:209], v[210:211]
	v_pk_add_f32 v[120:121], v[218:219], v[120:121]
	v_pk_add_f32 v[122:123], v[208:209], v[122:123]
	v_cvt_pk_bf16_f32 v144, v124, v125
	v_cvt_pk_bf16_f32 v145, v126, v127
	v_cvt_pk_bf16_f32 v146, v120, v121
	v_cvt_pk_bf16_f32 v147, v122, v123
	global_store_dwordx4 v[212:213], v[144:147], off
	v_lshlrev_b32_e32 v218, 16, v144
	v_and_b32_e32 v219, 0xffff0000, v144
	v_pk_add_f32 v[218:219], v[124:125], v[218:219] neg_lo:[0,1] neg_hi:[0,1]
	v_pk_mul_f32 v[230:231], v[124:125], v[124:125]
	v_cvt_pk_bf16_f32 v148, v218, v219
	v_lshlrev_b32_e32 v218, 16, v145
	v_and_b32_e32 v219, 0xffff0000, v145
	v_pk_add_f32 v[218:219], v[126:127], v[218:219] neg_lo:[0,1] neg_hi:[0,1]
	v_pk_fma_f32 v[230:231], v[126:127], v[126:127], v[230:231]
	v_cvt_pk_bf16_f32 v149, v218, v219
	v_lshlrev_b32_e32 v218, 16, v146
	v_and_b32_e32 v219, 0xffff0000, v146
	v_pk_add_f32 v[218:219], v[120:121], v[218:219] neg_lo:[0,1] neg_hi:[0,1]
	v_pk_fma_f32 v[230:231], v[120:121], v[120:121], v[230:231]
	v_cvt_pk_bf16_f32 v150, v218, v219
	v_lshlrev_b32_e32 v218, 16, v147
	v_and_b32_e32 v219, 0xffff0000, v147
	v_pk_add_f32 v[218:219], v[122:123], v[218:219] neg_lo:[0,1] neg_hi:[0,1]
	v_pk_fma_f32 v[230:231], v[122:123], v[122:123], v[230:231]
	v_cvt_pk_bf16_f32 v151, v218, v219
	global_store_dwordx4 v[186:187], v[148:151], off
	v_permlane16_swap_b32_e32 v116, v112
	v_permlane16_swap_b32_e32 v117, v113
	v_permlane16_swap_b32_e32 v118, v114
	v_permlane16_swap_b32_e32 v119, v115
	s_waitcnt vmcnt(11)
	v_lshlrev_b32_e32 v218, 16, v152
	v_and_b32_e32 v219, 0xffff0000, v152
	s_waitcnt vmcnt(10)
	v_lshlrev_b32_e32 v228, 16, v156
	v_and_b32_e32 v229, 0xffff0000, v156
	v_lshlrev_b32_e32 v208, 16, v153
	v_and_b32_e32 v209, 0xffff0000, v153
	v_lshlrev_b32_e32 v210, 16, v157
	v_and_b32_e32 v211, 0xffff0000, v157
	v_pk_add_f32 v[218:219], v[218:219], v[228:229]
	v_pk_add_f32 v[208:209], v[208:209], v[210:211]
	v_pk_add_f32 v[116:117], v[218:219], v[116:117]
	v_pk_add_f32 v[118:119], v[208:209], v[118:119]
	v_lshlrev_b32_e32 v218, 16, v154
	v_and_b32_e32 v219, 0xffff0000, v154
	v_lshlrev_b32_e32 v228, 16, v158
	v_and_b32_e32 v229, 0xffff0000, v158
	v_lshlrev_b32_e32 v208, 16, v155
	v_and_b32_e32 v209, 0xffff0000, v155
	v_lshlrev_b32_e32 v210, 16, v159
	v_and_b32_e32 v211, 0xffff0000, v159
	v_pk_add_f32 v[218:219], v[218:219], v[228:229]
	v_pk_add_f32 v[208:209], v[208:209], v[210:211]
	v_pk_add_f32 v[112:113], v[218:219], v[112:113]
	v_pk_add_f32 v[114:115], v[208:209], v[114:115]
	v_cvt_pk_bf16_f32 v152, v116, v117
	v_cvt_pk_bf16_f32 v153, v118, v119
	v_cvt_pk_bf16_f32 v154, v112, v113
	v_cvt_pk_bf16_f32 v155, v114, v115
	global_store_dwordx4 v[212:213], v[152:155], off offset:256
	v_lshlrev_b32_e32 v218, 16, v152
	v_and_b32_e32 v219, 0xffff0000, v152
	v_pk_add_f32 v[218:219], v[116:117], v[218:219] neg_lo:[0,1] neg_hi:[0,1]
	v_pk_fma_f32 v[230:231], v[116:117], v[116:117], v[230:231]
	v_cvt_pk_bf16_f32 v156, v218, v219
	v_lshlrev_b32_e32 v218, 16, v153
	v_and_b32_e32 v219, 0xffff0000, v153
	v_pk_add_f32 v[218:219], v[118:119], v[218:219] neg_lo:[0,1] neg_hi:[0,1]
	v_pk_fma_f32 v[230:231], v[118:119], v[118:119], v[230:231]
	v_cvt_pk_bf16_f32 v157, v218, v219
	v_lshlrev_b32_e32 v218, 16, v154
	v_and_b32_e32 v219, 0xffff0000, v154
	v_pk_add_f32 v[218:219], v[112:113], v[218:219] neg_lo:[0,1] neg_hi:[0,1]
	v_pk_fma_f32 v[230:231], v[112:113], v[112:113], v[230:231]
	v_cvt_pk_bf16_f32 v158, v218, v219
	v_lshlrev_b32_e32 v218, 16, v155
	v_and_b32_e32 v219, 0xffff0000, v155
	v_pk_add_f32 v[218:219], v[114:115], v[218:219] neg_lo:[0,1] neg_hi:[0,1]
	v_pk_fma_f32 v[230:231], v[114:115], v[114:115], v[230:231]
	v_cvt_pk_bf16_f32 v159, v218, v219
	global_store_dwordx4 v[186:187], v[156:159], off offset:256
	v_add_f32_e32 v236, v230, v231
	v_mov_b32_e32 v237, v236
	s_nop 1
	v_permlane16_swap_b32_e32 v237, v236
	v_add_f32_e32 v236, v236, v237
	v_mov_b32_e32 v237, v236
	s_nop 1
	v_permlane32_swap_b32_e32 v237, v236
	v_add_f32_e32 v236, v236, v237
	v_mov_b32_e32 v142, v134
	v_mov_b32_e32 v143, v135
	s_and_saveexec_b64 s[22:23], s[4:5]
	global_store_dword v[142:143], v236, off
	s_mov_b64 exec, s[22:23]
	v_add_co_u32_e32 v208, vcc, 0x30000, v204
	s_nop 1
	v_addc_co_u32_e32 v209, vcc, 0, v205, vcc
	v_add_co_u32_e32 v210, vcc, 0x30000, v206
	s_nop 1
	v_addc_co_u32_e32 v211, vcc, 0, v207, vcc
	global_load_dwordx4 v[144:147], v[208:209], off
	global_load_dwordx4 v[148:151], v[210:211], off
	global_load_dwordx4 v[152:155], v[208:209], off offset:256
	global_load_dwordx4 v[156:159], v[210:211], off offset:256
	v_add_co_u32_e32 v212, vcc, 0x10000, v204
	s_nop 1
	v_addc_co_u32_e32 v213, vcc, 0, v205, vcc
	v_add_co_u32_e32 v186, vcc, 0x10000, v206
	s_nop 1
	v_addc_co_u32_e32 v187, vcc, 0, v207, vcc
	v_permlane16_swap_b32_e32 v108, v104
	v_permlane16_swap_b32_e32 v109, v105
	v_permlane16_swap_b32_e32 v110, v106
	v_permlane16_swap_b32_e32 v111, v107
	s_waitcnt vmcnt(16)
	v_lshlrev_b32_e32 v218, 16, v160
	v_and_b32_e32 v219, 0xffff0000, v160
	s_waitcnt vmcnt(15)
	v_lshlrev_b32_e32 v228, 16, v164
	v_and_b32_e32 v229, 0xffff0000, v164
	v_lshlrev_b32_e32 v208, 16, v161
	v_and_b32_e32 v209, 0xffff0000, v161
	v_lshlrev_b32_e32 v210, 16, v165
	v_and_b32_e32 v211, 0xffff0000, v165
	v_pk_add_f32 v[218:219], v[218:219], v[228:229]
	v_pk_add_f32 v[208:209], v[208:209], v[210:211]
	v_pk_add_f32 v[108:109], v[218:219], v[108:109]
	v_pk_add_f32 v[110:111], v[208:209], v[110:111]
	v_lshlrev_b32_e32 v218, 16, v162
	v_and_b32_e32 v219, 0xffff0000, v162
	v_lshlrev_b32_e32 v228, 16, v166
	v_and_b32_e32 v229, 0xffff0000, v166
	v_lshlrev_b32_e32 v208, 16, v163
	v_and_b32_e32 v209, 0xffff0000, v163
	v_lshlrev_b32_e32 v210, 16, v167
	v_and_b32_e32 v211, 0xffff0000, v167
	v_pk_add_f32 v[218:219], v[218:219], v[228:229]
	v_pk_add_f32 v[208:209], v[208:209], v[210:211]
	v_pk_add_f32 v[104:105], v[218:219], v[104:105]
	v_pk_add_f32 v[106:107], v[208:209], v[106:107]
	v_cvt_pk_bf16_f32 v160, v108, v109
	v_cvt_pk_bf16_f32 v161, v110, v111
	v_cvt_pk_bf16_f32 v162, v104, v105
	v_cvt_pk_bf16_f32 v163, v106, v107
	global_store_dwordx4 v[212:213], v[160:163], off
	v_lshlrev_b32_e32 v218, 16, v160
	v_and_b32_e32 v219, 0xffff0000, v160
	v_pk_add_f32 v[218:219], v[108:109], v[218:219] neg_lo:[0,1] neg_hi:[0,1]
	v_pk_mul_f32 v[230:231], v[108:109], v[108:109]
	v_cvt_pk_bf16_f32 v164, v218, v219
	v_lshlrev_b32_e32 v218, 16, v161
	v_and_b32_e32 v219, 0xffff0000, v161
	v_pk_add_f32 v[218:219], v[110:111], v[218:219] neg_lo:[0,1] neg_hi:[0,1]
	v_pk_fma_f32 v[230:231], v[110:111], v[110:111], v[230:231]
	v_cvt_pk_bf16_f32 v165, v218, v219
	v_lshlrev_b32_e32 v218, 16, v162
	v_and_b32_e32 v219, 0xffff0000, v162
	v_pk_add_f32 v[218:219], v[104:105], v[218:219] neg_lo:[0,1] neg_hi:[0,1]
	v_pk_fma_f32 v[230:231], v[104:105], v[104:105], v[230:231]
	v_cvt_pk_bf16_f32 v166, v218, v219
	v_lshlrev_b32_e32 v218, 16, v163
	v_and_b32_e32 v219, 0xffff0000, v163
	v_pk_add_f32 v[218:219], v[106:107], v[218:219] neg_lo:[0,1] neg_hi:[0,1]
	v_pk_fma_f32 v[230:231], v[106:107], v[106:107], v[230:231]
	v_cvt_pk_bf16_f32 v167, v218, v219
	global_store_dwordx4 v[186:187], v[164:167], off
	v_permlane16_swap_b32_e32 v100, v96
	v_permlane16_swap_b32_e32 v101, v97
	v_permlane16_swap_b32_e32 v102, v98
	v_permlane16_swap_b32_e32 v103, v99
	s_waitcnt vmcnt(16)
	v_lshlrev_b32_e32 v218, 16, v168
	v_and_b32_e32 v219, 0xffff0000, v168
	s_waitcnt vmcnt(15)
	v_lshlrev_b32_e32 v228, 16, v172
	v_and_b32_e32 v229, 0xffff0000, v172
	v_lshlrev_b32_e32 v208, 16, v169
	v_and_b32_e32 v209, 0xffff0000, v169
	v_lshlrev_b32_e32 v210, 16, v173
	v_and_b32_e32 v211, 0xffff0000, v173
	v_pk_add_f32 v[218:219], v[218:219], v[228:229]
	v_pk_add_f32 v[208:209], v[208:209], v[210:211]
	v_pk_add_f32 v[100:101], v[218:219], v[100:101]
	v_pk_add_f32 v[102:103], v[208:209], v[102:103]
	v_lshlrev_b32_e32 v218, 16, v170
	v_and_b32_e32 v219, 0xffff0000, v170
	v_lshlrev_b32_e32 v228, 16, v174
	v_and_b32_e32 v229, 0xffff0000, v174
	v_lshlrev_b32_e32 v208, 16, v171
	v_and_b32_e32 v209, 0xffff0000, v171
	v_lshlrev_b32_e32 v210, 16, v175
	v_and_b32_e32 v211, 0xffff0000, v175
	v_pk_add_f32 v[218:219], v[218:219], v[228:229]
	v_pk_add_f32 v[208:209], v[208:209], v[210:211]
	v_pk_add_f32 v[96:97], v[218:219], v[96:97]
	v_pk_add_f32 v[98:99], v[208:209], v[98:99]
	v_cvt_pk_bf16_f32 v168, v100, v101
	v_cvt_pk_bf16_f32 v169, v102, v103
	v_cvt_pk_bf16_f32 v170, v96, v97
	v_cvt_pk_bf16_f32 v171, v98, v99
	global_store_dwordx4 v[212:213], v[168:171], off offset:256
	v_lshlrev_b32_e32 v218, 16, v168
	v_and_b32_e32 v219, 0xffff0000, v168
	v_pk_add_f32 v[218:219], v[100:101], v[218:219] neg_lo:[0,1] neg_hi:[0,1]
	v_pk_fma_f32 v[230:231], v[100:101], v[100:101], v[230:231]
	v_cvt_pk_bf16_f32 v172, v218, v219
	v_lshlrev_b32_e32 v218, 16, v169
	v_and_b32_e32 v219, 0xffff0000, v169
	v_pk_add_f32 v[218:219], v[102:103], v[218:219] neg_lo:[0,1] neg_hi:[0,1]
	v_pk_fma_f32 v[230:231], v[102:103], v[102:103], v[230:231]
	v_cvt_pk_bf16_f32 v173, v218, v219
	v_lshlrev_b32_e32 v218, 16, v170
	v_and_b32_e32 v219, 0xffff0000, v170
	v_pk_add_f32 v[218:219], v[96:97], v[218:219] neg_lo:[0,1] neg_hi:[0,1]
	v_pk_fma_f32 v[230:231], v[96:97], v[96:97], v[230:231]
	v_cvt_pk_bf16_f32 v174, v218, v219
	v_lshlrev_b32_e32 v218, 16, v171
	v_and_b32_e32 v219, 0xffff0000, v171
	v_pk_add_f32 v[218:219], v[98:99], v[218:219] neg_lo:[0,1] neg_hi:[0,1]
	v_pk_fma_f32 v[230:231], v[98:99], v[98:99], v[230:231]
	v_cvt_pk_bf16_f32 v175, v218, v219
	global_store_dwordx4 v[186:187], v[172:175], off offset:256
	v_add_f32_e32 v236, v230, v231
	v_mov_b32_e32 v237, v236
	s_nop 1
	v_permlane16_swap_b32_e32 v237, v236
	v_add_f32_e32 v236, v236, v237
	v_mov_b32_e32 v237, v236
	s_nop 1
	v_permlane32_swap_b32_e32 v237, v236
	v_add_f32_e32 v236, v236, v237
	v_add_co_u32_e32 v142, vcc, 0x800, v134
	s_nop 1
	v_addc_co_u32_e32 v143, vcc, 0, v135, vcc
	s_and_saveexec_b64 s[22:23], s[4:5]
	global_store_dword v[142:143], v236, off
	s_mov_b64 exec, s[22:23]
	v_add_co_u32_e32 v208, vcc, 0x80000, v204
	s_nop 1
	v_addc_co_u32_e32 v209, vcc, 0, v205, vcc
	v_add_co_u32_e32 v210, vcc, 0x80000, v206
	s_nop 1
	v_addc_co_u32_e32 v211, vcc, 0, v207, vcc
	global_load_dwordx4 v[160:163], v[208:209], off
	global_load_dwordx4 v[164:167], v[210:211], off
	global_load_dwordx4 v[168:171], v[208:209], off offset:256
	global_load_dwordx4 v[172:175], v[210:211], off offset:256
	v_add_co_u32_e32 v212, vcc, 0x20000, v204
	s_nop 1
	v_addc_co_u32_e32 v213, vcc, 0, v205, vcc
	v_add_co_u32_e32 v186, vcc, 0x20000, v206
	s_nop 1
	v_addc_co_u32_e32 v187, vcc, 0, v207, vcc
	v_permlane16_swap_b32_e32 v92, v88
	v_permlane16_swap_b32_e32 v93, v89
	v_permlane16_swap_b32_e32 v94, v90
	v_permlane16_swap_b32_e32 v95, v91
	s_waitcnt vmcnt(21)
	v_lshlrev_b32_e32 v218, 16, v188
	v_and_b32_e32 v219, 0xffff0000, v188
	s_waitcnt vmcnt(20)
	v_lshlrev_b32_e32 v228, 16, v192
	v_and_b32_e32 v229, 0xffff0000, v192
	v_lshlrev_b32_e32 v208, 16, v189
	v_and_b32_e32 v209, 0xffff0000, v189
	v_lshlrev_b32_e32 v210, 16, v193
	v_and_b32_e32 v211, 0xffff0000, v193
	v_pk_add_f32 v[218:219], v[218:219], v[228:229]
	v_pk_add_f32 v[208:209], v[208:209], v[210:211]
	v_pk_add_f32 v[92:93], v[218:219], v[92:93]
	v_pk_add_f32 v[94:95], v[208:209], v[94:95]
	v_lshlrev_b32_e32 v218, 16, v190
	v_and_b32_e32 v219, 0xffff0000, v190
	v_lshlrev_b32_e32 v228, 16, v194
	v_and_b32_e32 v229, 0xffff0000, v194
	v_lshlrev_b32_e32 v208, 16, v191
	v_and_b32_e32 v209, 0xffff0000, v191
	v_lshlrev_b32_e32 v210, 16, v195
	v_and_b32_e32 v211, 0xffff0000, v195
	v_pk_add_f32 v[218:219], v[218:219], v[228:229]
	v_pk_add_f32 v[208:209], v[208:209], v[210:211]
	v_pk_add_f32 v[88:89], v[218:219], v[88:89]
	v_pk_add_f32 v[90:91], v[208:209], v[90:91]
	v_cvt_pk_bf16_f32 v188, v92, v93
	v_cvt_pk_bf16_f32 v189, v94, v95
	v_cvt_pk_bf16_f32 v190, v88, v89
	v_cvt_pk_bf16_f32 v191, v90, v91
	global_store_dwordx4 v[212:213], v[188:191], off
	v_lshlrev_b32_e32 v218, 16, v188
	v_and_b32_e32 v219, 0xffff0000, v188
	v_pk_add_f32 v[218:219], v[92:93], v[218:219] neg_lo:[0,1] neg_hi:[0,1]
	v_pk_mul_f32 v[230:231], v[92:93], v[92:93]
	v_cvt_pk_bf16_f32 v192, v218, v219
	v_lshlrev_b32_e32 v218, 16, v189
	v_and_b32_e32 v219, 0xffff0000, v189
	v_pk_add_f32 v[218:219], v[94:95], v[218:219] neg_lo:[0,1] neg_hi:[0,1]
	v_pk_fma_f32 v[230:231], v[94:95], v[94:95], v[230:231]
	v_cvt_pk_bf16_f32 v193, v218, v219
	v_lshlrev_b32_e32 v218, 16, v190
	v_and_b32_e32 v219, 0xffff0000, v190
	v_pk_add_f32 v[218:219], v[88:89], v[218:219] neg_lo:[0,1] neg_hi:[0,1]
	v_pk_fma_f32 v[230:231], v[88:89], v[88:89], v[230:231]
	v_cvt_pk_bf16_f32 v194, v218, v219
	v_lshlrev_b32_e32 v218, 16, v191
	v_and_b32_e32 v219, 0xffff0000, v191
	v_pk_add_f32 v[218:219], v[90:91], v[218:219] neg_lo:[0,1] neg_hi:[0,1]
	v_pk_fma_f32 v[230:231], v[90:91], v[90:91], v[230:231]
	v_cvt_pk_bf16_f32 v195, v218, v219
	global_store_dwordx4 v[186:187], v[192:195], off
	v_permlane16_swap_b32_e32 v84, v80
	v_permlane16_swap_b32_e32 v85, v81
	v_permlane16_swap_b32_e32 v86, v82
	v_permlane16_swap_b32_e32 v87, v83
	s_waitcnt vmcnt(21)
	v_lshlrev_b32_e32 v218, 16, v196
	v_and_b32_e32 v219, 0xffff0000, v196
	s_waitcnt vmcnt(20)
	v_lshlrev_b32_e32 v228, 16, v200
	v_and_b32_e32 v229, 0xffff0000, v200
	v_lshlrev_b32_e32 v208, 16, v197
	v_and_b32_e32 v209, 0xffff0000, v197
	v_lshlrev_b32_e32 v210, 16, v201
	v_and_b32_e32 v211, 0xffff0000, v201
	v_pk_add_f32 v[218:219], v[218:219], v[228:229]
	v_pk_add_f32 v[208:209], v[208:209], v[210:211]
	v_pk_add_f32 v[84:85], v[218:219], v[84:85]
	v_pk_add_f32 v[86:87], v[208:209], v[86:87]
	v_lshlrev_b32_e32 v218, 16, v198
	v_and_b32_e32 v219, 0xffff0000, v198
	v_lshlrev_b32_e32 v228, 16, v202
	v_and_b32_e32 v229, 0xffff0000, v202
	v_lshlrev_b32_e32 v208, 16, v199
	v_and_b32_e32 v209, 0xffff0000, v199
	v_lshlrev_b32_e32 v210, 16, v203
	v_and_b32_e32 v211, 0xffff0000, v203
	v_pk_add_f32 v[218:219], v[218:219], v[228:229]
	v_pk_add_f32 v[208:209], v[208:209], v[210:211]
	v_pk_add_f32 v[80:81], v[218:219], v[80:81]
	v_pk_add_f32 v[82:83], v[208:209], v[82:83]
	v_cvt_pk_bf16_f32 v196, v84, v85
	v_cvt_pk_bf16_f32 v197, v86, v87
	v_cvt_pk_bf16_f32 v198, v80, v81
	v_cvt_pk_bf16_f32 v199, v82, v83
	global_store_dwordx4 v[212:213], v[196:199], off offset:256
	v_lshlrev_b32_e32 v218, 16, v196
	v_and_b32_e32 v219, 0xffff0000, v196
	v_pk_add_f32 v[218:219], v[84:85], v[218:219] neg_lo:[0,1] neg_hi:[0,1]
	v_pk_fma_f32 v[230:231], v[84:85], v[84:85], v[230:231]
	v_cvt_pk_bf16_f32 v200, v218, v219
	v_lshlrev_b32_e32 v218, 16, v197
	v_and_b32_e32 v219, 0xffff0000, v197
	v_pk_add_f32 v[218:219], v[86:87], v[218:219] neg_lo:[0,1] neg_hi:[0,1]
	v_pk_fma_f32 v[230:231], v[86:87], v[86:87], v[230:231]
	v_cvt_pk_bf16_f32 v201, v218, v219
	v_lshlrev_b32_e32 v218, 16, v198
	v_and_b32_e32 v219, 0xffff0000, v198
	v_pk_add_f32 v[218:219], v[80:81], v[218:219] neg_lo:[0,1] neg_hi:[0,1]
	v_pk_fma_f32 v[230:231], v[80:81], v[80:81], v[230:231]
	v_cvt_pk_bf16_f32 v202, v218, v219
	v_lshlrev_b32_e32 v218, 16, v199
	v_and_b32_e32 v219, 0xffff0000, v199
	v_pk_add_f32 v[218:219], v[82:83], v[218:219] neg_lo:[0,1] neg_hi:[0,1]
	v_pk_fma_f32 v[230:231], v[82:83], v[82:83], v[230:231]
	v_cvt_pk_bf16_f32 v203, v218, v219
	global_store_dwordx4 v[186:187], v[200:203], off offset:256
	v_add_f32_e32 v236, v230, v231
	v_mov_b32_e32 v237, v236
	s_nop 1
	v_permlane16_swap_b32_e32 v237, v236
	v_add_f32_e32 v236, v236, v237
	v_mov_b32_e32 v237, v236
	s_nop 1
	v_permlane32_swap_b32_e32 v237, v236
	v_add_f32_e32 v236, v236, v237
	v_add_co_u32_e32 v142, vcc, 0x1000, v134
	s_nop 1
	v_addc_co_u32_e32 v143, vcc, 0, v135, vcc
	s_and_saveexec_b64 s[22:23], s[4:5]
	global_store_dword v[142:143], v236, off
	s_mov_b64 exec, s[22:23]
	v_add_co_u32_e32 v208, vcc, 0x90000, v204
	s_nop 1
	v_addc_co_u32_e32 v209, vcc, 0, v205, vcc
	v_add_co_u32_e32 v210, vcc, 0x90000, v206
	s_nop 1
	v_addc_co_u32_e32 v211, vcc, 0, v207, vcc
	global_load_dwordx4 v[188:191], v[208:209], off
	global_load_dwordx4 v[192:195], v[210:211], off
	global_load_dwordx4 v[196:199], v[208:209], off offset:256
	global_load_dwordx4 v[200:203], v[210:211], off offset:256
	v_add_co_u32_e32 v212, vcc, 0x30000, v204
	s_nop 1
	v_addc_co_u32_e32 v213, vcc, 0, v205, vcc
	v_add_co_u32_e32 v186, vcc, 0x30000, v206
	s_nop 1
	v_addc_co_u32_e32 v187, vcc, 0, v207, vcc
	v_permlane16_swap_b32_e32 v76, v72
	v_permlane16_swap_b32_e32 v77, v73
	v_permlane16_swap_b32_e32 v78, v74
	v_permlane16_swap_b32_e32 v79, v75
	s_waitcnt vmcnt(21)
	v_lshlrev_b32_e32 v218, 16, v144
	v_and_b32_e32 v219, 0xffff0000, v144
	s_waitcnt vmcnt(20)
	v_lshlrev_b32_e32 v228, 16, v148
	v_and_b32_e32 v229, 0xffff0000, v148
	v_lshlrev_b32_e32 v208, 16, v145
	v_and_b32_e32 v209, 0xffff0000, v145
	v_lshlrev_b32_e32 v210, 16, v149
	v_and_b32_e32 v211, 0xffff0000, v149
	v_pk_add_f32 v[218:219], v[218:219], v[228:229]
	v_pk_add_f32 v[208:209], v[208:209], v[210:211]
	v_pk_add_f32 v[76:77], v[218:219], v[76:77]
	v_pk_add_f32 v[78:79], v[208:209], v[78:79]
	v_lshlrev_b32_e32 v218, 16, v146
	v_and_b32_e32 v219, 0xffff0000, v146
	v_lshlrev_b32_e32 v228, 16, v150
	v_and_b32_e32 v229, 0xffff0000, v150
	v_lshlrev_b32_e32 v208, 16, v147
	v_and_b32_e32 v209, 0xffff0000, v147
	v_lshlrev_b32_e32 v210, 16, v151
	v_and_b32_e32 v211, 0xffff0000, v151
	v_pk_add_f32 v[218:219], v[218:219], v[228:229]
	v_pk_add_f32 v[208:209], v[208:209], v[210:211]
	v_pk_add_f32 v[72:73], v[218:219], v[72:73]
	v_pk_add_f32 v[74:75], v[208:209], v[74:75]
	v_cvt_pk_bf16_f32 v144, v76, v77
	v_cvt_pk_bf16_f32 v145, v78, v79
	v_cvt_pk_bf16_f32 v146, v72, v73
	v_cvt_pk_bf16_f32 v147, v74, v75
	global_store_dwordx4 v[212:213], v[144:147], off
	v_lshlrev_b32_e32 v218, 16, v144
	v_and_b32_e32 v219, 0xffff0000, v144
	v_pk_add_f32 v[218:219], v[76:77], v[218:219] neg_lo:[0,1] neg_hi:[0,1]
	v_pk_mul_f32 v[230:231], v[76:77], v[76:77]
	v_cvt_pk_bf16_f32 v148, v218, v219
	v_lshlrev_b32_e32 v218, 16, v145
	v_and_b32_e32 v219, 0xffff0000, v145
	v_pk_add_f32 v[218:219], v[78:79], v[218:219] neg_lo:[0,1] neg_hi:[0,1]
	v_pk_fma_f32 v[230:231], v[78:79], v[78:79], v[230:231]
	v_cvt_pk_bf16_f32 v149, v218, v219
	v_lshlrev_b32_e32 v218, 16, v146
	v_and_b32_e32 v219, 0xffff0000, v146
	v_pk_add_f32 v[218:219], v[72:73], v[218:219] neg_lo:[0,1] neg_hi:[0,1]
	v_pk_fma_f32 v[230:231], v[72:73], v[72:73], v[230:231]
	v_cvt_pk_bf16_f32 v150, v218, v219
	v_lshlrev_b32_e32 v218, 16, v147
	v_and_b32_e32 v219, 0xffff0000, v147
	v_pk_add_f32 v[218:219], v[74:75], v[218:219] neg_lo:[0,1] neg_hi:[0,1]
	v_pk_fma_f32 v[230:231], v[74:75], v[74:75], v[230:231]
	v_cvt_pk_bf16_f32 v151, v218, v219
	global_store_dwordx4 v[186:187], v[148:151], off
	v_permlane16_swap_b32_e32 v68, v64
	v_permlane16_swap_b32_e32 v69, v65
	v_permlane16_swap_b32_e32 v70, v66
	v_permlane16_swap_b32_e32 v71, v67
	s_waitcnt vmcnt(21)
	v_lshlrev_b32_e32 v218, 16, v152
	v_and_b32_e32 v219, 0xffff0000, v152
	s_waitcnt vmcnt(20)
	v_lshlrev_b32_e32 v228, 16, v156
	v_and_b32_e32 v229, 0xffff0000, v156
	v_lshlrev_b32_e32 v208, 16, v153
	v_and_b32_e32 v209, 0xffff0000, v153
	v_lshlrev_b32_e32 v210, 16, v157
	v_and_b32_e32 v211, 0xffff0000, v157
	v_pk_add_f32 v[218:219], v[218:219], v[228:229]
	v_pk_add_f32 v[208:209], v[208:209], v[210:211]
	v_pk_add_f32 v[68:69], v[218:219], v[68:69]
	v_pk_add_f32 v[70:71], v[208:209], v[70:71]
	v_lshlrev_b32_e32 v218, 16, v154
	v_and_b32_e32 v219, 0xffff0000, v154
	v_lshlrev_b32_e32 v228, 16, v158
	v_and_b32_e32 v229, 0xffff0000, v158
	v_lshlrev_b32_e32 v208, 16, v155
	v_and_b32_e32 v209, 0xffff0000, v155
	v_lshlrev_b32_e32 v210, 16, v159
	v_and_b32_e32 v211, 0xffff0000, v159
	v_pk_add_f32 v[218:219], v[218:219], v[228:229]
	v_pk_add_f32 v[208:209], v[208:209], v[210:211]
	v_pk_add_f32 v[64:65], v[218:219], v[64:65]
	v_pk_add_f32 v[66:67], v[208:209], v[66:67]
	v_cvt_pk_bf16_f32 v152, v68, v69
	v_cvt_pk_bf16_f32 v153, v70, v71
	v_cvt_pk_bf16_f32 v154, v64, v65
	v_cvt_pk_bf16_f32 v155, v66, v67
	global_store_dwordx4 v[212:213], v[152:155], off offset:256
	v_lshlrev_b32_e32 v218, 16, v152
	v_and_b32_e32 v219, 0xffff0000, v152
	v_pk_add_f32 v[218:219], v[68:69], v[218:219] neg_lo:[0,1] neg_hi:[0,1]
	v_pk_fma_f32 v[230:231], v[68:69], v[68:69], v[230:231]
	v_cvt_pk_bf16_f32 v156, v218, v219
	v_lshlrev_b32_e32 v218, 16, v153
	v_and_b32_e32 v219, 0xffff0000, v153
	v_pk_add_f32 v[218:219], v[70:71], v[218:219] neg_lo:[0,1] neg_hi:[0,1]
	v_pk_fma_f32 v[230:231], v[70:71], v[70:71], v[230:231]
	v_cvt_pk_bf16_f32 v157, v218, v219
	v_lshlrev_b32_e32 v218, 16, v154
	v_and_b32_e32 v219, 0xffff0000, v154
	v_pk_add_f32 v[218:219], v[64:65], v[218:219] neg_lo:[0,1] neg_hi:[0,1]
	v_pk_fma_f32 v[230:231], v[64:65], v[64:65], v[230:231]
	v_cvt_pk_bf16_f32 v158, v218, v219
	v_lshlrev_b32_e32 v218, 16, v155
	v_and_b32_e32 v219, 0xffff0000, v155
	v_pk_add_f32 v[218:219], v[66:67], v[218:219] neg_lo:[0,1] neg_hi:[0,1]
	v_pk_fma_f32 v[230:231], v[66:67], v[66:67], v[230:231]
	v_cvt_pk_bf16_f32 v159, v218, v219
	global_store_dwordx4 v[186:187], v[156:159], off offset:256
	v_add_f32_e32 v236, v230, v231
	v_mov_b32_e32 v237, v236
	s_nop 1
	v_permlane16_swap_b32_e32 v237, v236
	v_add_f32_e32 v236, v236, v237
	v_mov_b32_e32 v237, v236
	s_nop 1
	v_permlane32_swap_b32_e32 v237, v236
	v_add_f32_e32 v236, v236, v237
	v_add_co_u32_e32 v142, vcc, 0x1800, v134
	s_nop 1
	v_addc_co_u32_e32 v143, vcc, 0, v135, vcc
	s_and_saveexec_b64 s[22:23], s[4:5]
	global_store_dword v[142:143], v236, off
	s_mov_b64 exec, s[22:23]
	v_add_co_u32_e32 v208, vcc, 0xa0000, v204
	s_nop 1
	v_addc_co_u32_e32 v209, vcc, 0, v205, vcc
	v_add_co_u32_e32 v210, vcc, 0xa0000, v206
	s_nop 1
	v_addc_co_u32_e32 v211, vcc, 0, v207, vcc
	global_load_dwordx4 v[144:147], v[208:209], off
	global_load_dwordx4 v[148:151], v[210:211], off
	global_load_dwordx4 v[152:155], v[208:209], off offset:256
	global_load_dwordx4 v[156:159], v[210:211], off offset:256
	v_add_co_u32_e32 v212, vcc, 0x80000, v204
	s_nop 1
	v_addc_co_u32_e32 v213, vcc, 0, v205, vcc
	v_add_co_u32_e32 v186, vcc, 0x80000, v206
	s_nop 1
	v_addc_co_u32_e32 v187, vcc, 0, v207, vcc
	v_permlane16_swap_b32_e32 v60, v56
	v_permlane16_swap_b32_e32 v61, v57
	v_permlane16_swap_b32_e32 v62, v58
	v_permlane16_swap_b32_e32 v63, v59
	s_waitcnt vmcnt(21)
	v_lshlrev_b32_e32 v218, 16, v160
	v_and_b32_e32 v219, 0xffff0000, v160
	s_waitcnt vmcnt(20)
	v_lshlrev_b32_e32 v228, 16, v164
	v_and_b32_e32 v229, 0xffff0000, v164
	v_lshlrev_b32_e32 v208, 16, v161
	v_and_b32_e32 v209, 0xffff0000, v161
	v_lshlrev_b32_e32 v210, 16, v165
	v_and_b32_e32 v211, 0xffff0000, v165
	v_pk_add_f32 v[218:219], v[218:219], v[228:229]
	v_pk_add_f32 v[208:209], v[208:209], v[210:211]
	v_pk_add_f32 v[60:61], v[218:219], v[60:61]
	v_pk_add_f32 v[62:63], v[208:209], v[62:63]
	v_lshlrev_b32_e32 v218, 16, v162
	v_and_b32_e32 v219, 0xffff0000, v162
	v_lshlrev_b32_e32 v228, 16, v166
	v_and_b32_e32 v229, 0xffff0000, v166
	v_lshlrev_b32_e32 v208, 16, v163
	v_and_b32_e32 v209, 0xffff0000, v163
	v_lshlrev_b32_e32 v210, 16, v167
	v_and_b32_e32 v211, 0xffff0000, v167
	v_pk_add_f32 v[218:219], v[218:219], v[228:229]
	v_pk_add_f32 v[208:209], v[208:209], v[210:211]
	v_pk_add_f32 v[56:57], v[218:219], v[56:57]
	v_pk_add_f32 v[58:59], v[208:209], v[58:59]
	v_cvt_pk_bf16_f32 v160, v60, v61
	v_cvt_pk_bf16_f32 v161, v62, v63
	v_cvt_pk_bf16_f32 v162, v56, v57
	v_cvt_pk_bf16_f32 v163, v58, v59
	global_store_dwordx4 v[212:213], v[160:163], off
	v_lshlrev_b32_e32 v218, 16, v160
	v_and_b32_e32 v219, 0xffff0000, v160
	v_pk_add_f32 v[218:219], v[60:61], v[218:219] neg_lo:[0,1] neg_hi:[0,1]
	v_pk_mul_f32 v[230:231], v[60:61], v[60:61]
	v_cvt_pk_bf16_f32 v164, v218, v219
	v_lshlrev_b32_e32 v218, 16, v161
	v_and_b32_e32 v219, 0xffff0000, v161
	v_pk_add_f32 v[218:219], v[62:63], v[218:219] neg_lo:[0,1] neg_hi:[0,1]
	v_pk_fma_f32 v[230:231], v[62:63], v[62:63], v[230:231]
	v_cvt_pk_bf16_f32 v165, v218, v219
	v_lshlrev_b32_e32 v218, 16, v162
	v_and_b32_e32 v219, 0xffff0000, v162
	v_pk_add_f32 v[218:219], v[56:57], v[218:219] neg_lo:[0,1] neg_hi:[0,1]
	v_pk_fma_f32 v[230:231], v[56:57], v[56:57], v[230:231]
	v_cvt_pk_bf16_f32 v166, v218, v219
	v_lshlrev_b32_e32 v218, 16, v163
	v_and_b32_e32 v219, 0xffff0000, v163
	v_pk_add_f32 v[218:219], v[58:59], v[218:219] neg_lo:[0,1] neg_hi:[0,1]
	v_pk_fma_f32 v[230:231], v[58:59], v[58:59], v[230:231]
	v_cvt_pk_bf16_f32 v167, v218, v219
	global_store_dwordx4 v[186:187], v[164:167], off
	v_permlane16_swap_b32_e32 v52, v48
	v_permlane16_swap_b32_e32 v53, v49
	v_permlane16_swap_b32_e32 v54, v50
	v_permlane16_swap_b32_e32 v55, v51
	s_waitcnt vmcnt(21)
	v_lshlrev_b32_e32 v218, 16, v168
	v_and_b32_e32 v219, 0xffff0000, v168
	s_waitcnt vmcnt(20)
	v_lshlrev_b32_e32 v228, 16, v172
	v_and_b32_e32 v229, 0xffff0000, v172
	v_lshlrev_b32_e32 v208, 16, v169
	v_and_b32_e32 v209, 0xffff0000, v169
	v_lshlrev_b32_e32 v210, 16, v173
	v_and_b32_e32 v211, 0xffff0000, v173
	v_pk_add_f32 v[218:219], v[218:219], v[228:229]
	v_pk_add_f32 v[208:209], v[208:209], v[210:211]
	v_pk_add_f32 v[52:53], v[218:219], v[52:53]
	v_pk_add_f32 v[54:55], v[208:209], v[54:55]
	v_lshlrev_b32_e32 v218, 16, v170
	v_and_b32_e32 v219, 0xffff0000, v170
	v_lshlrev_b32_e32 v228, 16, v174
	v_and_b32_e32 v229, 0xffff0000, v174
	v_lshlrev_b32_e32 v208, 16, v171
	v_and_b32_e32 v209, 0xffff0000, v171
	v_lshlrev_b32_e32 v210, 16, v175
	v_and_b32_e32 v211, 0xffff0000, v175
	v_pk_add_f32 v[218:219], v[218:219], v[228:229]
	v_pk_add_f32 v[208:209], v[208:209], v[210:211]
	v_pk_add_f32 v[48:49], v[218:219], v[48:49]
	v_pk_add_f32 v[50:51], v[208:209], v[50:51]
	v_cvt_pk_bf16_f32 v168, v52, v53
	v_cvt_pk_bf16_f32 v169, v54, v55
	v_cvt_pk_bf16_f32 v170, v48, v49
	v_cvt_pk_bf16_f32 v171, v50, v51
	global_store_dwordx4 v[212:213], v[168:171], off offset:256
	v_lshlrev_b32_e32 v218, 16, v168
	v_and_b32_e32 v219, 0xffff0000, v168
	v_pk_add_f32 v[218:219], v[52:53], v[218:219] neg_lo:[0,1] neg_hi:[0,1]
	v_pk_fma_f32 v[230:231], v[52:53], v[52:53], v[230:231]
	v_cvt_pk_bf16_f32 v172, v218, v219
	v_lshlrev_b32_e32 v218, 16, v169
	v_and_b32_e32 v219, 0xffff0000, v169
	v_pk_add_f32 v[218:219], v[54:55], v[218:219] neg_lo:[0,1] neg_hi:[0,1]
	v_pk_fma_f32 v[230:231], v[54:55], v[54:55], v[230:231]
	v_cvt_pk_bf16_f32 v173, v218, v219
	v_lshlrev_b32_e32 v218, 16, v170
	v_and_b32_e32 v219, 0xffff0000, v170
	v_pk_add_f32 v[218:219], v[48:49], v[218:219] neg_lo:[0,1] neg_hi:[0,1]
	v_pk_fma_f32 v[230:231], v[48:49], v[48:49], v[230:231]
	v_cvt_pk_bf16_f32 v174, v218, v219
	v_lshlrev_b32_e32 v218, 16, v171
	v_and_b32_e32 v219, 0xffff0000, v171
	v_pk_add_f32 v[218:219], v[50:51], v[218:219] neg_lo:[0,1] neg_hi:[0,1]
	v_pk_fma_f32 v[230:231], v[50:51], v[50:51], v[230:231]
	v_cvt_pk_bf16_f32 v175, v218, v219
	global_store_dwordx4 v[186:187], v[172:175], off offset:256
	v_add_f32_e32 v236, v230, v231
	v_mov_b32_e32 v237, v236
	s_nop 1
	v_permlane16_swap_b32_e32 v237, v236
	v_add_f32_e32 v236, v236, v237
	v_mov_b32_e32 v237, v236
	s_nop 1
	v_permlane32_swap_b32_e32 v237, v236
	v_add_f32_e32 v236, v236, v237
	v_add_co_u32_e32 v142, vcc, 0x4000, v134
	s_nop 1
	v_addc_co_u32_e32 v143, vcc, 0, v135, vcc
	s_and_saveexec_b64 s[22:23], s[4:5]
	global_store_dword v[142:143], v236, off
	s_mov_b64 exec, s[22:23]
	v_add_co_u32_e32 v208, vcc, 0xb0000, v204
	s_nop 1
	v_addc_co_u32_e32 v209, vcc, 0, v205, vcc
	v_add_co_u32_e32 v210, vcc, 0xb0000, v206
	s_nop 1
	v_addc_co_u32_e32 v211, vcc, 0, v207, vcc
	global_load_dwordx4 v[160:163], v[208:209], off
	global_load_dwordx4 v[164:167], v[210:211], off
	global_load_dwordx4 v[168:171], v[208:209], off offset:256
	global_load_dwordx4 v[172:175], v[210:211], off offset:256
	v_add_co_u32_e32 v212, vcc, 0x90000, v204
	s_nop 1
	v_addc_co_u32_e32 v213, vcc, 0, v205, vcc
	v_add_co_u32_e32 v186, vcc, 0x90000, v206
	s_nop 1
	v_addc_co_u32_e32 v187, vcc, 0, v207, vcc
	v_permlane16_swap_b32_e32 v44, v40
	v_permlane16_swap_b32_e32 v45, v41
	v_permlane16_swap_b32_e32 v46, v42
	v_permlane16_swap_b32_e32 v47, v43
	s_waitcnt vmcnt(21)
	v_lshlrev_b32_e32 v218, 16, v188
	v_and_b32_e32 v219, 0xffff0000, v188
	s_waitcnt vmcnt(20)
	v_lshlrev_b32_e32 v228, 16, v192
	v_and_b32_e32 v229, 0xffff0000, v192
	v_lshlrev_b32_e32 v208, 16, v189
	v_and_b32_e32 v209, 0xffff0000, v189
	v_lshlrev_b32_e32 v210, 16, v193
	v_and_b32_e32 v211, 0xffff0000, v193
	v_pk_add_f32 v[218:219], v[218:219], v[228:229]
	v_pk_add_f32 v[208:209], v[208:209], v[210:211]
	v_pk_add_f32 v[44:45], v[218:219], v[44:45]
	v_pk_add_f32 v[46:47], v[208:209], v[46:47]
	v_lshlrev_b32_e32 v218, 16, v190
	v_and_b32_e32 v219, 0xffff0000, v190
	v_lshlrev_b32_e32 v228, 16, v194
	v_and_b32_e32 v229, 0xffff0000, v194
	v_lshlrev_b32_e32 v208, 16, v191
	v_and_b32_e32 v209, 0xffff0000, v191
	v_lshlrev_b32_e32 v210, 16, v195
	v_and_b32_e32 v211, 0xffff0000, v195
	v_pk_add_f32 v[218:219], v[218:219], v[228:229]
	v_pk_add_f32 v[208:209], v[208:209], v[210:211]
	v_pk_add_f32 v[40:41], v[218:219], v[40:41]
	v_pk_add_f32 v[42:43], v[208:209], v[42:43]
	v_cvt_pk_bf16_f32 v188, v44, v45
	v_cvt_pk_bf16_f32 v189, v46, v47
	v_cvt_pk_bf16_f32 v190, v40, v41
	v_cvt_pk_bf16_f32 v191, v42, v43
	global_store_dwordx4 v[212:213], v[188:191], off
	v_lshlrev_b32_e32 v218, 16, v188
	v_and_b32_e32 v219, 0xffff0000, v188
	v_pk_add_f32 v[218:219], v[44:45], v[218:219] neg_lo:[0,1] neg_hi:[0,1]
	v_pk_mul_f32 v[230:231], v[44:45], v[44:45]
	v_cvt_pk_bf16_f32 v192, v218, v219
	v_lshlrev_b32_e32 v218, 16, v189
	v_and_b32_e32 v219, 0xffff0000, v189
	v_pk_add_f32 v[218:219], v[46:47], v[218:219] neg_lo:[0,1] neg_hi:[0,1]
	v_pk_fma_f32 v[230:231], v[46:47], v[46:47], v[230:231]
	v_cvt_pk_bf16_f32 v193, v218, v219
	v_lshlrev_b32_e32 v218, 16, v190
	v_and_b32_e32 v219, 0xffff0000, v190
	v_pk_add_f32 v[218:219], v[40:41], v[218:219] neg_lo:[0,1] neg_hi:[0,1]
	v_pk_fma_f32 v[230:231], v[40:41], v[40:41], v[230:231]
	v_cvt_pk_bf16_f32 v194, v218, v219
	v_lshlrev_b32_e32 v218, 16, v191
	v_and_b32_e32 v219, 0xffff0000, v191
	v_pk_add_f32 v[218:219], v[42:43], v[218:219] neg_lo:[0,1] neg_hi:[0,1]
	v_pk_fma_f32 v[230:231], v[42:43], v[42:43], v[230:231]
	v_cvt_pk_bf16_f32 v195, v218, v219
	global_store_dwordx4 v[186:187], v[192:195], off
	v_permlane16_swap_b32_e32 v36, v32
	v_permlane16_swap_b32_e32 v37, v33
	v_permlane16_swap_b32_e32 v38, v34
	v_permlane16_swap_b32_e32 v39, v35
	s_waitcnt vmcnt(21)
	v_lshlrev_b32_e32 v218, 16, v196
	v_and_b32_e32 v219, 0xffff0000, v196
	s_waitcnt vmcnt(20)
	v_lshlrev_b32_e32 v228, 16, v200
	v_and_b32_e32 v229, 0xffff0000, v200
	v_lshlrev_b32_e32 v208, 16, v197
	v_and_b32_e32 v209, 0xffff0000, v197
	v_lshlrev_b32_e32 v210, 16, v201
	v_and_b32_e32 v211, 0xffff0000, v201
	v_pk_add_f32 v[218:219], v[218:219], v[228:229]
	v_pk_add_f32 v[208:209], v[208:209], v[210:211]
	v_pk_add_f32 v[36:37], v[218:219], v[36:37]
	v_pk_add_f32 v[38:39], v[208:209], v[38:39]
	v_lshlrev_b32_e32 v218, 16, v198
	v_and_b32_e32 v219, 0xffff0000, v198
	v_lshlrev_b32_e32 v228, 16, v202
	v_and_b32_e32 v229, 0xffff0000, v202
	v_lshlrev_b32_e32 v208, 16, v199
	v_and_b32_e32 v209, 0xffff0000, v199
	v_lshlrev_b32_e32 v210, 16, v203
	v_and_b32_e32 v211, 0xffff0000, v203
	v_pk_add_f32 v[218:219], v[218:219], v[228:229]
	v_pk_add_f32 v[208:209], v[208:209], v[210:211]
	v_pk_add_f32 v[32:33], v[218:219], v[32:33]
	v_pk_add_f32 v[34:35], v[208:209], v[34:35]
	v_cvt_pk_bf16_f32 v196, v36, v37
	v_cvt_pk_bf16_f32 v197, v38, v39
	v_cvt_pk_bf16_f32 v198, v32, v33
	v_cvt_pk_bf16_f32 v199, v34, v35
	global_store_dwordx4 v[212:213], v[196:199], off offset:256
	v_lshlrev_b32_e32 v218, 16, v196
	v_and_b32_e32 v219, 0xffff0000, v196
	v_pk_add_f32 v[218:219], v[36:37], v[218:219] neg_lo:[0,1] neg_hi:[0,1]
	v_pk_fma_f32 v[230:231], v[36:37], v[36:37], v[230:231]
	v_cvt_pk_bf16_f32 v200, v218, v219
	v_lshlrev_b32_e32 v218, 16, v197
	v_and_b32_e32 v219, 0xffff0000, v197
	v_pk_add_f32 v[218:219], v[38:39], v[218:219] neg_lo:[0,1] neg_hi:[0,1]
	v_pk_fma_f32 v[230:231], v[38:39], v[38:39], v[230:231]
	v_cvt_pk_bf16_f32 v201, v218, v219
	v_lshlrev_b32_e32 v218, 16, v198
	v_and_b32_e32 v219, 0xffff0000, v198
	v_pk_add_f32 v[218:219], v[32:33], v[218:219] neg_lo:[0,1] neg_hi:[0,1]
	v_pk_fma_f32 v[230:231], v[32:33], v[32:33], v[230:231]
	v_cvt_pk_bf16_f32 v202, v218, v219
	v_lshlrev_b32_e32 v218, 16, v199
	v_and_b32_e32 v219, 0xffff0000, v199
	v_pk_add_f32 v[218:219], v[34:35], v[218:219] neg_lo:[0,1] neg_hi:[0,1]
	v_pk_fma_f32 v[230:231], v[34:35], v[34:35], v[230:231]
	v_cvt_pk_bf16_f32 v203, v218, v219
	global_store_dwordx4 v[186:187], v[200:203], off offset:256
	v_add_f32_e32 v236, v230, v231
	v_mov_b32_e32 v237, v236
	s_nop 1
	v_permlane16_swap_b32_e32 v237, v236
	v_add_f32_e32 v236, v236, v237
	v_mov_b32_e32 v237, v236
	s_nop 1
	v_permlane32_swap_b32_e32 v237, v236
	v_add_f32_e32 v236, v236, v237
	v_add_co_u32_e32 v142, vcc, 0x4800, v134
	s_nop 1
	v_addc_co_u32_e32 v143, vcc, 0, v135, vcc
	s_and_saveexec_b64 s[22:23], s[4:5]
	global_store_dword v[142:143], v236, off
	s_mov_b64 exec, s[22:23]
	v_add_co_u32_e32 v212, vcc, 0xa0000, v204
	s_nop 1
	v_addc_co_u32_e32 v213, vcc, 0, v205, vcc
	v_add_co_u32_e32 v186, vcc, 0xa0000, v206
	s_nop 1
	v_addc_co_u32_e32 v187, vcc, 0, v207, vcc
	v_permlane16_swap_b32_e32 v28, v24
	v_permlane16_swap_b32_e32 v29, v25
	v_permlane16_swap_b32_e32 v30, v26
	v_permlane16_swap_b32_e32 v31, v27
	s_waitcnt vmcnt(17)
	v_lshlrev_b32_e32 v218, 16, v144
	v_and_b32_e32 v219, 0xffff0000, v144
	s_waitcnt vmcnt(16)
	v_lshlrev_b32_e32 v228, 16, v148
	v_and_b32_e32 v229, 0xffff0000, v148
	v_lshlrev_b32_e32 v208, 16, v145
	v_and_b32_e32 v209, 0xffff0000, v145
	v_lshlrev_b32_e32 v210, 16, v149
	v_and_b32_e32 v211, 0xffff0000, v149
	v_pk_add_f32 v[218:219], v[218:219], v[228:229]
	v_pk_add_f32 v[208:209], v[208:209], v[210:211]
	v_pk_add_f32 v[28:29], v[218:219], v[28:29]
	v_pk_add_f32 v[30:31], v[208:209], v[30:31]
	v_lshlrev_b32_e32 v218, 16, v146
	v_and_b32_e32 v219, 0xffff0000, v146
	v_lshlrev_b32_e32 v228, 16, v150
	v_and_b32_e32 v229, 0xffff0000, v150
	v_lshlrev_b32_e32 v208, 16, v147
	v_and_b32_e32 v209, 0xffff0000, v147
	v_lshlrev_b32_e32 v210, 16, v151
	v_and_b32_e32 v211, 0xffff0000, v151
	v_pk_add_f32 v[218:219], v[218:219], v[228:229]
	v_pk_add_f32 v[208:209], v[208:209], v[210:211]
	v_pk_add_f32 v[24:25], v[218:219], v[24:25]
	v_pk_add_f32 v[26:27], v[208:209], v[26:27]
	v_cvt_pk_bf16_f32 v144, v28, v29
	v_cvt_pk_bf16_f32 v145, v30, v31
	v_cvt_pk_bf16_f32 v146, v24, v25
	v_cvt_pk_bf16_f32 v147, v26, v27
	global_store_dwordx4 v[212:213], v[144:147], off
	v_lshlrev_b32_e32 v218, 16, v144
	v_and_b32_e32 v219, 0xffff0000, v144
	v_pk_add_f32 v[218:219], v[28:29], v[218:219] neg_lo:[0,1] neg_hi:[0,1]
	v_pk_mul_f32 v[230:231], v[28:29], v[28:29]
	v_cvt_pk_bf16_f32 v148, v218, v219
	v_lshlrev_b32_e32 v218, 16, v145
	v_and_b32_e32 v219, 0xffff0000, v145
	v_pk_add_f32 v[218:219], v[30:31], v[218:219] neg_lo:[0,1] neg_hi:[0,1]
	v_pk_fma_f32 v[230:231], v[30:31], v[30:31], v[230:231]
	v_cvt_pk_bf16_f32 v149, v218, v219
	v_lshlrev_b32_e32 v218, 16, v146
	v_and_b32_e32 v219, 0xffff0000, v146
	v_pk_add_f32 v[218:219], v[24:25], v[218:219] neg_lo:[0,1] neg_hi:[0,1]
	v_pk_fma_f32 v[230:231], v[24:25], v[24:25], v[230:231]
	v_cvt_pk_bf16_f32 v150, v218, v219
	v_lshlrev_b32_e32 v218, 16, v147
	v_and_b32_e32 v219, 0xffff0000, v147
	v_pk_add_f32 v[218:219], v[26:27], v[218:219] neg_lo:[0,1] neg_hi:[0,1]
	v_pk_fma_f32 v[230:231], v[26:27], v[26:27], v[230:231]
	v_cvt_pk_bf16_f32 v151, v218, v219
	global_store_dwordx4 v[186:187], v[148:151], off
	v_permlane16_swap_b32_e32 v20, v16
	v_permlane16_swap_b32_e32 v21, v17
	v_permlane16_swap_b32_e32 v22, v18
	v_permlane16_swap_b32_e32 v23, v19
	s_waitcnt vmcnt(17)
	v_lshlrev_b32_e32 v218, 16, v152
	v_and_b32_e32 v219, 0xffff0000, v152
	s_waitcnt vmcnt(16)
	v_lshlrev_b32_e32 v228, 16, v156
	v_and_b32_e32 v229, 0xffff0000, v156
	v_lshlrev_b32_e32 v208, 16, v153
	v_and_b32_e32 v209, 0xffff0000, v153
	v_lshlrev_b32_e32 v210, 16, v157
	v_and_b32_e32 v211, 0xffff0000, v157
	v_pk_add_f32 v[218:219], v[218:219], v[228:229]
	v_pk_add_f32 v[208:209], v[208:209], v[210:211]
	v_pk_add_f32 v[20:21], v[218:219], v[20:21]
	v_pk_add_f32 v[22:23], v[208:209], v[22:23]
	v_lshlrev_b32_e32 v218, 16, v154
	v_and_b32_e32 v219, 0xffff0000, v154
	v_lshlrev_b32_e32 v228, 16, v158
	v_and_b32_e32 v229, 0xffff0000, v158
	v_lshlrev_b32_e32 v208, 16, v155
	v_and_b32_e32 v209, 0xffff0000, v155
	v_lshlrev_b32_e32 v210, 16, v159
	v_and_b32_e32 v211, 0xffff0000, v159
	v_pk_add_f32 v[218:219], v[218:219], v[228:229]
	v_pk_add_f32 v[208:209], v[208:209], v[210:211]
	v_pk_add_f32 v[16:17], v[218:219], v[16:17]
	v_pk_add_f32 v[18:19], v[208:209], v[18:19]
	v_cvt_pk_bf16_f32 v152, v20, v21
	v_cvt_pk_bf16_f32 v153, v22, v23
	v_cvt_pk_bf16_f32 v154, v16, v17
	v_cvt_pk_bf16_f32 v155, v18, v19
	global_store_dwordx4 v[212:213], v[152:155], off offset:256
	v_lshlrev_b32_e32 v218, 16, v152
	v_and_b32_e32 v219, 0xffff0000, v152
	v_pk_add_f32 v[218:219], v[20:21], v[218:219] neg_lo:[0,1] neg_hi:[0,1]
	v_pk_fma_f32 v[230:231], v[20:21], v[20:21], v[230:231]
	v_cvt_pk_bf16_f32 v156, v218, v219
	v_lshlrev_b32_e32 v218, 16, v153
	v_and_b32_e32 v219, 0xffff0000, v153
	v_pk_add_f32 v[218:219], v[22:23], v[218:219] neg_lo:[0,1] neg_hi:[0,1]
	v_pk_fma_f32 v[230:231], v[22:23], v[22:23], v[230:231]
	v_cvt_pk_bf16_f32 v157, v218, v219
	v_lshlrev_b32_e32 v218, 16, v154
	v_and_b32_e32 v219, 0xffff0000, v154
	v_pk_add_f32 v[218:219], v[16:17], v[218:219] neg_lo:[0,1] neg_hi:[0,1]
	v_pk_fma_f32 v[230:231], v[16:17], v[16:17], v[230:231]
	v_cvt_pk_bf16_f32 v158, v218, v219
	v_lshlrev_b32_e32 v218, 16, v155
	v_and_b32_e32 v219, 0xffff0000, v155
	v_pk_add_f32 v[218:219], v[18:19], v[218:219] neg_lo:[0,1] neg_hi:[0,1]
	v_pk_fma_f32 v[230:231], v[18:19], v[18:19], v[230:231]
	v_cvt_pk_bf16_f32 v159, v218, v219
	global_store_dwordx4 v[186:187], v[156:159], off offset:256
	v_add_f32_e32 v236, v230, v231
	v_mov_b32_e32 v237, v236
	s_nop 1
	v_permlane16_swap_b32_e32 v237, v236
	v_add_f32_e32 v236, v236, v237
	v_mov_b32_e32 v237, v236
	s_nop 1
	v_permlane32_swap_b32_e32 v237, v236
	v_add_f32_e32 v236, v236, v237
	v_add_co_u32_e32 v142, vcc, 0x5000, v134
	s_nop 1
	v_addc_co_u32_e32 v143, vcc, 0, v135, vcc
	s_and_saveexec_b64 s[22:23], s[4:5]
	global_store_dword v[142:143], v236, off
	s_mov_b64 exec, s[22:23]
	v_add_co_u32_e32 v212, vcc, 0xb0000, v204
	s_nop 1
	v_addc_co_u32_e32 v213, vcc, 0, v205, vcc
	v_add_co_u32_e32 v186, vcc, 0xb0000, v206
	s_nop 1
	v_addc_co_u32_e32 v187, vcc, 0, v207, vcc
	v_permlane16_swap_b32_e32 v12, v8
	v_permlane16_swap_b32_e32 v13, v9
	v_permlane16_swap_b32_e32 v14, v10
	v_permlane16_swap_b32_e32 v15, v11
	s_waitcnt vmcnt(13)
	v_lshlrev_b32_e32 v218, 16, v160
	v_and_b32_e32 v219, 0xffff0000, v160
	s_waitcnt vmcnt(12)
	v_lshlrev_b32_e32 v228, 16, v164
	v_and_b32_e32 v229, 0xffff0000, v164
	v_lshlrev_b32_e32 v208, 16, v161
	v_and_b32_e32 v209, 0xffff0000, v161
	v_lshlrev_b32_e32 v210, 16, v165
	v_and_b32_e32 v211, 0xffff0000, v165
	v_pk_add_f32 v[218:219], v[218:219], v[228:229]
	v_pk_add_f32 v[208:209], v[208:209], v[210:211]
	v_pk_add_f32 v[12:13], v[218:219], v[12:13]
	v_pk_add_f32 v[14:15], v[208:209], v[14:15]
	v_lshlrev_b32_e32 v218, 16, v162
	v_and_b32_e32 v219, 0xffff0000, v162
	v_lshlrev_b32_e32 v228, 16, v166
	v_and_b32_e32 v229, 0xffff0000, v166
	v_lshlrev_b32_e32 v208, 16, v163
	v_and_b32_e32 v209, 0xffff0000, v163
	v_lshlrev_b32_e32 v210, 16, v167
	v_and_b32_e32 v211, 0xffff0000, v167
	v_pk_add_f32 v[218:219], v[218:219], v[228:229]
	v_pk_add_f32 v[208:209], v[208:209], v[210:211]
	v_pk_add_f32 v[8:9], v[218:219], v[8:9]
	v_pk_add_f32 v[10:11], v[208:209], v[10:11]
	v_cvt_pk_bf16_f32 v160, v12, v13
	v_cvt_pk_bf16_f32 v161, v14, v15
	v_cvt_pk_bf16_f32 v162, v8, v9
	v_cvt_pk_bf16_f32 v163, v10, v11
	global_store_dwordx4 v[212:213], v[160:163], off
	v_lshlrev_b32_e32 v218, 16, v160
	v_and_b32_e32 v219, 0xffff0000, v160
	v_pk_add_f32 v[218:219], v[12:13], v[218:219] neg_lo:[0,1] neg_hi:[0,1]
	v_pk_mul_f32 v[230:231], v[12:13], v[12:13]
	v_cvt_pk_bf16_f32 v164, v218, v219
	v_lshlrev_b32_e32 v218, 16, v161
	v_and_b32_e32 v219, 0xffff0000, v161
	v_pk_add_f32 v[218:219], v[14:15], v[218:219] neg_lo:[0,1] neg_hi:[0,1]
	v_pk_fma_f32 v[230:231], v[14:15], v[14:15], v[230:231]
	v_cvt_pk_bf16_f32 v165, v218, v219
	v_lshlrev_b32_e32 v218, 16, v162
	v_and_b32_e32 v219, 0xffff0000, v162
	v_pk_add_f32 v[218:219], v[8:9], v[218:219] neg_lo:[0,1] neg_hi:[0,1]
	v_pk_fma_f32 v[230:231], v[8:9], v[8:9], v[230:231]
	v_cvt_pk_bf16_f32 v166, v218, v219
	v_lshlrev_b32_e32 v218, 16, v163
	v_and_b32_e32 v219, 0xffff0000, v163
	v_pk_add_f32 v[218:219], v[10:11], v[218:219] neg_lo:[0,1] neg_hi:[0,1]
	v_pk_fma_f32 v[230:231], v[10:11], v[10:11], v[230:231]
	v_cvt_pk_bf16_f32 v167, v218, v219
	global_store_dwordx4 v[186:187], v[164:167], off
	v_permlane16_swap_b32_e32 v4, v0
	v_permlane16_swap_b32_e32 v5, v1
	v_permlane16_swap_b32_e32 v6, v2
	v_permlane16_swap_b32_e32 v7, v3
	s_waitcnt vmcnt(13)
	v_lshlrev_b32_e32 v218, 16, v168
	v_and_b32_e32 v219, 0xffff0000, v168
	s_waitcnt vmcnt(12)
	v_lshlrev_b32_e32 v228, 16, v172
	v_and_b32_e32 v229, 0xffff0000, v172
	v_lshlrev_b32_e32 v208, 16, v169
	v_and_b32_e32 v209, 0xffff0000, v169
	v_lshlrev_b32_e32 v210, 16, v173
	v_and_b32_e32 v211, 0xffff0000, v173
	v_pk_add_f32 v[218:219], v[218:219], v[228:229]
	v_pk_add_f32 v[208:209], v[208:209], v[210:211]
	v_pk_add_f32 v[4:5], v[218:219], v[4:5]
	v_pk_add_f32 v[6:7], v[208:209], v[6:7]
	v_lshlrev_b32_e32 v218, 16, v170
	v_and_b32_e32 v219, 0xffff0000, v170
	v_lshlrev_b32_e32 v228, 16, v174
	v_and_b32_e32 v229, 0xffff0000, v174
	v_lshlrev_b32_e32 v208, 16, v171
	v_and_b32_e32 v209, 0xffff0000, v171
	v_lshlrev_b32_e32 v210, 16, v175
	v_and_b32_e32 v211, 0xffff0000, v175
	v_pk_add_f32 v[218:219], v[218:219], v[228:229]
	v_pk_add_f32 v[208:209], v[208:209], v[210:211]
	v_pk_add_f32 v[0:1], v[218:219], v[0:1]
	v_pk_add_f32 v[2:3], v[208:209], v[2:3]
	v_cvt_pk_bf16_f32 v168, v4, v5
	v_cvt_pk_bf16_f32 v169, v6, v7
	v_cvt_pk_bf16_f32 v170, v0, v1
	v_cvt_pk_bf16_f32 v171, v2, v3
	global_store_dwordx4 v[212:213], v[168:171], off offset:256
	v_lshlrev_b32_e32 v218, 16, v168
	v_and_b32_e32 v219, 0xffff0000, v168
	v_pk_add_f32 v[218:219], v[4:5], v[218:219] neg_lo:[0,1] neg_hi:[0,1]
	v_pk_fma_f32 v[230:231], v[4:5], v[4:5], v[230:231]
	v_cvt_pk_bf16_f32 v172, v218, v219
	v_lshlrev_b32_e32 v218, 16, v169
	v_and_b32_e32 v219, 0xffff0000, v169
	v_pk_add_f32 v[218:219], v[6:7], v[218:219] neg_lo:[0,1] neg_hi:[0,1]
	v_pk_fma_f32 v[230:231], v[6:7], v[6:7], v[230:231]
	v_cvt_pk_bf16_f32 v173, v218, v219
	v_lshlrev_b32_e32 v218, 16, v170
	v_and_b32_e32 v219, 0xffff0000, v170
	v_pk_add_f32 v[218:219], v[0:1], v[218:219] neg_lo:[0,1] neg_hi:[0,1]
	v_pk_fma_f32 v[230:231], v[0:1], v[0:1], v[230:231]
	v_cvt_pk_bf16_f32 v174, v218, v219
	v_lshlrev_b32_e32 v218, 16, v171
	v_and_b32_e32 v219, 0xffff0000, v171
	v_pk_add_f32 v[218:219], v[2:3], v[218:219] neg_lo:[0,1] neg_hi:[0,1]
	v_pk_fma_f32 v[230:231], v[2:3], v[2:3], v[230:231]
	v_cvt_pk_bf16_f32 v175, v218, v219
	global_store_dwordx4 v[186:187], v[172:175], off offset:256
	v_add_f32_e32 v236, v230, v231
	v_mov_b32_e32 v237, v236
	s_nop 1
	v_permlane16_swap_b32_e32 v237, v236
	v_add_f32_e32 v236, v236, v237
	v_mov_b32_e32 v237, v236
	s_nop 1
	v_permlane32_swap_b32_e32 v237, v236
	v_add_f32_e32 v236, v236, v237
	v_add_co_u32_e32 v142, vcc, 0x5800, v134
	s_nop 1
	v_addc_co_u32_e32 v143, vcc, 0, v135, vcc
	s_and_saveexec_b64 s[22:23], s[4:5]
	global_store_dword v[142:143], v236, off
	s_mov_b64 exec, s[22:23]
	s_and_b64 vcc, exec, s[6:7]
	s_mov_b64 s[6:7], -1
	s_cbranch_vccnz .LBB0_279
	s_branch .LBB0_455

.LBB0_497:
	s_or_b64 exec, exec, s[6:7]
	s_and_b32 s6, s19, -4
	s_cmp_lg_u32 s6, 12
	s_mov_b64 s[6:7], -1
	s_movk_i32 s31, 0x2000
	s_cbranch_scc0 .LBB0_504
	s_and_b32 s6, s19, -2
	s_cmp_lg_u32 s6, 16
	s_mov_b64 s[6:7], -1
	s_cbranch_scc0 .LBB0_500
	s_cmp_lt_i32 s19, 2
	s_cselect_b64 vcc, -1, 0
	s_lshl_b32 s6, s19, 8
	s_ashr_i32 s7, s6, 31
	v_mov_b64_e32 v[130:131], s[8:9]
	v_and_b32_e32 v136, 16, v225
	v_cndmask_b32_e32 v140, 1.0, v221, vcc
	s_lshl_b64 s[6:7], s[6:7], 1
	s_mov_b32 s15, s93
	v_lshrrev_b32_e32 v137, 1, v136
	v_lshlrev_b32_e32 v176, 1, v148
	v_add3_u32 v176, v176, v136, v137
	s_waitcnt lgkmcnt(0)
	v_mad_i64_i32 v[134:135], s[28:29], v156, s96, v[130:131]
	v_mul_f32_e32 v132, v140, v168
	v_lshl_add_u64 v[134:135], v[134:135], 0, s[6:7]
	v_lshl_add_u64 v[134:135], v[134:135], 0, s[14:15]
	v_lshl_add_u64 v[134:135], v[134:135], 0, v[176:177]
	v_permlane16_swap_b32_e32 v124, v120
	v_permlane16_swap_b32_e32 v125, v121
	v_permlane16_swap_b32_e32 v126, v122
	v_permlane16_swap_b32_e32 v127, v123
	v_pk_mul_f32 v[124:125], v[124:125], v[132:133] op_sel_hi:[1,0]
	v_pk_mul_f32 v[126:127], v[126:127], v[132:133] op_sel_hi:[1,0]
	v_pk_mul_f32 v[120:121], v[120:121], v[132:133] op_sel_hi:[1,0]
	v_pk_mul_f32 v[122:123], v[122:123], v[132:133] op_sel_hi:[1,0]
	v_cvt_pk_bf16_f32 v136, v124, v125
	v_cvt_pk_bf16_f32 v137, v126, v127
	v_cvt_pk_bf16_f32 v138, v120, v121
	v_cvt_pk_bf16_f32 v139, v122, v123
	global_store_dwordx4 v[134:135], v[136:139], off
	v_permlane16_swap_b32_e32 v116, v112
	v_permlane16_swap_b32_e32 v117, v113
	v_permlane16_swap_b32_e32 v118, v114
	v_permlane16_swap_b32_e32 v119, v115
	v_pk_mul_f32 v[116:117], v[116:117], v[132:133] op_sel_hi:[1,0]
	v_pk_mul_f32 v[118:119], v[118:119], v[132:133] op_sel_hi:[1,0]
	v_pk_mul_f32 v[112:113], v[112:113], v[132:133] op_sel_hi:[1,0]
	v_pk_mul_f32 v[114:115], v[114:115], v[132:133] op_sel_hi:[1,0]
	v_cvt_pk_bf16_f32 v136, v116, v117
	v_cvt_pk_bf16_f32 v137, v118, v119
	v_cvt_pk_bf16_f32 v138, v112, v113
	v_cvt_pk_bf16_f32 v139, v114, v115
	global_store_dwordx4 v[134:135], v[136:139], off offset:256
	v_add_u32_e32 v133, 0x10, v156
	v_mad_i64_i32 v[134:135], s[28:29], v133, s96, v[130:131]
	v_mul_f32_e32 v132, v140, v169
	v_lshl_add_u64 v[134:135], v[134:135], 0, s[6:7]
	v_lshl_add_u64 v[134:135], v[134:135], 0, s[14:15]
	v_lshl_add_u64 v[134:135], v[134:135], 0, v[176:177]
	v_permlane16_swap_b32_e32 v108, v104
	v_permlane16_swap_b32_e32 v109, v105
	v_permlane16_swap_b32_e32 v110, v106
	v_permlane16_swap_b32_e32 v111, v107
	v_pk_mul_f32 v[108:109], v[108:109], v[132:133] op_sel_hi:[1,0]
	v_pk_mul_f32 v[110:111], v[110:111], v[132:133] op_sel_hi:[1,0]
	v_pk_mul_f32 v[104:105], v[104:105], v[132:133] op_sel_hi:[1,0]
	v_pk_mul_f32 v[106:107], v[106:107], v[132:133] op_sel_hi:[1,0]
	v_cvt_pk_bf16_f32 v136, v108, v109
	v_cvt_pk_bf16_f32 v137, v110, v111
	v_cvt_pk_bf16_f32 v138, v104, v105
	v_cvt_pk_bf16_f32 v139, v106, v107
	global_store_dwordx4 v[134:135], v[136:139], off
	v_permlane16_swap_b32_e32 v100, v96
	v_permlane16_swap_b32_e32 v101, v97
	v_permlane16_swap_b32_e32 v102, v98
	v_permlane16_swap_b32_e32 v103, v99
	v_pk_mul_f32 v[100:101], v[100:101], v[132:133] op_sel_hi:[1,0]
	v_pk_mul_f32 v[102:103], v[102:103], v[132:133] op_sel_hi:[1,0]
	v_pk_mul_f32 v[96:97], v[96:97], v[132:133] op_sel_hi:[1,0]
	v_pk_mul_f32 v[98:99], v[98:99], v[132:133] op_sel_hi:[1,0]
	v_cvt_pk_bf16_f32 v136, v100, v101
	v_cvt_pk_bf16_f32 v137, v102, v103
	v_cvt_pk_bf16_f32 v138, v96, v97
	v_cvt_pk_bf16_f32 v139, v98, v99
	global_store_dwordx4 v[134:135], v[136:139], off offset:256
	v_add_u32_e32 v133, 0x20, v156
	v_mad_i64_i32 v[134:135], s[28:29], v133, s96, v[130:131]
	v_mul_f32_e32 v132, v140, v166
	v_lshl_add_u64 v[134:135], v[134:135], 0, s[6:7]
	v_lshl_add_u64 v[134:135], v[134:135], 0, s[14:15]
	v_lshl_add_u64 v[134:135], v[134:135], 0, v[176:177]
	v_permlane16_swap_b32_e32 v92, v88
	v_permlane16_swap_b32_e32 v93, v89
	v_permlane16_swap_b32_e32 v94, v90
	v_permlane16_swap_b32_e32 v95, v91
	v_pk_mul_f32 v[92:93], v[92:93], v[132:133] op_sel_hi:[1,0]
	v_pk_mul_f32 v[94:95], v[94:95], v[132:133] op_sel_hi:[1,0]
	v_pk_mul_f32 v[88:89], v[88:89], v[132:133] op_sel_hi:[1,0]
	v_pk_mul_f32 v[90:91], v[90:91], v[132:133] op_sel_hi:[1,0]
	v_cvt_pk_bf16_f32 v136, v92, v93
	v_cvt_pk_bf16_f32 v137, v94, v95
	v_cvt_pk_bf16_f32 v138, v88, v89
	v_cvt_pk_bf16_f32 v139, v90, v91
	global_store_dwordx4 v[134:135], v[136:139], off
	v_permlane16_swap_b32_e32 v84, v80
	v_permlane16_swap_b32_e32 v85, v81
	v_permlane16_swap_b32_e32 v86, v82
	v_permlane16_swap_b32_e32 v87, v83
	v_pk_mul_f32 v[84:85], v[84:85], v[132:133] op_sel_hi:[1,0]
	v_pk_mul_f32 v[86:87], v[86:87], v[132:133] op_sel_hi:[1,0]
	v_pk_mul_f32 v[80:81], v[80:81], v[132:133] op_sel_hi:[1,0]
	v_pk_mul_f32 v[82:83], v[82:83], v[132:133] op_sel_hi:[1,0]
	v_cvt_pk_bf16_f32 v136, v84, v85
	v_cvt_pk_bf16_f32 v137, v86, v87
	v_cvt_pk_bf16_f32 v138, v80, v81
	v_cvt_pk_bf16_f32 v139, v82, v83
	global_store_dwordx4 v[134:135], v[136:139], off offset:256
	v_add_u32_e32 v133, 0x30, v156
	v_mad_i64_i32 v[134:135], s[28:29], v133, s96, v[130:131]
	v_mul_f32_e32 v132, v140, v167
	v_lshl_add_u64 v[134:135], v[134:135], 0, s[6:7]
	v_lshl_add_u64 v[134:135], v[134:135], 0, s[14:15]
	v_lshl_add_u64 v[134:135], v[134:135], 0, v[176:177]
	v_permlane16_swap_b32_e32 v76, v72
	v_permlane16_swap_b32_e32 v77, v73
	v_permlane16_swap_b32_e32 v78, v74
	v_permlane16_swap_b32_e32 v79, v75
	v_pk_mul_f32 v[76:77], v[76:77], v[132:133] op_sel_hi:[1,0]
	v_pk_mul_f32 v[78:79], v[78:79], v[132:133] op_sel_hi:[1,0]
	v_pk_mul_f32 v[72:73], v[72:73], v[132:133] op_sel_hi:[1,0]
	v_pk_mul_f32 v[74:75], v[74:75], v[132:133] op_sel_hi:[1,0]
	v_cvt_pk_bf16_f32 v136, v76, v77
	v_cvt_pk_bf16_f32 v137, v78, v79
	v_cvt_pk_bf16_f32 v138, v72, v73
	v_cvt_pk_bf16_f32 v139, v74, v75
	global_store_dwordx4 v[134:135], v[136:139], off
	v_permlane16_swap_b32_e32 v68, v64
	v_permlane16_swap_b32_e32 v69, v65
	v_permlane16_swap_b32_e32 v70, v66
	v_permlane16_swap_b32_e32 v71, v67
	v_pk_mul_f32 v[68:69], v[68:69], v[132:133] op_sel_hi:[1,0]
	v_pk_mul_f32 v[70:71], v[70:71], v[132:133] op_sel_hi:[1,0]
	v_pk_mul_f32 v[64:65], v[64:65], v[132:133] op_sel_hi:[1,0]
	v_pk_mul_f32 v[66:67], v[66:67], v[132:133] op_sel_hi:[1,0]
	v_cvt_pk_bf16_f32 v136, v68, v69
	v_cvt_pk_bf16_f32 v137, v70, v71
	v_cvt_pk_bf16_f32 v138, v64, v65
	v_cvt_pk_bf16_f32 v139, v66, v67
	global_store_dwordx4 v[134:135], v[136:139], off offset:256
	v_add_u32_e32 v133, 0x80, v156
	v_mad_i64_i32 v[134:135], s[28:29], v133, s96, v[130:131]
	v_mul_f32_e32 v132, v140, v162
	v_lshl_add_u64 v[134:135], v[134:135], 0, s[6:7]
	v_lshl_add_u64 v[134:135], v[134:135], 0, s[14:15]
	v_lshl_add_u64 v[134:135], v[134:135], 0, v[176:177]
	v_permlane16_swap_b32_e32 v60, v56
	v_permlane16_swap_b32_e32 v61, v57
	v_permlane16_swap_b32_e32 v62, v58
	v_permlane16_swap_b32_e32 v63, v59
	v_pk_mul_f32 v[60:61], v[60:61], v[132:133] op_sel_hi:[1,0]
	v_pk_mul_f32 v[62:63], v[62:63], v[132:133] op_sel_hi:[1,0]
	v_pk_mul_f32 v[56:57], v[56:57], v[132:133] op_sel_hi:[1,0]
	v_pk_mul_f32 v[58:59], v[58:59], v[132:133] op_sel_hi:[1,0]
	v_cvt_pk_bf16_f32 v136, v60, v61
	v_cvt_pk_bf16_f32 v137, v62, v63
	v_cvt_pk_bf16_f32 v138, v56, v57
	v_cvt_pk_bf16_f32 v139, v58, v59
	global_store_dwordx4 v[134:135], v[136:139], off
	v_permlane16_swap_b32_e32 v52, v48
	v_permlane16_swap_b32_e32 v53, v49
	v_permlane16_swap_b32_e32 v54, v50
	v_permlane16_swap_b32_e32 v55, v51
	v_pk_mul_f32 v[52:53], v[52:53], v[132:133] op_sel_hi:[1,0]
	v_pk_mul_f32 v[54:55], v[54:55], v[132:133] op_sel_hi:[1,0]
	v_pk_mul_f32 v[48:49], v[48:49], v[132:133] op_sel_hi:[1,0]
	v_pk_mul_f32 v[50:51], v[50:51], v[132:133] op_sel_hi:[1,0]
	v_cvt_pk_bf16_f32 v136, v52, v53
	v_cvt_pk_bf16_f32 v137, v54, v55
	v_cvt_pk_bf16_f32 v138, v48, v49
	v_cvt_pk_bf16_f32 v139, v50, v51
	global_store_dwordx4 v[134:135], v[136:139], off offset:256
	v_add_u32_e32 v133, 0x90, v156
	v_mad_i64_i32 v[134:135], s[28:29], v133, s96, v[130:131]
	v_mul_f32_e32 v132, v140, v163
	v_lshl_add_u64 v[134:135], v[134:135], 0, s[6:7]
	v_lshl_add_u64 v[134:135], v[134:135], 0, s[14:15]
	v_lshl_add_u64 v[134:135], v[134:135], 0, v[176:177]
	v_permlane16_swap_b32_e32 v44, v40
	v_permlane16_swap_b32_e32 v45, v41
	v_permlane16_swap_b32_e32 v46, v42
	v_permlane16_swap_b32_e32 v47, v43
	v_pk_mul_f32 v[44:45], v[44:45], v[132:133] op_sel_hi:[1,0]
	v_pk_mul_f32 v[46:47], v[46:47], v[132:133] op_sel_hi:[1,0]
	v_pk_mul_f32 v[40:41], v[40:41], v[132:133] op_sel_hi:[1,0]
	v_pk_mul_f32 v[42:43], v[42:43], v[132:133] op_sel_hi:[1,0]
	v_cvt_pk_bf16_f32 v136, v44, v45
	v_cvt_pk_bf16_f32 v137, v46, v47
	v_cvt_pk_bf16_f32 v138, v40, v41
	v_cvt_pk_bf16_f32 v139, v42, v43
	global_store_dwordx4 v[134:135], v[136:139], off
	v_permlane16_swap_b32_e32 v36, v32
	v_permlane16_swap_b32_e32 v37, v33
	v_permlane16_swap_b32_e32 v38, v34
	v_permlane16_swap_b32_e32 v39, v35
	v_pk_mul_f32 v[36:37], v[36:37], v[132:133] op_sel_hi:[1,0]
	v_pk_mul_f32 v[38:39], v[38:39], v[132:133] op_sel_hi:[1,0]
	v_pk_mul_f32 v[32:33], v[32:33], v[132:133] op_sel_hi:[1,0]
	v_pk_mul_f32 v[34:35], v[34:35], v[132:133] op_sel_hi:[1,0]
	v_cvt_pk_bf16_f32 v136, v36, v37
	v_cvt_pk_bf16_f32 v137, v38, v39
	v_cvt_pk_bf16_f32 v138, v32, v33
	v_cvt_pk_bf16_f32 v139, v34, v35
	global_store_dwordx4 v[134:135], v[136:139], off offset:256
	v_add_u32_e32 v133, 0xa0, v156
	v_mad_i64_i32 v[134:135], s[28:29], v133, s96, v[130:131]
	v_mul_f32_e32 v132, v140, v128
	v_lshl_add_u64 v[134:135], v[134:135], 0, s[6:7]
	v_lshl_add_u64 v[134:135], v[134:135], 0, s[14:15]
	v_lshl_add_u64 v[134:135], v[134:135], 0, v[176:177]
	v_permlane16_swap_b32_e32 v28, v24
	v_permlane16_swap_b32_e32 v29, v25
	v_permlane16_swap_b32_e32 v30, v26
	v_permlane16_swap_b32_e32 v31, v27
	v_pk_mul_f32 v[28:29], v[28:29], v[132:133] op_sel_hi:[1,0]
	v_pk_mul_f32 v[30:31], v[30:31], v[132:133] op_sel_hi:[1,0]
	v_pk_mul_f32 v[24:25], v[24:25], v[132:133] op_sel_hi:[1,0]
	v_pk_mul_f32 v[26:27], v[26:27], v[132:133] op_sel_hi:[1,0]
	v_cvt_pk_bf16_f32 v136, v28, v29
	v_cvt_pk_bf16_f32 v137, v30, v31
	v_cvt_pk_bf16_f32 v138, v24, v25
	v_cvt_pk_bf16_f32 v139, v26, v27
	global_store_dwordx4 v[134:135], v[136:139], off
	v_permlane16_swap_b32_e32 v20, v16
	v_permlane16_swap_b32_e32 v21, v17
	v_permlane16_swap_b32_e32 v22, v18
	v_permlane16_swap_b32_e32 v23, v19
	v_pk_mul_f32 v[20:21], v[20:21], v[132:133] op_sel_hi:[1,0]
	v_pk_mul_f32 v[22:23], v[22:23], v[132:133] op_sel_hi:[1,0]
	v_pk_mul_f32 v[16:17], v[16:17], v[132:133] op_sel_hi:[1,0]
	v_pk_mul_f32 v[18:19], v[18:19], v[132:133] op_sel_hi:[1,0]
	v_cvt_pk_bf16_f32 v136, v20, v21
	v_cvt_pk_bf16_f32 v137, v22, v23
	v_cvt_pk_bf16_f32 v138, v16, v17
	v_cvt_pk_bf16_f32 v139, v18, v19
	global_store_dwordx4 v[134:135], v[136:139], off offset:256
	v_add_u32_e32 v133, 0xb0, v156
	v_mad_i64_i32 v[134:135], s[28:29], v133, s96, v[130:131]
	v_mul_f32_e32 v132, v140, v129
	v_lshl_add_u64 v[134:135], v[134:135], 0, s[6:7]
	v_lshl_add_u64 v[134:135], v[134:135], 0, s[14:15]
	v_lshl_add_u64 v[134:135], v[134:135], 0, v[176:177]
	v_permlane16_swap_b32_e32 v12, v8
	v_permlane16_swap_b32_e32 v13, v9
	v_permlane16_swap_b32_e32 v14, v10
	v_permlane16_swap_b32_e32 v15, v11
	v_pk_mul_f32 v[12:13], v[12:13], v[132:133] op_sel_hi:[1,0]
	v_pk_mul_f32 v[14:15], v[14:15], v[132:133] op_sel_hi:[1,0]
	v_pk_mul_f32 v[8:9], v[8:9], v[132:133] op_sel_hi:[1,0]
	v_pk_mul_f32 v[10:11], v[10:11], v[132:133] op_sel_hi:[1,0]
	v_cvt_pk_bf16_f32 v136, v12, v13
	v_cvt_pk_bf16_f32 v137, v14, v15
	v_cvt_pk_bf16_f32 v138, v8, v9
	v_cvt_pk_bf16_f32 v139, v10, v11
	global_store_dwordx4 v[134:135], v[136:139], off
	v_permlane16_swap_b32_e32 v4, v0
	v_permlane16_swap_b32_e32 v5, v1
	v_permlane16_swap_b32_e32 v6, v2
	v_permlane16_swap_b32_e32 v7, v3
	v_pk_mul_f32 v[4:5], v[4:5], v[132:133] op_sel_hi:[1,0]
	v_pk_mul_f32 v[6:7], v[6:7], v[132:133] op_sel_hi:[1,0]
	v_pk_mul_f32 v[0:1], v[0:1], v[132:133] op_sel_hi:[1,0]
	v_pk_mul_f32 v[2:3], v[2:3], v[132:133] op_sel_hi:[1,0]
	v_cvt_pk_bf16_f32 v136, v4, v5
	v_cvt_pk_bf16_f32 v137, v6, v7
	v_cvt_pk_bf16_f32 v138, v0, v1
	v_cvt_pk_bf16_f32 v139, v2, v3
	global_store_dwordx4 v[134:135], v[136:139], off offset:256
	s_mov_b64 s[6:7], 0
.LBB0_500:
	s_andn2_b64 vcc, exec, s[6:7]
	s_cbranch_vccnz .LBB0_502
	s_ashr_i32 s6, s21, 4
	v_lshl_add_u32 v157, s19, 8, v188
	s_and_b32 s6, s6, 0xfffffe00
	v_or_b32_e32 v130, s6, v157
	v_ashrrev_i32_e32 v131, 31, v130
	v_and_b32_e32 v134, 0x1fcf, v156
	v_lshlrev_b64 v[132:133], 14, v[130:131]
	v_lshl_add_u64 v[132:133], s[10:11], 0, v[132:133]
	v_lshlrev_b32_e32 v176, 1, v134
	v_lshl_add_u64 v[132:133], v[132:133], 0, v[176:177]
	s_waitcnt lgkmcnt(0)
	v_mbcnt_lo_u32_b32 v157, -1, 0
	v_mbcnt_hi_u32_b32 v157, -1, v157
	s_mov_b32 s6, 0xcccccccc
	s_mov_b32 s7, 0xcccccccc
	v_and_b32_e32 v159, 3, v157
	v_and_b32_e32 v170, 1, v157
	v_mul_u32_u24_e32 v159, 0x3ffe, v159
	v_mov_b32_e32 v171, 0x5040100
	v_mov_b32_e32 v172, 0x3020706
	v_cmp_eq_u32_e32 vcc, 1, v170
	s_nop 1
	v_cndmask_b32_e32 v171, v171, v172, vcc
	v_add_co_u32_e32 v132, vcc, v132, v159
	s_nop 1
	v_addc_co_u32_e32 v133, vcc, 0, v133, vcc
	v_add_co_u32_e32 v134, vcc, 0x40000, v132
	s_nop 1
	v_addc_co_u32_e32 v135, vcc, 0, v133, vcc
	v_add_co_u32_e32 v136, vcc, 0x200000, v132
	s_nop 1
	v_addc_co_u32_e32 v137, vcc, 0, v133, vcc
	v_add_co_u32_e32 v138, vcc, 0x240000, v132
	s_nop 1
	v_addc_co_u32_e32 v139, vcc, 0, v133, vcc
	v_pk_mul_f32 v[140:141], v[124:125], v[168:169] op_sel_hi:[1,0]
	v_pk_mul_f32 v[142:143], v[126:127], v[168:169] op_sel_hi:[1,0]
	v_pk_mul_f32 v[200:201], v[120:121], v[168:169] op_sel_hi:[1,0]
	v_pk_mul_f32 v[202:203], v[122:123], v[168:169] op_sel_hi:[1,0]
	v_cvt_pk_bf16_f32 v190, v140, v141
	v_cvt_pk_bf16_f32 v191, v142, v143
	v_cvt_pk_bf16_f32 v204, v200, v201
	v_cvt_pk_bf16_f32 v205, v202, v203
	v_mov_b32_dpp v192, v190 quad_perm:[1,0,3,2] row_mask:0xf bank_mask:0xf
	v_mov_b32_dpp v193, v191 quad_perm:[1,0,3,2] row_mask:0xf bank_mask:0xf
	v_mov_b32_dpp v206, v204 quad_perm:[1,0,3,2] row_mask:0xf bank_mask:0xf
	v_mov_b32_dpp v207, v205 quad_perm:[1,0,3,2] row_mask:0xf bank_mask:0xf
	v_perm_b32 v194, v192, v190, v171
	v_perm_b32 v195, v193, v191, v171
	v_perm_b32 v130, v206, v204, v171
	v_perm_b32 v131, v207, v205, v171
	v_mov_b32_dpp v196, v194 quad_perm:[2,3,0,1] row_mask:0xf bank_mask:0xf
	v_mov_b32_dpp v197, v195 quad_perm:[2,3,0,1] row_mask:0xf bank_mask:0xf
	v_mov_b32_dpp v172, v130 quad_perm:[2,3,0,1] row_mask:0xf bank_mask:0xf
	v_mov_b32_dpp v173, v131 quad_perm:[2,3,0,1] row_mask:0xf bank_mask:0xf
	v_cndmask_b32_e64 v198, v194, v197, s[6:7]
	v_cndmask_b32_e64 v199, v196, v195, s[6:7]
	v_cndmask_b32_e64 v200, v130, v173, s[6:7]
	v_cndmask_b32_e64 v201, v172, v131, s[6:7]
	global_store_dwordx2 v[132:133], v[198:199], off
	global_store_dwordx2 v[134:135], v[200:201], off
	v_pk_mul_f32 v[140:141], v[116:117], v[168:169] op_sel_hi:[1,0]
	v_pk_mul_f32 v[142:143], v[118:119], v[168:169] op_sel_hi:[1,0]
	v_pk_mul_f32 v[200:201], v[112:113], v[168:169] op_sel_hi:[1,0]
	v_pk_mul_f32 v[202:203], v[114:115], v[168:169] op_sel_hi:[1,0]
	v_cvt_pk_bf16_f32 v190, v140, v141
	v_cvt_pk_bf16_f32 v191, v142, v143
	v_cvt_pk_bf16_f32 v204, v200, v201
	v_cvt_pk_bf16_f32 v205, v202, v203
	v_mov_b32_dpp v192, v190 quad_perm:[1,0,3,2] row_mask:0xf bank_mask:0xf
	v_mov_b32_dpp v193, v191 quad_perm:[1,0,3,2] row_mask:0xf bank_mask:0xf
	v_mov_b32_dpp v206, v204 quad_perm:[1,0,3,2] row_mask:0xf bank_mask:0xf
	v_mov_b32_dpp v207, v205 quad_perm:[1,0,3,2] row_mask:0xf bank_mask:0xf
	v_perm_b32 v194, v192, v190, v171
	v_perm_b32 v195, v193, v191, v171
	v_perm_b32 v130, v206, v204, v171
	v_perm_b32 v131, v207, v205, v171
	v_mov_b32_dpp v196, v194 quad_perm:[2,3,0,1] row_mask:0xf bank_mask:0xf
	v_mov_b32_dpp v197, v195 quad_perm:[2,3,0,1] row_mask:0xf bank_mask:0xf
	v_mov_b32_dpp v172, v130 quad_perm:[2,3,0,1] row_mask:0xf bank_mask:0xf
	v_mov_b32_dpp v173, v131 quad_perm:[2,3,0,1] row_mask:0xf bank_mask:0xf
	v_cndmask_b32_e64 v198, v194, v197, s[6:7]
	v_cndmask_b32_e64 v199, v196, v195, s[6:7]
	v_cndmask_b32_e64 v200, v130, v173, s[6:7]
	v_cndmask_b32_e64 v201, v172, v131, s[6:7]
	global_store_dwordx2 v[136:137], v[198:199], off
	global_store_dwordx2 v[138:139], v[200:201], off
	v_pk_mul_f32 v[140:141], v[108:109], v[168:169] op_sel:[0,1]
	v_pk_mul_f32 v[142:143], v[110:111], v[168:169] op_sel:[0,1]
	v_pk_mul_f32 v[200:201], v[104:105], v[168:169] op_sel:[0,1]
	v_pk_mul_f32 v[202:203], v[106:107], v[168:169] op_sel:[0,1]
	v_cvt_pk_bf16_f32 v190, v140, v141
	v_cvt_pk_bf16_f32 v191, v142, v143
	v_cvt_pk_bf16_f32 v204, v200, v201
	v_cvt_pk_bf16_f32 v205, v202, v203
	v_mov_b32_dpp v192, v190 quad_perm:[1,0,3,2] row_mask:0xf bank_mask:0xf
	v_mov_b32_dpp v193, v191 quad_perm:[1,0,3,2] row_mask:0xf bank_mask:0xf
	v_mov_b32_dpp v206, v204 quad_perm:[1,0,3,2] row_mask:0xf bank_mask:0xf
	v_mov_b32_dpp v207, v205 quad_perm:[1,0,3,2] row_mask:0xf bank_mask:0xf
	v_perm_b32 v194, v192, v190, v171
	v_perm_b32 v195, v193, v191, v171
	v_perm_b32 v130, v206, v204, v171
	v_perm_b32 v131, v207, v205, v171
	v_mov_b32_dpp v196, v194 quad_perm:[2,3,0,1] row_mask:0xf bank_mask:0xf
	v_mov_b32_dpp v197, v195 quad_perm:[2,3,0,1] row_mask:0xf bank_mask:0xf
	v_mov_b32_dpp v172, v130 quad_perm:[2,3,0,1] row_mask:0xf bank_mask:0xf
	v_mov_b32_dpp v173, v131 quad_perm:[2,3,0,1] row_mask:0xf bank_mask:0xf
	v_cndmask_b32_e64 v198, v194, v197, s[6:7]
	v_cndmask_b32_e64 v199, v196, v195, s[6:7]
	v_cndmask_b32_e64 v200, v130, v173, s[6:7]
	v_cndmask_b32_e64 v201, v172, v131, s[6:7]
	global_store_dwordx2 v[132:133], v[198:199], off offset:32
	global_store_dwordx2 v[134:135], v[200:201], off offset:32
	v_pk_mul_f32 v[140:141], v[100:101], v[168:169] op_sel:[0,1]
	v_pk_mul_f32 v[142:143], v[102:103], v[168:169] op_sel:[0,1]
	v_pk_mul_f32 v[200:201], v[96:97], v[168:169] op_sel:[0,1]
	v_pk_mul_f32 v[202:203], v[98:99], v[168:169] op_sel:[0,1]
	v_cvt_pk_bf16_f32 v190, v140, v141
	v_cvt_pk_bf16_f32 v191, v142, v143
	v_cvt_pk_bf16_f32 v204, v200, v201
	v_cvt_pk_bf16_f32 v205, v202, v203
	v_mov_b32_dpp v192, v190 quad_perm:[1,0,3,2] row_mask:0xf bank_mask:0xf
	v_mov_b32_dpp v193, v191 quad_perm:[1,0,3,2] row_mask:0xf bank_mask:0xf
	v_mov_b32_dpp v206, v204 quad_perm:[1,0,3,2] row_mask:0xf bank_mask:0xf
	v_mov_b32_dpp v207, v205 quad_perm:[1,0,3,2] row_mask:0xf bank_mask:0xf
	v_perm_b32 v194, v192, v190, v171
	v_perm_b32 v195, v193, v191, v171
	v_perm_b32 v130, v206, v204, v171
	v_perm_b32 v131, v207, v205, v171
	v_mov_b32_dpp v196, v194 quad_perm:[2,3,0,1] row_mask:0xf bank_mask:0xf
	v_mov_b32_dpp v197, v195 quad_perm:[2,3,0,1] row_mask:0xf bank_mask:0xf
	v_mov_b32_dpp v172, v130 quad_perm:[2,3,0,1] row_mask:0xf bank_mask:0xf
	v_mov_b32_dpp v173, v131 quad_perm:[2,3,0,1] row_mask:0xf bank_mask:0xf
	v_cndmask_b32_e64 v198, v194, v197, s[6:7]
	v_cndmask_b32_e64 v199, v196, v195, s[6:7]
	v_cndmask_b32_e64 v200, v130, v173, s[6:7]
	v_cndmask_b32_e64 v201, v172, v131, s[6:7]
	global_store_dwordx2 v[136:137], v[198:199], off offset:32
	global_store_dwordx2 v[138:139], v[200:201], off offset:32
	v_pk_mul_f32 v[140:141], v[92:93], v[166:167] op_sel_hi:[1,0]
	v_pk_mul_f32 v[142:143], v[94:95], v[166:167] op_sel_hi:[1,0]
	v_pk_mul_f32 v[200:201], v[88:89], v[166:167] op_sel_hi:[1,0]
	v_pk_mul_f32 v[202:203], v[90:91], v[166:167] op_sel_hi:[1,0]
	v_cvt_pk_bf16_f32 v190, v140, v141
	v_cvt_pk_bf16_f32 v191, v142, v143
	v_cvt_pk_bf16_f32 v204, v200, v201
	v_cvt_pk_bf16_f32 v205, v202, v203
	v_mov_b32_dpp v192, v190 quad_perm:[1,0,3,2] row_mask:0xf bank_mask:0xf
	v_mov_b32_dpp v193, v191 quad_perm:[1,0,3,2] row_mask:0xf bank_mask:0xf
	v_mov_b32_dpp v206, v204 quad_perm:[1,0,3,2] row_mask:0xf bank_mask:0xf
	v_mov_b32_dpp v207, v205 quad_perm:[1,0,3,2] row_mask:0xf bank_mask:0xf
	v_perm_b32 v194, v192, v190, v171
	v_perm_b32 v195, v193, v191, v171
	v_perm_b32 v130, v206, v204, v171
	v_perm_b32 v131, v207, v205, v171
	v_mov_b32_dpp v196, v194 quad_perm:[2,3,0,1] row_mask:0xf bank_mask:0xf
	v_mov_b32_dpp v197, v195 quad_perm:[2,3,0,1] row_mask:0xf bank_mask:0xf
	v_mov_b32_dpp v172, v130 quad_perm:[2,3,0,1] row_mask:0xf bank_mask:0xf
	v_mov_b32_dpp v173, v131 quad_perm:[2,3,0,1] row_mask:0xf bank_mask:0xf
	v_cndmask_b32_e64 v198, v194, v197, s[6:7]
	v_cndmask_b32_e64 v199, v196, v195, s[6:7]
	v_cndmask_b32_e64 v200, v130, v173, s[6:7]
	v_cndmask_b32_e64 v201, v172, v131, s[6:7]
	global_store_dwordx2 v[132:133], v[198:199], off offset:64
	global_store_dwordx2 v[134:135], v[200:201], off offset:64
	v_pk_mul_f32 v[140:141], v[84:85], v[166:167] op_sel_hi:[1,0]
	v_pk_mul_f32 v[142:143], v[86:87], v[166:167] op_sel_hi:[1,0]
	v_pk_mul_f32 v[200:201], v[80:81], v[166:167] op_sel_hi:[1,0]
	v_pk_mul_f32 v[202:203], v[82:83], v[166:167] op_sel_hi:[1,0]
	v_cvt_pk_bf16_f32 v190, v140, v141
	v_cvt_pk_bf16_f32 v191, v142, v143
	v_cvt_pk_bf16_f32 v204, v200, v201
	v_cvt_pk_bf16_f32 v205, v202, v203
	v_mov_b32_dpp v192, v190 quad_perm:[1,0,3,2] row_mask:0xf bank_mask:0xf
	v_mov_b32_dpp v193, v191 quad_perm:[1,0,3,2] row_mask:0xf bank_mask:0xf
	v_mov_b32_dpp v206, v204 quad_perm:[1,0,3,2] row_mask:0xf bank_mask:0xf
	v_mov_b32_dpp v207, v205 quad_perm:[1,0,3,2] row_mask:0xf bank_mask:0xf
	v_perm_b32 v194, v192, v190, v171
	v_perm_b32 v195, v193, v191, v171
	v_perm_b32 v130, v206, v204, v171
	v_perm_b32 v131, v207, v205, v171
	v_mov_b32_dpp v196, v194 quad_perm:[2,3,0,1] row_mask:0xf bank_mask:0xf
	v_mov_b32_dpp v197, v195 quad_perm:[2,3,0,1] row_mask:0xf bank_mask:0xf
	v_mov_b32_dpp v172, v130 quad_perm:[2,3,0,1] row_mask:0xf bank_mask:0xf
	v_mov_b32_dpp v173, v131 quad_perm:[2,3,0,1] row_mask:0xf bank_mask:0xf
	v_cndmask_b32_e64 v198, v194, v197, s[6:7]
	v_cndmask_b32_e64 v199, v196, v195, s[6:7]
	v_cndmask_b32_e64 v200, v130, v173, s[6:7]
	v_cndmask_b32_e64 v201, v172, v131, s[6:7]
	global_store_dwordx2 v[136:137], v[198:199], off offset:64
	global_store_dwordx2 v[138:139], v[200:201], off offset:64
	v_pk_mul_f32 v[140:141], v[76:77], v[166:167] op_sel:[0,1]
	v_pk_mul_f32 v[142:143], v[78:79], v[166:167] op_sel:[0,1]
	v_pk_mul_f32 v[200:201], v[72:73], v[166:167] op_sel:[0,1]
	v_pk_mul_f32 v[202:203], v[74:75], v[166:167] op_sel:[0,1]
	v_cvt_pk_bf16_f32 v190, v140, v141
	v_cvt_pk_bf16_f32 v191, v142, v143
	v_cvt_pk_bf16_f32 v204, v200, v201
	v_cvt_pk_bf16_f32 v205, v202, v203
	v_mov_b32_dpp v192, v190 quad_perm:[1,0,3,2] row_mask:0xf bank_mask:0xf
	v_mov_b32_dpp v193, v191 quad_perm:[1,0,3,2] row_mask:0xf bank_mask:0xf
	v_mov_b32_dpp v206, v204 quad_perm:[1,0,3,2] row_mask:0xf bank_mask:0xf
	v_mov_b32_dpp v207, v205 quad_perm:[1,0,3,2] row_mask:0xf bank_mask:0xf
	v_perm_b32 v194, v192, v190, v171
	v_perm_b32 v195, v193, v191, v171
	v_perm_b32 v130, v206, v204, v171
	v_perm_b32 v131, v207, v205, v171
	v_mov_b32_dpp v196, v194 quad_perm:[2,3,0,1] row_mask:0xf bank_mask:0xf
	v_mov_b32_dpp v197, v195 quad_perm:[2,3,0,1] row_mask:0xf bank_mask:0xf
	v_mov_b32_dpp v172, v130 quad_perm:[2,3,0,1] row_mask:0xf bank_mask:0xf
	v_mov_b32_dpp v173, v131 quad_perm:[2,3,0,1] row_mask:0xf bank_mask:0xf
	v_cndmask_b32_e64 v198, v194, v197, s[6:7]
	v_cndmask_b32_e64 v199, v196, v195, s[6:7]
	v_cndmask_b32_e64 v200, v130, v173, s[6:7]
	v_cndmask_b32_e64 v201, v172, v131, s[6:7]
	global_store_dwordx2 v[132:133], v[198:199], off offset:96
	global_store_dwordx2 v[134:135], v[200:201], off offset:96
	v_pk_mul_f32 v[140:141], v[68:69], v[166:167] op_sel:[0,1]
	v_pk_mul_f32 v[142:143], v[70:71], v[166:167] op_sel:[0,1]
	v_pk_mul_f32 v[200:201], v[64:65], v[166:167] op_sel:[0,1]
	v_pk_mul_f32 v[202:203], v[66:67], v[166:167] op_sel:[0,1]
	v_cvt_pk_bf16_f32 v190, v140, v141
	v_cvt_pk_bf16_f32 v191, v142, v143
	v_cvt_pk_bf16_f32 v204, v200, v201
	v_cvt_pk_bf16_f32 v205, v202, v203
	v_mov_b32_dpp v192, v190 quad_perm:[1,0,3,2] row_mask:0xf bank_mask:0xf
	v_mov_b32_dpp v193, v191 quad_perm:[1,0,3,2] row_mask:0xf bank_mask:0xf
	v_mov_b32_dpp v206, v204 quad_perm:[1,0,3,2] row_mask:0xf bank_mask:0xf
	v_mov_b32_dpp v207, v205 quad_perm:[1,0,3,2] row_mask:0xf bank_mask:0xf
	v_perm_b32 v194, v192, v190, v171
	v_perm_b32 v195, v193, v191, v171
	v_perm_b32 v130, v206, v204, v171
	v_perm_b32 v131, v207, v205, v171
	v_mov_b32_dpp v196, v194 quad_perm:[2,3,0,1] row_mask:0xf bank_mask:0xf
	v_mov_b32_dpp v197, v195 quad_perm:[2,3,0,1] row_mask:0xf bank_mask:0xf
	v_mov_b32_dpp v172, v130 quad_perm:[2,3,0,1] row_mask:0xf bank_mask:0xf
	v_mov_b32_dpp v173, v131 quad_perm:[2,3,0,1] row_mask:0xf bank_mask:0xf
	v_cndmask_b32_e64 v198, v194, v197, s[6:7]
	v_cndmask_b32_e64 v199, v196, v195, s[6:7]
	v_cndmask_b32_e64 v200, v130, v173, s[6:7]
	v_cndmask_b32_e64 v201, v172, v131, s[6:7]
	global_store_dwordx2 v[136:137], v[198:199], off offset:96
	global_store_dwordx2 v[138:139], v[200:201], off offset:96
	v_pk_mul_f32 v[140:141], v[60:61], v[162:163] op_sel_hi:[1,0]
	v_pk_mul_f32 v[142:143], v[62:63], v[162:163] op_sel_hi:[1,0]
	v_pk_mul_f32 v[200:201], v[56:57], v[162:163] op_sel_hi:[1,0]
	v_pk_mul_f32 v[202:203], v[58:59], v[162:163] op_sel_hi:[1,0]
	v_cvt_pk_bf16_f32 v190, v140, v141
	v_cvt_pk_bf16_f32 v191, v142, v143
	v_cvt_pk_bf16_f32 v204, v200, v201
	v_cvt_pk_bf16_f32 v205, v202, v203
	v_mov_b32_dpp v192, v190 quad_perm:[1,0,3,2] row_mask:0xf bank_mask:0xf
	v_mov_b32_dpp v193, v191 quad_perm:[1,0,3,2] row_mask:0xf bank_mask:0xf
	v_mov_b32_dpp v206, v204 quad_perm:[1,0,3,2] row_mask:0xf bank_mask:0xf
	v_mov_b32_dpp v207, v205 quad_perm:[1,0,3,2] row_mask:0xf bank_mask:0xf
	v_perm_b32 v194, v192, v190, v171
	v_perm_b32 v195, v193, v191, v171
	v_perm_b32 v130, v206, v204, v171
	v_perm_b32 v131, v207, v205, v171
	v_mov_b32_dpp v196, v194 quad_perm:[2,3,0,1] row_mask:0xf bank_mask:0xf
	v_mov_b32_dpp v197, v195 quad_perm:[2,3,0,1] row_mask:0xf bank_mask:0xf
	v_mov_b32_dpp v172, v130 quad_perm:[2,3,0,1] row_mask:0xf bank_mask:0xf
	v_mov_b32_dpp v173, v131 quad_perm:[2,3,0,1] row_mask:0xf bank_mask:0xf
	v_cndmask_b32_e64 v198, v194, v197, s[6:7]
	v_cndmask_b32_e64 v199, v196, v195, s[6:7]
	v_cndmask_b32_e64 v200, v130, v173, s[6:7]
	v_cndmask_b32_e64 v201, v172, v131, s[6:7]
	global_store_dwordx2 v[132:133], v[198:199], off offset:256
	global_store_dwordx2 v[134:135], v[200:201], off offset:256
	v_pk_mul_f32 v[140:141], v[52:53], v[162:163] op_sel_hi:[1,0]
	v_pk_mul_f32 v[142:143], v[54:55], v[162:163] op_sel_hi:[1,0]
	v_pk_mul_f32 v[200:201], v[48:49], v[162:163] op_sel_hi:[1,0]
	v_pk_mul_f32 v[202:203], v[50:51], v[162:163] op_sel_hi:[1,0]
	v_cvt_pk_bf16_f32 v190, v140, v141
	v_cvt_pk_bf16_f32 v191, v142, v143
	v_cvt_pk_bf16_f32 v204, v200, v201
	v_cvt_pk_bf16_f32 v205, v202, v203
	v_mov_b32_dpp v192, v190 quad_perm:[1,0,3,2] row_mask:0xf bank_mask:0xf
	v_mov_b32_dpp v193, v191 quad_perm:[1,0,3,2] row_mask:0xf bank_mask:0xf
	v_mov_b32_dpp v206, v204 quad_perm:[1,0,3,2] row_mask:0xf bank_mask:0xf
	v_mov_b32_dpp v207, v205 quad_perm:[1,0,3,2] row_mask:0xf bank_mask:0xf
	v_perm_b32 v194, v192, v190, v171
	v_perm_b32 v195, v193, v191, v171
	v_perm_b32 v130, v206, v204, v171
	v_perm_b32 v131, v207, v205, v171
	v_mov_b32_dpp v196, v194 quad_perm:[2,3,0,1] row_mask:0xf bank_mask:0xf
	v_mov_b32_dpp v197, v195 quad_perm:[2,3,0,1] row_mask:0xf bank_mask:0xf
	v_mov_b32_dpp v172, v130 quad_perm:[2,3,0,1] row_mask:0xf bank_mask:0xf
	v_mov_b32_dpp v173, v131 quad_perm:[2,3,0,1] row_mask:0xf bank_mask:0xf
	v_cndmask_b32_e64 v198, v194, v197, s[6:7]
	v_cndmask_b32_e64 v199, v196, v195, s[6:7]
	v_cndmask_b32_e64 v200, v130, v173, s[6:7]
	v_cndmask_b32_e64 v201, v172, v131, s[6:7]
	global_store_dwordx2 v[136:137], v[198:199], off offset:256
	global_store_dwordx2 v[138:139], v[200:201], off offset:256
	v_pk_mul_f32 v[140:141], v[44:45], v[162:163] op_sel:[0,1]
	v_pk_mul_f32 v[142:143], v[46:47], v[162:163] op_sel:[0,1]
	v_pk_mul_f32 v[200:201], v[40:41], v[162:163] op_sel:[0,1]
	v_pk_mul_f32 v[202:203], v[42:43], v[162:163] op_sel:[0,1]
	v_cvt_pk_bf16_f32 v190, v140, v141
	v_cvt_pk_bf16_f32 v191, v142, v143
	v_cvt_pk_bf16_f32 v204, v200, v201
	v_cvt_pk_bf16_f32 v205, v202, v203
	v_mov_b32_dpp v192, v190 quad_perm:[1,0,3,2] row_mask:0xf bank_mask:0xf
	v_mov_b32_dpp v193, v191 quad_perm:[1,0,3,2] row_mask:0xf bank_mask:0xf
	v_mov_b32_dpp v206, v204 quad_perm:[1,0,3,2] row_mask:0xf bank_mask:0xf
	v_mov_b32_dpp v207, v205 quad_perm:[1,0,3,2] row_mask:0xf bank_mask:0xf
	v_perm_b32 v194, v192, v190, v171
	v_perm_b32 v195, v193, v191, v171
	v_perm_b32 v130, v206, v204, v171
	v_perm_b32 v131, v207, v205, v171
	v_mov_b32_dpp v196, v194 quad_perm:[2,3,0,1] row_mask:0xf bank_mask:0xf
	v_mov_b32_dpp v197, v195 quad_perm:[2,3,0,1] row_mask:0xf bank_mask:0xf
	v_mov_b32_dpp v172, v130 quad_perm:[2,3,0,1] row_mask:0xf bank_mask:0xf
	v_mov_b32_dpp v173, v131 quad_perm:[2,3,0,1] row_mask:0xf bank_mask:0xf
	v_cndmask_b32_e64 v198, v194, v197, s[6:7]
	v_cndmask_b32_e64 v199, v196, v195, s[6:7]
	v_cndmask_b32_e64 v200, v130, v173, s[6:7]
	v_cndmask_b32_e64 v201, v172, v131, s[6:7]
	global_store_dwordx2 v[132:133], v[198:199], off offset:288
	global_store_dwordx2 v[134:135], v[200:201], off offset:288
	v_pk_mul_f32 v[140:141], v[36:37], v[162:163] op_sel:[0,1]
	v_pk_mul_f32 v[142:143], v[38:39], v[162:163] op_sel:[0,1]
	v_pk_mul_f32 v[200:201], v[32:33], v[162:163] op_sel:[0,1]
	v_pk_mul_f32 v[202:203], v[34:35], v[162:163] op_sel:[0,1]
	v_cvt_pk_bf16_f32 v190, v140, v141
	v_cvt_pk_bf16_f32 v191, v142, v143
	v_cvt_pk_bf16_f32 v204, v200, v201
	v_cvt_pk_bf16_f32 v205, v202, v203
	v_mov_b32_dpp v192, v190 quad_perm:[1,0,3,2] row_mask:0xf bank_mask:0xf
	v_mov_b32_dpp v193, v191 quad_perm:[1,0,3,2] row_mask:0xf bank_mask:0xf
	v_mov_b32_dpp v206, v204 quad_perm:[1,0,3,2] row_mask:0xf bank_mask:0xf
	v_mov_b32_dpp v207, v205 quad_perm:[1,0,3,2] row_mask:0xf bank_mask:0xf
	v_perm_b32 v194, v192, v190, v171
	v_perm_b32 v195, v193, v191, v171
	v_perm_b32 v130, v206, v204, v171
	v_perm_b32 v131, v207, v205, v171
	v_mov_b32_dpp v196, v194 quad_perm:[2,3,0,1] row_mask:0xf bank_mask:0xf
	v_mov_b32_dpp v197, v195 quad_perm:[2,3,0,1] row_mask:0xf bank_mask:0xf
	v_mov_b32_dpp v172, v130 quad_perm:[2,3,0,1] row_mask:0xf bank_mask:0xf
	v_mov_b32_dpp v173, v131 quad_perm:[2,3,0,1] row_mask:0xf bank_mask:0xf
	v_cndmask_b32_e64 v198, v194, v197, s[6:7]
	v_cndmask_b32_e64 v199, v196, v195, s[6:7]
	v_cndmask_b32_e64 v200, v130, v173, s[6:7]
	v_cndmask_b32_e64 v201, v172, v131, s[6:7]
	global_store_dwordx2 v[136:137], v[198:199], off offset:288
	global_store_dwordx2 v[138:139], v[200:201], off offset:288
	v_pk_mul_f32 v[140:141], v[28:29], v[128:129] op_sel_hi:[1,0]
	v_pk_mul_f32 v[142:143], v[30:31], v[128:129] op_sel_hi:[1,0]
	v_pk_mul_f32 v[200:201], v[24:25], v[128:129] op_sel_hi:[1,0]
	v_pk_mul_f32 v[202:203], v[26:27], v[128:129] op_sel_hi:[1,0]
	v_cvt_pk_bf16_f32 v190, v140, v141
	v_cvt_pk_bf16_f32 v191, v142, v143
	v_cvt_pk_bf16_f32 v204, v200, v201
	v_cvt_pk_bf16_f32 v205, v202, v203
	v_mov_b32_dpp v192, v190 quad_perm:[1,0,3,2] row_mask:0xf bank_mask:0xf
	v_mov_b32_dpp v193, v191 quad_perm:[1,0,3,2] row_mask:0xf bank_mask:0xf
	v_mov_b32_dpp v206, v204 quad_perm:[1,0,3,2] row_mask:0xf bank_mask:0xf
	v_mov_b32_dpp v207, v205 quad_perm:[1,0,3,2] row_mask:0xf bank_mask:0xf
	v_perm_b32 v194, v192, v190, v171
	v_perm_b32 v195, v193, v191, v171
	v_perm_b32 v130, v206, v204, v171
	v_perm_b32 v131, v207, v205, v171
	v_mov_b32_dpp v196, v194 quad_perm:[2,3,0,1] row_mask:0xf bank_mask:0xf
	v_mov_b32_dpp v197, v195 quad_perm:[2,3,0,1] row_mask:0xf bank_mask:0xf
	v_mov_b32_dpp v172, v130 quad_perm:[2,3,0,1] row_mask:0xf bank_mask:0xf
	v_mov_b32_dpp v173, v131 quad_perm:[2,3,0,1] row_mask:0xf bank_mask:0xf
	v_cndmask_b32_e64 v198, v194, v197, s[6:7]
	v_cndmask_b32_e64 v199, v196, v195, s[6:7]
	v_cndmask_b32_e64 v200, v130, v173, s[6:7]
	v_cndmask_b32_e64 v201, v172, v131, s[6:7]
	global_store_dwordx2 v[132:133], v[198:199], off offset:320
	global_store_dwordx2 v[134:135], v[200:201], off offset:320
	v_pk_mul_f32 v[140:141], v[20:21], v[128:129] op_sel_hi:[1,0]
	v_pk_mul_f32 v[142:143], v[22:23], v[128:129] op_sel_hi:[1,0]
	v_pk_mul_f32 v[200:201], v[16:17], v[128:129] op_sel_hi:[1,0]
	v_pk_mul_f32 v[202:203], v[18:19], v[128:129] op_sel_hi:[1,0]
	v_cvt_pk_bf16_f32 v190, v140, v141
	v_cvt_pk_bf16_f32 v191, v142, v143
	v_cvt_pk_bf16_f32 v204, v200, v201
	v_cvt_pk_bf16_f32 v205, v202, v203
	v_mov_b32_dpp v192, v190 quad_perm:[1,0,3,2] row_mask:0xf bank_mask:0xf
	v_mov_b32_dpp v193, v191 quad_perm:[1,0,3,2] row_mask:0xf bank_mask:0xf
	v_mov_b32_dpp v206, v204 quad_perm:[1,0,3,2] row_mask:0xf bank_mask:0xf
	v_mov_b32_dpp v207, v205 quad_perm:[1,0,3,2] row_mask:0xf bank_mask:0xf
	v_perm_b32 v194, v192, v190, v171
	v_perm_b32 v195, v193, v191, v171
	v_perm_b32 v130, v206, v204, v171
	v_perm_b32 v131, v207, v205, v171
	v_mov_b32_dpp v196, v194 quad_perm:[2,3,0,1] row_mask:0xf bank_mask:0xf
	v_mov_b32_dpp v197, v195 quad_perm:[2,3,0,1] row_mask:0xf bank_mask:0xf
	v_mov_b32_dpp v172, v130 quad_perm:[2,3,0,1] row_mask:0xf bank_mask:0xf
	v_mov_b32_dpp v173, v131 quad_perm:[2,3,0,1] row_mask:0xf bank_mask:0xf
	v_cndmask_b32_e64 v198, v194, v197, s[6:7]
	v_cndmask_b32_e64 v199, v196, v195, s[6:7]
	v_cndmask_b32_e64 v200, v130, v173, s[6:7]
	v_cndmask_b32_e64 v201, v172, v131, s[6:7]
	global_store_dwordx2 v[136:137], v[198:199], off offset:320
	global_store_dwordx2 v[138:139], v[200:201], off offset:320
	v_pk_mul_f32 v[140:141], v[12:13], v[128:129] op_sel:[0,1]
	v_pk_mul_f32 v[142:143], v[14:15], v[128:129] op_sel:[0,1]
	v_pk_mul_f32 v[200:201], v[8:9], v[128:129] op_sel:[0,1]
	v_pk_mul_f32 v[202:203], v[10:11], v[128:129] op_sel:[0,1]
	v_cvt_pk_bf16_f32 v190, v140, v141
	v_cvt_pk_bf16_f32 v191, v142, v143
	v_cvt_pk_bf16_f32 v204, v200, v201
	v_cvt_pk_bf16_f32 v205, v202, v203
	v_mov_b32_dpp v192, v190 quad_perm:[1,0,3,2] row_mask:0xf bank_mask:0xf
	v_mov_b32_dpp v193, v191 quad_perm:[1,0,3,2] row_mask:0xf bank_mask:0xf
	v_mov_b32_dpp v206, v204 quad_perm:[1,0,3,2] row_mask:0xf bank_mask:0xf
	v_mov_b32_dpp v207, v205 quad_perm:[1,0,3,2] row_mask:0xf bank_mask:0xf
	v_perm_b32 v194, v192, v190, v171
	v_perm_b32 v195, v193, v191, v171
	v_perm_b32 v130, v206, v204, v171
	v_perm_b32 v131, v207, v205, v171
	v_mov_b32_dpp v196, v194 quad_perm:[2,3,0,1] row_mask:0xf bank_mask:0xf
	v_mov_b32_dpp v197, v195 quad_perm:[2,3,0,1] row_mask:0xf bank_mask:0xf
	v_mov_b32_dpp v172, v130 quad_perm:[2,3,0,1] row_mask:0xf bank_mask:0xf
	v_mov_b32_dpp v173, v131 quad_perm:[2,3,0,1] row_mask:0xf bank_mask:0xf
	v_cndmask_b32_e64 v198, v194, v197, s[6:7]
	v_cndmask_b32_e64 v199, v196, v195, s[6:7]
	v_cndmask_b32_e64 v200, v130, v173, s[6:7]
	v_cndmask_b32_e64 v201, v172, v131, s[6:7]
	global_store_dwordx2 v[132:133], v[198:199], off offset:352
	global_store_dwordx2 v[134:135], v[200:201], off offset:352
	v_pk_mul_f32 v[140:141], v[4:5], v[128:129] op_sel:[0,1]
	v_pk_mul_f32 v[142:143], v[6:7], v[128:129] op_sel:[0,1]
	v_pk_mul_f32 v[200:201], v[0:1], v[128:129] op_sel:[0,1]
	v_pk_mul_f32 v[202:203], v[2:3], v[128:129] op_sel:[0,1]
	v_cvt_pk_bf16_f32 v190, v140, v141
	v_cvt_pk_bf16_f32 v191, v142, v143
	v_cvt_pk_bf16_f32 v204, v200, v201
	v_cvt_pk_bf16_f32 v205, v202, v203
	v_mov_b32_dpp v192, v190 quad_perm:[1,0,3,2] row_mask:0xf bank_mask:0xf
	v_mov_b32_dpp v193, v191 quad_perm:[1,0,3,2] row_mask:0xf bank_mask:0xf
	v_mov_b32_dpp v206, v204 quad_perm:[1,0,3,2] row_mask:0xf bank_mask:0xf
	v_mov_b32_dpp v207, v205 quad_perm:[1,0,3,2] row_mask:0xf bank_mask:0xf
	v_perm_b32 v194, v192, v190, v171
	v_perm_b32 v195, v193, v191, v171
	v_perm_b32 v130, v206, v204, v171
	v_perm_b32 v131, v207, v205, v171
	v_mov_b32_dpp v196, v194 quad_perm:[2,3,0,1] row_mask:0xf bank_mask:0xf
	v_mov_b32_dpp v197, v195 quad_perm:[2,3,0,1] row_mask:0xf bank_mask:0xf
	v_mov_b32_dpp v172, v130 quad_perm:[2,3,0,1] row_mask:0xf bank_mask:0xf
	v_mov_b32_dpp v173, v131 quad_perm:[2,3,0,1] row_mask:0xf bank_mask:0xf
	v_cndmask_b32_e64 v198, v194, v197, s[6:7]
	v_cndmask_b32_e64 v199, v196, v195, s[6:7]
	v_cndmask_b32_e64 v200, v130, v173, s[6:7]
	v_cndmask_b32_e64 v201, v172, v131, s[6:7]
	global_store_dwordx2 v[136:137], v[198:199], off offset:352
	global_store_dwordx2 v[138:139], v[200:201], off offset:352
	s_movk_i32 s69, 0x4000
